# K-loops: s_setprio 1 raised before the pre-MMA barrier, redundant lgkmcnt wait after it dropped (MMA segment starts with its first MFMA)
# speedup vs baseline: 1.0050x; 1.0050x over previous
.LBB0_161:
	s_add_u32 s86, s69, s6
	s_addc_u32 s87, s70, s7
	s_add_u32 s88, s71, s8
	s_addc_u32 s89, s72, s9
	s_ashr_i32 s23, s22, 31
	s_lshl_b64 s[6:7], s[22:23], 19
	s_add_u32 s24, s34, s6
	s_addc_u32 s25, s35, s7
	s_and_b64 s[8:9], s[0:1], exec
	s_cselect_b32 s23, s25, s43
	s_cselect_b32 s90, s24, s42
	s_ashr_i32 s21, s20, 31
	s_lshl_b64 s[8:9], s[20:21], 19
	s_add_u32 s26, s17, s8
	s_addc_u32 s27, s19, s9
	s_and_b64 s[48:49], s[0:1], exec
	s_cselect_b32 s21, s27, s39
	s_cselect_b32 s91, s26, s38
	s_add_u32 s48, s90, 0x80
	s_addc_u32 s49, s23, 0
	s_add_u32 s54, s91, 0x80
	s_addc_u32 s55, s21, 0
	v_lshl_add_u64 v[128:129], s[42:43], 0, v[150:151]
	v_lshl_add_u64 v[130:131], s[42:43], 0, v[152:153]
	s_mov_b32 s92, 0
	s_mov_b64 s[56:57], 0
	s_cmpk_eq_i32 s56, 0x700
	s_cselect_b64 s[62:63], -1, 0
	s_add_u32 s64, s42, s56
	s_addc_u32 s65, s43, s57
	s_add_u32 s94, s38, s56
	s_addc_u32 s93, s39, s57
	s_add_u32 s58, s64, 0x180
	s_addc_u32 s59, s65, 0
	s_add_u32 s60, s94, 0x180
	s_addc_u32 s61, s93, 0
	s_cmpk_eq_i32 s56, 0x700
	s_cselect_b32 s58, s48, s58
	s_cselect_b32 s59, s49, s59
	s_cselect_b32 s60, s54, s60
	s_cselect_b32 s61, s55, s61
	v_add_u32_e32 v144, s82, v171
	ds_read_b128 v[132:135], v144
	ds_read_b128 v[158:161], v144 offset:1024
	ds_read_b128 v[162:165], v144 offset:2048
	ds_read_b128 v[166:169], v144 offset:3072
	v_add_u32_e32 v144, s83, v171
	ds_read_b128 v[184:187], v144
	ds_read_b128 v[188:191], v144 offset:1024
	ds_read_b128 v[192:195], v144 offset:2048
	ds_read_b128 v[196:199], v144 offset:3072
	s_add_u32 s10, s64, 0x100
	s_addc_u32 s95, s65, 0
	s_and_b64 s[64:65], exec, s[62:63]
	s_cselect_b32 s65, s23, s95
	s_cselect_b32 s64, s90, s10
	s_add_u32 s10, s94, 0x100
	s_addc_u32 s93, s93, 0
	s_and_b64 s[62:63], exec, s[62:63]
	s_cselect_b32 s63, s21, s93
	s_cselect_b32 s62, s91, s10
	v_lshl_add_u64 v[232:233], v[128:129], 0, s[56:57]
	s_add_i32 m0, s29, 0xc000
	ds_read_b128 v[200:203], v181
	ds_read_b128 v[204:207], v181 offset:1024
	ds_read_b128 v[208:211], v181 offset:2048
	ds_read_b128 v[212:215], v181 offset:3072
	ds_read_b128 v[216:219], v181 offset:4096
	ds_read_b128 v[220:223], v181 offset:5120
	ds_read_b128 v[224:227], v181 offset:6144
	global_load_lds_dwordx4 v[232:233], off
	v_lshl_add_u64 v[232:233], v[130:131], 0, s[56:57]
	s_add_i32 m0, s29, 0xe000
	ds_read_b128 v[228:231], v181 offset:7168
	global_load_lds_dwordx4 v[232:233], off
	s_waitcnt vmcnt(8)
	s_waitcnt lgkmcnt(0)
	s_setprio 1
	s_barrier
	v_mfma_f32_16x16x32_bf16 v[124:127], v[132:135], v[200:203], 0
	v_mfma_f32_16x16x32_bf16 v[120:123], v[162:165], v[200:203], 0
	v_mfma_f32_16x16x32_bf16 v[108:111], v[132:135], v[208:211], 0
	v_mfma_f32_16x16x32_bf16 v[104:107], v[162:165], v[208:211], 0
	v_mfma_f32_16x16x32_bf16 v[92:95], v[132:135], v[216:219], 0
	v_mfma_f32_16x16x32_bf16 v[88:91], v[162:165], v[216:219], 0
	v_mfma_f32_16x16x32_bf16 v[76:79], v[132:135], v[224:227], 0
	v_mfma_f32_16x16x32_bf16 v[72:75], v[162:165], v[224:227], 0
	v_mfma_f32_16x16x32_bf16 v[124:127], v[158:161], v[204:207], v[124:127]
	v_mfma_f32_16x16x32_bf16 v[120:123], v[166:169], v[204:207], v[120:123]
	v_mfma_f32_16x16x32_bf16 v[108:111], v[158:161], v[212:215], v[108:111]
	v_mfma_f32_16x16x32_bf16 v[104:107], v[166:169], v[212:215], v[104:107]
	v_mfma_f32_16x16x32_bf16 v[92:95], v[158:161], v[220:223], v[92:95]
	v_mfma_f32_16x16x32_bf16 v[88:91], v[166:169], v[220:223], v[88:91]
	v_mfma_f32_16x16x32_bf16 v[76:79], v[158:161], v[228:231], v[76:79]
	v_mfma_f32_16x16x32_bf16 v[72:75], v[166:169], v[228:231], v[72:75]
	s_setprio 0
	s_setprio 1
	v_mfma_f32_16x16x32_bf16 v[116:119], v[184:187], v[200:203], 0
	v_mfma_f32_16x16x32_bf16 v[112:115], v[192:195], v[200:203], 0
	v_mfma_f32_16x16x32_bf16 v[100:103], v[184:187], v[208:211], 0
	v_mfma_f32_16x16x32_bf16 v[96:99], v[192:195], v[208:211], 0
	v_mfma_f32_16x16x32_bf16 v[84:87], v[184:187], v[216:219], 0
	v_mfma_f32_16x16x32_bf16 v[80:83], v[192:195], v[216:219], 0
	v_mfma_f32_16x16x32_bf16 v[68:71], v[184:187], v[224:227], 0
	v_mfma_f32_16x16x32_bf16 v[64:67], v[192:195], v[224:227], 0
	v_mfma_f32_16x16x32_bf16 v[116:119], v[188:191], v[204:207], v[116:119]
	v_mfma_f32_16x16x32_bf16 v[112:115], v[196:199], v[204:207], v[112:115]
	v_mfma_f32_16x16x32_bf16 v[100:103], v[188:191], v[212:215], v[100:103]
	v_mfma_f32_16x16x32_bf16 v[96:99], v[196:199], v[212:215], v[96:99]
	v_mfma_f32_16x16x32_bf16 v[84:87], v[188:191], v[220:223], v[84:87]
	v_mfma_f32_16x16x32_bf16 v[80:83], v[196:199], v[220:223], v[80:83]
	v_mfma_f32_16x16x32_bf16 v[68:71], v[188:191], v[228:231], v[68:71]
	v_mfma_f32_16x16x32_bf16 v[64:67], v[196:199], v[228:231], v[64:67]
	s_setprio 0
	s_barrier
	s_add_i32 s10, s82, s66
	s_mov_b32 m0, s10
	ds_read_b128 v[200:203], v181 offset:16384
	ds_read_b128 v[204:207], v181 offset:17408
	ds_read_b128 v[208:211], v181 offset:18432
	global_load_lds_dwordx4 v138, s[62:63]
	s_add_i32 m0, s10, 0x2000
	ds_read_b128 v[212:215], v181 offset:19456
	global_load_lds_dwordx4 v142, s[62:63]
	s_add_u32 s62, s62, 0x40000
	s_addc_u32 s63, s63, 0
	s_add_i32 s10, s83, s66
	s_mov_b32 m0, s10
	ds_read_b128 v[216:219], v181 offset:20480
	global_load_lds_dwordx4 v138, s[62:63]
	s_add_i32 m0, s10, 0x2000
	ds_read_b128 v[220:223], v181 offset:21504
	global_load_lds_dwordx4 v142, s[62:63]
	s_mov_b32 m0, s29
	ds_read_b128 v[224:227], v181 offset:22528
	global_load_lds_dwordx4 v136, s[64:65]
	s_mov_b32 m0, s31
	ds_read_b128 v[228:231], v181 offset:23552
	global_load_lds_dwordx4 v140, s[64:65]
	s_waitcnt vmcnt(8)
	s_waitcnt lgkmcnt(0)
	s_setprio 1
	s_barrier
	v_mfma_f32_16x16x32_bf16 v[60:63], v[132:135], v[200:203], 0
	v_mfma_f32_16x16x32_bf16 v[56:59], v[162:165], v[200:203], 0
	v_mfma_f32_16x16x32_bf16 v[44:47], v[132:135], v[208:211], 0
	v_mfma_f32_16x16x32_bf16 v[40:43], v[162:165], v[208:211], 0
	v_mfma_f32_16x16x32_bf16 v[28:31], v[132:135], v[216:219], 0
	v_mfma_f32_16x16x32_bf16 v[24:27], v[162:165], v[216:219], 0
	v_mfma_f32_16x16x32_bf16 v[12:15], v[132:135], v[224:227], 0
	v_mfma_f32_16x16x32_bf16 v[8:11], v[162:165], v[224:227], 0
	v_mfma_f32_16x16x32_bf16 v[60:63], v[158:161], v[204:207], v[60:63]
	v_mfma_f32_16x16x32_bf16 v[56:59], v[166:169], v[204:207], v[56:59]
	v_mfma_f32_16x16x32_bf16 v[44:47], v[158:161], v[212:215], v[44:47]
	v_mfma_f32_16x16x32_bf16 v[40:43], v[166:169], v[212:215], v[40:43]
	v_mfma_f32_16x16x32_bf16 v[28:31], v[158:161], v[220:223], v[28:31]
	v_mfma_f32_16x16x32_bf16 v[24:27], v[166:169], v[220:223], v[24:27]
	v_mfma_f32_16x16x32_bf16 v[12:15], v[158:161], v[228:231], v[12:15]
	v_mfma_f32_16x16x32_bf16 v[8:11], v[166:169], v[228:231], v[8:11]
	s_setprio 0
	s_setprio 1
	v_mfma_f32_16x16x32_bf16 v[52:55], v[184:187], v[200:203], 0
	v_mfma_f32_16x16x32_bf16 v[48:51], v[192:195], v[200:203], 0
	v_mfma_f32_16x16x32_bf16 v[36:39], v[184:187], v[208:211], 0
	v_mfma_f32_16x16x32_bf16 v[32:35], v[192:195], v[208:211], 0
	v_mfma_f32_16x16x32_bf16 v[20:23], v[184:187], v[216:219], 0
	v_mfma_f32_16x16x32_bf16 v[16:19], v[192:195], v[216:219], 0
	v_mfma_f32_16x16x32_bf16 v[4:7], v[184:187], v[224:227], 0
	v_mfma_f32_16x16x32_bf16 v[0:3], v[192:195], v[224:227], 0
	v_mfma_f32_16x16x32_bf16 v[52:55], v[188:191], v[204:207], v[52:55]
	v_mfma_f32_16x16x32_bf16 v[48:51], v[196:199], v[204:207], v[48:51]
	v_mfma_f32_16x16x32_bf16 v[36:39], v[188:191], v[212:215], v[36:39]
	v_mfma_f32_16x16x32_bf16 v[32:35], v[196:199], v[212:215], v[32:35]
	v_mfma_f32_16x16x32_bf16 v[20:23], v[188:191], v[220:223], v[20:23]
	v_mfma_f32_16x16x32_bf16 v[16:19], v[196:199], v[220:223], v[16:19]
	v_mfma_f32_16x16x32_bf16 v[4:7], v[188:191], v[228:231], v[4:7]
	v_mfma_f32_16x16x32_bf16 v[0:3], v[196:199], v[228:231], v[0:3]
	s_setprio 0
	s_barrier
	s_add_i32 s10, 0, 0x18000
	v_add_u32_e32 v144, s10, v171
	s_add_i32 s93, 0, 0x1c000
	ds_read_b128 v[132:135], v144
	ds_read_b128 v[158:161], v144 offset:1024
	ds_read_b128 v[162:165], v144 offset:2048
	ds_read_b128 v[166:169], v144 offset:3072
	v_add_u32_e32 v144, s93, v171
	ds_read_b128 v[184:187], v144
	ds_read_b128 v[188:191], v144 offset:1024
	ds_read_b128 v[192:195], v144 offset:2048
	ds_read_b128 v[196:199], v144 offset:3072
	s_add_u32 s62, s64, 0x40000
	s_addc_u32 s63, s65, 0
	s_mov_b32 m0, s67
	ds_read_b128 v[200:203], v181 offset:32768
	ds_read_b128 v[204:207], v181 offset:33792
	ds_read_b128 v[208:211], v181 offset:34816
	ds_read_b128 v[212:215], v181 offset:35840
	ds_read_b128 v[216:219], v181 offset:36864
	ds_read_b128 v[220:223], v181 offset:37888
	ds_read_b128 v[224:227], v181 offset:38912
	global_load_lds_dwordx4 v136, s[62:63]
	s_mov_b32 m0, s68
	ds_read_b128 v[228:231], v181 offset:39936
	global_load_lds_dwordx4 v140, s[62:63]
	s_waitcnt vmcnt(8)
	s_waitcnt lgkmcnt(0)
	s_setprio 1
	s_barrier
	v_mfma_f32_16x16x32_bf16 v[124:127], v[132:135], v[200:203], v[124:127]
	v_mfma_f32_16x16x32_bf16 v[120:123], v[162:165], v[200:203], v[120:123]
	v_mfma_f32_16x16x32_bf16 v[108:111], v[132:135], v[208:211], v[108:111]
	v_mfma_f32_16x16x32_bf16 v[104:107], v[162:165], v[208:211], v[104:107]
	v_mfma_f32_16x16x32_bf16 v[92:95], v[132:135], v[216:219], v[92:95]
	v_mfma_f32_16x16x32_bf16 v[88:91], v[162:165], v[216:219], v[88:91]
	v_mfma_f32_16x16x32_bf16 v[76:79], v[132:135], v[224:227], v[76:79]
	v_mfma_f32_16x16x32_bf16 v[72:75], v[162:165], v[224:227], v[72:75]
	v_mfma_f32_16x16x32_bf16 v[124:127], v[158:161], v[204:207], v[124:127]
	v_mfma_f32_16x16x32_bf16 v[120:123], v[166:169], v[204:207], v[120:123]
	v_mfma_f32_16x16x32_bf16 v[108:111], v[158:161], v[212:215], v[108:111]
	v_mfma_f32_16x16x32_bf16 v[104:107], v[166:169], v[212:215], v[104:107]
	v_mfma_f32_16x16x32_bf16 v[92:95], v[158:161], v[220:223], v[92:95]
	v_mfma_f32_16x16x32_bf16 v[88:91], v[166:169], v[220:223], v[88:91]
	v_mfma_f32_16x16x32_bf16 v[76:79], v[158:161], v[228:231], v[76:79]
	v_mfma_f32_16x16x32_bf16 v[72:75], v[166:169], v[228:231], v[72:75]
	s_setprio 0
	s_setprio 1
	v_mfma_f32_16x16x32_bf16 v[116:119], v[184:187], v[200:203], v[116:119]
	v_mfma_f32_16x16x32_bf16 v[112:115], v[192:195], v[200:203], v[112:115]
	v_mfma_f32_16x16x32_bf16 v[100:103], v[184:187], v[208:211], v[100:103]
	v_mfma_f32_16x16x32_bf16 v[96:99], v[192:195], v[208:211], v[96:99]
	v_mfma_f32_16x16x32_bf16 v[84:87], v[184:187], v[216:219], v[84:87]
	v_mfma_f32_16x16x32_bf16 v[80:83], v[192:195], v[216:219], v[80:83]
	v_mfma_f32_16x16x32_bf16 v[68:71], v[184:187], v[224:227], v[68:71]
	v_mfma_f32_16x16x32_bf16 v[64:67], v[192:195], v[224:227], v[64:67]
	v_mfma_f32_16x16x32_bf16 v[116:119], v[188:191], v[204:207], v[116:119]
	v_mfma_f32_16x16x32_bf16 v[112:115], v[196:199], v[204:207], v[112:115]
	v_mfma_f32_16x16x32_bf16 v[100:103], v[188:191], v[212:215], v[100:103]
	v_mfma_f32_16x16x32_bf16 v[96:99], v[196:199], v[212:215], v[96:99]
	v_mfma_f32_16x16x32_bf16 v[84:87], v[188:191], v[220:223], v[84:87]
	v_mfma_f32_16x16x32_bf16 v[80:83], v[196:199], v[220:223], v[80:83]
	v_mfma_f32_16x16x32_bf16 v[68:71], v[188:191], v[228:231], v[68:71]
	v_mfma_f32_16x16x32_bf16 v[64:67], v[196:199], v[228:231], v[64:67]
	s_setprio 0
	s_barrier
	s_add_i32 s10, s10, s66
	s_mov_b32 m0, s10
	ds_read_b128 v[200:203], v181 offset:49152
	ds_read_b128 v[204:207], v181 offset:50176
	ds_read_b128 v[208:211], v181 offset:51200
	global_load_lds_dwordx4 v138, s[60:61]
	s_add_i32 m0, s10, 0x2000
	ds_read_b128 v[212:215], v181 offset:52224
	global_load_lds_dwordx4 v142, s[60:61]
	s_add_u32 s60, s60, 0x40000
	s_addc_u32 s61, s61, 0
	s_add_i32 s10, s93, s66
	s_mov_b32 m0, s10
	ds_read_b128 v[216:219], v181 offset:53248
	global_load_lds_dwordx4 v138, s[60:61]
	s_add_i32 m0, s10, 0x2000
	ds_read_b128 v[220:223], v181 offset:54272
	global_load_lds_dwordx4 v142, s[60:61]
	s_mov_b32 m0, s73
	ds_read_b128 v[224:227], v181 offset:55296
	global_load_lds_dwordx4 v136, s[58:59]
	v_lshl_add_u64 v[232:233], s[58:59], 0, v[140:141]
	s_mov_b32 m0, s78
	ds_read_b128 v[228:231], v181 offset:56320
	global_load_lds_dwordx4 v[232:233], off
	s_waitcnt vmcnt(8)
	s_waitcnt lgkmcnt(0)
	s_setprio 1
	s_barrier
	v_mfma_f32_16x16x32_bf16 v[60:63], v[132:135], v[200:203], v[60:63]
	v_mfma_f32_16x16x32_bf16 v[56:59], v[162:165], v[200:203], v[56:59]
	v_mfma_f32_16x16x32_bf16 v[44:47], v[132:135], v[208:211], v[44:47]
	v_mfma_f32_16x16x32_bf16 v[40:43], v[162:165], v[208:211], v[40:43]
	v_mfma_f32_16x16x32_bf16 v[28:31], v[132:135], v[216:219], v[28:31]
	v_mfma_f32_16x16x32_bf16 v[24:27], v[162:165], v[216:219], v[24:27]
	v_mfma_f32_16x16x32_bf16 v[12:15], v[132:135], v[224:227], v[12:15]
	v_mfma_f32_16x16x32_bf16 v[8:11], v[162:165], v[224:227], v[8:11]
	v_mfma_f32_16x16x32_bf16 v[60:63], v[158:161], v[204:207], v[60:63]
	v_mfma_f32_16x16x32_bf16 v[56:59], v[166:169], v[204:207], v[56:59]
	v_mfma_f32_16x16x32_bf16 v[44:47], v[158:161], v[212:215], v[44:47]
	v_mfma_f32_16x16x32_bf16 v[40:43], v[166:169], v[212:215], v[40:43]
	v_mfma_f32_16x16x32_bf16 v[28:31], v[158:161], v[220:223], v[28:31]
	v_mfma_f32_16x16x32_bf16 v[24:27], v[166:169], v[220:223], v[24:27]
	v_mfma_f32_16x16x32_bf16 v[12:15], v[158:161], v[228:231], v[12:15]
	v_mfma_f32_16x16x32_bf16 v[8:11], v[166:169], v[228:231], v[8:11]
	s_setprio 0
	s_setprio 1
	v_mfma_f32_16x16x32_bf16 v[52:55], v[184:187], v[200:203], v[52:55]
	v_mfma_f32_16x16x32_bf16 v[48:51], v[192:195], v[200:203], v[48:51]
	v_mfma_f32_16x16x32_bf16 v[36:39], v[184:187], v[208:211], v[36:39]
	v_mfma_f32_16x16x32_bf16 v[32:35], v[192:195], v[208:211], v[32:35]
	v_mfma_f32_16x16x32_bf16 v[20:23], v[184:187], v[216:219], v[20:23]
	v_mfma_f32_16x16x32_bf16 v[16:19], v[192:195], v[216:219], v[16:19]
	v_mfma_f32_16x16x32_bf16 v[4:7], v[184:187], v[224:227], v[4:7]
	v_mfma_f32_16x16x32_bf16 v[0:3], v[192:195], v[224:227], v[0:3]
	v_mfma_f32_16x16x32_bf16 v[52:55], v[188:191], v[204:207], v[52:55]
	v_mfma_f32_16x16x32_bf16 v[48:51], v[196:199], v[204:207], v[48:51]
	v_mfma_f32_16x16x32_bf16 v[36:39], v[188:191], v[212:215], v[36:39]
	v_mfma_f32_16x16x32_bf16 v[32:35], v[196:199], v[212:215], v[32:35]
	v_mfma_f32_16x16x32_bf16 v[20:23], v[188:191], v[220:223], v[20:23]
	v_mfma_f32_16x16x32_bf16 v[16:19], v[196:199], v[220:223], v[16:19]
	v_mfma_f32_16x16x32_bf16 v[4:7], v[188:191], v[228:231], v[4:7]
	v_mfma_f32_16x16x32_bf16 v[0:3], v[196:199], v[228:231], v[0:3]
	s_setprio 0
	s_barrier
	s_add_i32 s10, s92, 2
	s_add_u32 s56, s56, 0x100
	s_addc_u32 s57, s57, 0
	s_cmp_gt_u32 s92, 13
	s_mov_b32 s92, s10
	s_cbranch_scc1 .LBB0_169
	s_branch .LBB0_163
.LBB0_162:
	v_add_u32_e32 v144, s82, v171
	ds_read_b128 v[132:135], v144
	ds_read_b128 v[158:161], v144 offset:1024
	ds_read_b128 v[162:165], v144 offset:2048
	ds_read_b128 v[166:169], v144 offset:3072
	v_add_u32_e32 v144, s83, v171
	ds_read_b128 v[184:187], v144
	ds_read_b128 v[188:191], v144 offset:1024
	ds_read_b128 v[192:195], v144 offset:2048
	ds_read_b128 v[196:199], v144 offset:3072
	s_add_u32 s10, s64, 0x100
	s_addc_u32 s95, s65, 0
	s_and_b64 s[64:65], exec, s[62:63]
	s_cselect_b32 s65, s23, s95
	s_cselect_b32 s64, s90, s10
	s_add_u32 s10, s94, 0x100
	s_addc_u32 s93, s93, 0
	s_and_b64 s[62:63], exec, s[62:63]
	s_cselect_b32 s63, s21, s93
	s_cselect_b32 s62, s91, s10
	v_lshl_add_u64 v[232:233], v[128:129], 0, s[56:57]
	s_add_i32 m0, s29, 0xc000
	ds_read_b128 v[200:203], v181
	ds_read_b128 v[204:207], v181 offset:1024
	ds_read_b128 v[208:211], v181 offset:2048
	ds_read_b128 v[212:215], v181 offset:3072
	ds_read_b128 v[216:219], v181 offset:4096
	ds_read_b128 v[220:223], v181 offset:5120
	ds_read_b128 v[224:227], v181 offset:6144
	global_load_lds_dwordx4 v[232:233], off
	v_lshl_add_u64 v[232:233], v[130:131], 0, s[56:57]
	s_add_i32 m0, s29, 0xe000
	ds_read_b128 v[228:231], v181 offset:7168
	global_load_lds_dwordx4 v[232:233], off
	s_waitcnt vmcnt(8)
	s_waitcnt lgkmcnt(0)
	s_setprio 1
	s_barrier
	v_mfma_f32_16x16x32_bf16 v[124:127], v[132:135], v[200:203], v[124:127]
	v_mfma_f32_16x16x32_bf16 v[120:123], v[162:165], v[200:203], v[120:123]
	v_mfma_f32_16x16x32_bf16 v[108:111], v[132:135], v[208:211], v[108:111]
	v_mfma_f32_16x16x32_bf16 v[104:107], v[162:165], v[208:211], v[104:107]
	v_mfma_f32_16x16x32_bf16 v[92:95], v[132:135], v[216:219], v[92:95]
	v_mfma_f32_16x16x32_bf16 v[88:91], v[162:165], v[216:219], v[88:91]
	v_mfma_f32_16x16x32_bf16 v[76:79], v[132:135], v[224:227], v[76:79]
	v_mfma_f32_16x16x32_bf16 v[72:75], v[162:165], v[224:227], v[72:75]
	v_mfma_f32_16x16x32_bf16 v[124:127], v[158:161], v[204:207], v[124:127]
	v_mfma_f32_16x16x32_bf16 v[120:123], v[166:169], v[204:207], v[120:123]
	v_mfma_f32_16x16x32_bf16 v[108:111], v[158:161], v[212:215], v[108:111]
	v_mfma_f32_16x16x32_bf16 v[104:107], v[166:169], v[212:215], v[104:107]
	v_mfma_f32_16x16x32_bf16 v[92:95], v[158:161], v[220:223], v[92:95]
	v_mfma_f32_16x16x32_bf16 v[88:91], v[166:169], v[220:223], v[88:91]
	v_mfma_f32_16x16x32_bf16 v[76:79], v[158:161], v[228:231], v[76:79]
	v_mfma_f32_16x16x32_bf16 v[72:75], v[166:169], v[228:231], v[72:75]
	s_setprio 0
	s_setprio 1
	v_mfma_f32_16x16x32_bf16 v[116:119], v[184:187], v[200:203], v[116:119]
	v_mfma_f32_16x16x32_bf16 v[112:115], v[192:195], v[200:203], v[112:115]
	v_mfma_f32_16x16x32_bf16 v[100:103], v[184:187], v[208:211], v[100:103]
	v_mfma_f32_16x16x32_bf16 v[96:99], v[192:195], v[208:211], v[96:99]
	v_mfma_f32_16x16x32_bf16 v[84:87], v[184:187], v[216:219], v[84:87]
	v_mfma_f32_16x16x32_bf16 v[80:83], v[192:195], v[216:219], v[80:83]
	v_mfma_f32_16x16x32_bf16 v[68:71], v[184:187], v[224:227], v[68:71]
	v_mfma_f32_16x16x32_bf16 v[64:67], v[192:195], v[224:227], v[64:67]
	v_mfma_f32_16x16x32_bf16 v[116:119], v[188:191], v[204:207], v[116:119]
	v_mfma_f32_16x16x32_bf16 v[112:115], v[196:199], v[204:207], v[112:115]
	v_mfma_f32_16x16x32_bf16 v[100:103], v[188:191], v[212:215], v[100:103]
	v_mfma_f32_16x16x32_bf16 v[96:99], v[196:199], v[212:215], v[96:99]
	v_mfma_f32_16x16x32_bf16 v[84:87], v[188:191], v[220:223], v[84:87]
	v_mfma_f32_16x16x32_bf16 v[80:83], v[196:199], v[220:223], v[80:83]
	v_mfma_f32_16x16x32_bf16 v[68:71], v[188:191], v[228:231], v[68:71]
	v_mfma_f32_16x16x32_bf16 v[64:67], v[196:199], v[228:231], v[64:67]
	s_setprio 0
	s_barrier
	s_add_i32 s10, s82, s66
	s_mov_b32 m0, s10
	ds_read_b128 v[200:203], v181 offset:16384
	ds_read_b128 v[204:207], v181 offset:17408
	ds_read_b128 v[208:211], v181 offset:18432
	global_load_lds_dwordx4 v138, s[62:63]
	s_add_i32 m0, s10, 0x2000
	ds_read_b128 v[212:215], v181 offset:19456
	global_load_lds_dwordx4 v142, s[62:63]
	s_add_u32 s62, s62, 0x40000
	s_addc_u32 s63, s63, 0
	s_add_i32 s10, s83, s66
	s_mov_b32 m0, s10
	ds_read_b128 v[216:219], v181 offset:20480
	global_load_lds_dwordx4 v138, s[62:63]
	s_add_i32 m0, s10, 0x2000
	ds_read_b128 v[220:223], v181 offset:21504
	global_load_lds_dwordx4 v142, s[62:63]
	s_mov_b32 m0, s29
	ds_read_b128 v[224:227], v181 offset:22528
	global_load_lds_dwordx4 v136, s[64:65]
	s_mov_b32 m0, s31
	ds_read_b128 v[228:231], v181 offset:23552
	global_load_lds_dwordx4 v140, s[64:65]
	s_waitcnt vmcnt(8)
	s_waitcnt lgkmcnt(0)
	s_setprio 1
	s_barrier
	v_mfma_f32_16x16x32_bf16 v[60:63], v[132:135], v[200:203], v[60:63]
	v_mfma_f32_16x16x32_bf16 v[56:59], v[162:165], v[200:203], v[56:59]
	v_mfma_f32_16x16x32_bf16 v[44:47], v[132:135], v[208:211], v[44:47]
	v_mfma_f32_16x16x32_bf16 v[40:43], v[162:165], v[208:211], v[40:43]
	v_mfma_f32_16x16x32_bf16 v[28:31], v[132:135], v[216:219], v[28:31]
	v_mfma_f32_16x16x32_bf16 v[24:27], v[162:165], v[216:219], v[24:27]
	v_mfma_f32_16x16x32_bf16 v[12:15], v[132:135], v[224:227], v[12:15]
	v_mfma_f32_16x16x32_bf16 v[8:11], v[162:165], v[224:227], v[8:11]
	v_mfma_f32_16x16x32_bf16 v[60:63], v[158:161], v[204:207], v[60:63]
	v_mfma_f32_16x16x32_bf16 v[56:59], v[166:169], v[204:207], v[56:59]
	v_mfma_f32_16x16x32_bf16 v[44:47], v[158:161], v[212:215], v[44:47]
	v_mfma_f32_16x16x32_bf16 v[40:43], v[166:169], v[212:215], v[40:43]
	v_mfma_f32_16x16x32_bf16 v[28:31], v[158:161], v[220:223], v[28:31]
	v_mfma_f32_16x16x32_bf16 v[24:27], v[166:169], v[220:223], v[24:27]
	v_mfma_f32_16x16x32_bf16 v[12:15], v[158:161], v[228:231], v[12:15]
	v_mfma_f32_16x16x32_bf16 v[8:11], v[166:169], v[228:231], v[8:11]
	s_setprio 0
	s_setprio 1
	v_mfma_f32_16x16x32_bf16 v[52:55], v[184:187], v[200:203], v[52:55]
	v_mfma_f32_16x16x32_bf16 v[48:51], v[192:195], v[200:203], v[48:51]
	v_mfma_f32_16x16x32_bf16 v[36:39], v[184:187], v[208:211], v[36:39]
	v_mfma_f32_16x16x32_bf16 v[32:35], v[192:195], v[208:211], v[32:35]
	v_mfma_f32_16x16x32_bf16 v[20:23], v[184:187], v[216:219], v[20:23]
	v_mfma_f32_16x16x32_bf16 v[16:19], v[192:195], v[216:219], v[16:19]
	v_mfma_f32_16x16x32_bf16 v[4:7], v[184:187], v[224:227], v[4:7]
	v_mfma_f32_16x16x32_bf16 v[0:3], v[192:195], v[224:227], v[0:3]
	v_mfma_f32_16x16x32_bf16 v[52:55], v[188:191], v[204:207], v[52:55]
	v_mfma_f32_16x16x32_bf16 v[48:51], v[196:199], v[204:207], v[48:51]
	v_mfma_f32_16x16x32_bf16 v[36:39], v[188:191], v[212:215], v[36:39]
	v_mfma_f32_16x16x32_bf16 v[32:35], v[196:199], v[212:215], v[32:35]
	v_mfma_f32_16x16x32_bf16 v[20:23], v[188:191], v[220:223], v[20:23]
	v_mfma_f32_16x16x32_bf16 v[16:19], v[196:199], v[220:223], v[16:19]
	v_mfma_f32_16x16x32_bf16 v[4:7], v[188:191], v[228:231], v[4:7]
	v_mfma_f32_16x16x32_bf16 v[0:3], v[196:199], v[228:231], v[0:3]
	s_setprio 0
	s_barrier
	s_add_i32 s10, 0, 0x18000
	v_add_u32_e32 v144, s10, v171
	s_add_i32 s93, 0, 0x1c000
	ds_read_b128 v[132:135], v144
	ds_read_b128 v[158:161], v144 offset:1024
	ds_read_b128 v[162:165], v144 offset:2048
	ds_read_b128 v[166:169], v144 offset:3072
	v_add_u32_e32 v144, s93, v171
	ds_read_b128 v[184:187], v144
	ds_read_b128 v[188:191], v144 offset:1024
	ds_read_b128 v[192:195], v144 offset:2048
	ds_read_b128 v[196:199], v144 offset:3072
	s_add_u32 s62, s64, 0x40000
	s_addc_u32 s63, s65, 0
	s_mov_b32 m0, s67
	ds_read_b128 v[200:203], v181 offset:32768
	ds_read_b128 v[204:207], v181 offset:33792
	ds_read_b128 v[208:211], v181 offset:34816
	ds_read_b128 v[212:215], v181 offset:35840
	ds_read_b128 v[216:219], v181 offset:36864
	ds_read_b128 v[220:223], v181 offset:37888
	ds_read_b128 v[224:227], v181 offset:38912
	global_load_lds_dwordx4 v136, s[62:63]
	s_mov_b32 m0, s68
	ds_read_b128 v[228:231], v181 offset:39936
	global_load_lds_dwordx4 v140, s[62:63]
	s_waitcnt vmcnt(8)
	s_waitcnt lgkmcnt(0)
	s_setprio 1
	s_barrier
	v_mfma_f32_16x16x32_bf16 v[124:127], v[132:135], v[200:203], v[124:127]
	v_mfma_f32_16x16x32_bf16 v[120:123], v[162:165], v[200:203], v[120:123]
	v_mfma_f32_16x16x32_bf16 v[108:111], v[132:135], v[208:211], v[108:111]
	v_mfma_f32_16x16x32_bf16 v[104:107], v[162:165], v[208:211], v[104:107]
	v_mfma_f32_16x16x32_bf16 v[92:95], v[132:135], v[216:219], v[92:95]
	v_mfma_f32_16x16x32_bf16 v[88:91], v[162:165], v[216:219], v[88:91]
	v_mfma_f32_16x16x32_bf16 v[76:79], v[132:135], v[224:227], v[76:79]
	v_mfma_f32_16x16x32_bf16 v[72:75], v[162:165], v[224:227], v[72:75]
	v_mfma_f32_16x16x32_bf16 v[124:127], v[158:161], v[204:207], v[124:127]
	v_mfma_f32_16x16x32_bf16 v[120:123], v[166:169], v[204:207], v[120:123]
	v_mfma_f32_16x16x32_bf16 v[108:111], v[158:161], v[212:215], v[108:111]
	v_mfma_f32_16x16x32_bf16 v[104:107], v[166:169], v[212:215], v[104:107]
	v_mfma_f32_16x16x32_bf16 v[92:95], v[158:161], v[220:223], v[92:95]
	v_mfma_f32_16x16x32_bf16 v[88:91], v[166:169], v[220:223], v[88:91]
	v_mfma_f32_16x16x32_bf16 v[76:79], v[158:161], v[228:231], v[76:79]
	v_mfma_f32_16x16x32_bf16 v[72:75], v[166:169], v[228:231], v[72:75]
	s_setprio 0
	s_setprio 1
	v_mfma_f32_16x16x32_bf16 v[116:119], v[184:187], v[200:203], v[116:119]
	v_mfma_f32_16x16x32_bf16 v[112:115], v[192:195], v[200:203], v[112:115]
	v_mfma_f32_16x16x32_bf16 v[100:103], v[184:187], v[208:211], v[100:103]
	v_mfma_f32_16x16x32_bf16 v[96:99], v[192:195], v[208:211], v[96:99]
	v_mfma_f32_16x16x32_bf16 v[84:87], v[184:187], v[216:219], v[84:87]
	v_mfma_f32_16x16x32_bf16 v[80:83], v[192:195], v[216:219], v[80:83]
	v_mfma_f32_16x16x32_bf16 v[68:71], v[184:187], v[224:227], v[68:71]
	v_mfma_f32_16x16x32_bf16 v[64:67], v[192:195], v[224:227], v[64:67]
	v_mfma_f32_16x16x32_bf16 v[116:119], v[188:191], v[204:207], v[116:119]
	v_mfma_f32_16x16x32_bf16 v[112:115], v[196:199], v[204:207], v[112:115]
	v_mfma_f32_16x16x32_bf16 v[100:103], v[188:191], v[212:215], v[100:103]
	v_mfma_f32_16x16x32_bf16 v[96:99], v[196:199], v[212:215], v[96:99]
	v_mfma_f32_16x16x32_bf16 v[84:87], v[188:191], v[220:223], v[84:87]
	v_mfma_f32_16x16x32_bf16 v[80:83], v[196:199], v[220:223], v[80:83]
	v_mfma_f32_16x16x32_bf16 v[68:71], v[188:191], v[228:231], v[68:71]
	v_mfma_f32_16x16x32_bf16 v[64:67], v[196:199], v[228:231], v[64:67]
	s_setprio 0
	s_barrier
	s_add_i32 s10, s10, s66
	s_mov_b32 m0, s10
	ds_read_b128 v[200:203], v181 offset:49152
	ds_read_b128 v[204:207], v181 offset:50176
	ds_read_b128 v[208:211], v181 offset:51200
	global_load_lds_dwordx4 v138, s[60:61]
	s_add_i32 m0, s10, 0x2000
	ds_read_b128 v[212:215], v181 offset:52224
	global_load_lds_dwordx4 v142, s[60:61]
	s_add_u32 s60, s60, 0x40000
	s_addc_u32 s61, s61, 0
	s_add_i32 s10, s93, s66
	s_mov_b32 m0, s10
	ds_read_b128 v[216:219], v181 offset:53248
	global_load_lds_dwordx4 v138, s[60:61]
	s_add_i32 m0, s10, 0x2000
	ds_read_b128 v[220:223], v181 offset:54272
	global_load_lds_dwordx4 v142, s[60:61]
	s_mov_b32 m0, s73
	ds_read_b128 v[224:227], v181 offset:55296
	global_load_lds_dwordx4 v136, s[58:59]
	v_lshl_add_u64 v[232:233], s[58:59], 0, v[140:141]
	s_mov_b32 m0, s78
	ds_read_b128 v[228:231], v181 offset:56320
	global_load_lds_dwordx4 v[232:233], off
	s_waitcnt vmcnt(8)
	s_waitcnt lgkmcnt(0)
	s_setprio 1
	s_barrier
	v_mfma_f32_16x16x32_bf16 v[60:63], v[132:135], v[200:203], v[60:63]
	v_mfma_f32_16x16x32_bf16 v[56:59], v[162:165], v[200:203], v[56:59]
	v_mfma_f32_16x16x32_bf16 v[44:47], v[132:135], v[208:211], v[44:47]
	v_mfma_f32_16x16x32_bf16 v[40:43], v[162:165], v[208:211], v[40:43]
	v_mfma_f32_16x16x32_bf16 v[28:31], v[132:135], v[216:219], v[28:31]
	v_mfma_f32_16x16x32_bf16 v[24:27], v[162:165], v[216:219], v[24:27]
	v_mfma_f32_16x16x32_bf16 v[12:15], v[132:135], v[224:227], v[12:15]
	v_mfma_f32_16x16x32_bf16 v[8:11], v[162:165], v[224:227], v[8:11]
	v_mfma_f32_16x16x32_bf16 v[60:63], v[158:161], v[204:207], v[60:63]
	v_mfma_f32_16x16x32_bf16 v[56:59], v[166:169], v[204:207], v[56:59]
	v_mfma_f32_16x16x32_bf16 v[44:47], v[158:161], v[212:215], v[44:47]
	v_mfma_f32_16x16x32_bf16 v[40:43], v[166:169], v[212:215], v[40:43]
	v_mfma_f32_16x16x32_bf16 v[28:31], v[158:161], v[220:223], v[28:31]
	v_mfma_f32_16x16x32_bf16 v[24:27], v[166:169], v[220:223], v[24:27]
	v_mfma_f32_16x16x32_bf16 v[12:15], v[158:161], v[228:231], v[12:15]
	v_mfma_f32_16x16x32_bf16 v[8:11], v[166:169], v[228:231], v[8:11]
	s_setprio 0
	s_setprio 1
	v_mfma_f32_16x16x32_bf16 v[52:55], v[184:187], v[200:203], v[52:55]
	v_mfma_f32_16x16x32_bf16 v[48:51], v[192:195], v[200:203], v[48:51]
	v_mfma_f32_16x16x32_bf16 v[36:39], v[184:187], v[208:211], v[36:39]
	v_mfma_f32_16x16x32_bf16 v[32:35], v[192:195], v[208:211], v[32:35]
	v_mfma_f32_16x16x32_bf16 v[20:23], v[184:187], v[216:219], v[20:23]
	v_mfma_f32_16x16x32_bf16 v[16:19], v[192:195], v[216:219], v[16:19]
	v_mfma_f32_16x16x32_bf16 v[4:7], v[184:187], v[224:227], v[4:7]
	v_mfma_f32_16x16x32_bf16 v[0:3], v[192:195], v[224:227], v[0:3]
	v_mfma_f32_16x16x32_bf16 v[52:55], v[188:191], v[204:207], v[52:55]
	v_mfma_f32_16x16x32_bf16 v[48:51], v[196:199], v[204:207], v[48:51]
	v_mfma_f32_16x16x32_bf16 v[36:39], v[188:191], v[212:215], v[36:39]
	v_mfma_f32_16x16x32_bf16 v[32:35], v[196:199], v[212:215], v[32:35]
	v_mfma_f32_16x16x32_bf16 v[20:23], v[188:191], v[220:223], v[20:23]
	v_mfma_f32_16x16x32_bf16 v[16:19], v[196:199], v[220:223], v[16:19]
	v_mfma_f32_16x16x32_bf16 v[4:7], v[188:191], v[228:231], v[4:7]
	v_mfma_f32_16x16x32_bf16 v[0:3], v[196:199], v[228:231], v[0:3]
	s_setprio 0
	s_barrier
	s_add_i32 s10, s92, 2
	s_add_u32 s56, s56, 0x100
	s_addc_u32 s57, s57, 0
	s_cmp_gt_u32 s92, 13
	s_mov_b32 s92, s10
	s_cbranch_scc1 .LBB0_169

.LBB0_612:
	s_cmp_lt_u32 s95, 8
	v_add_u32_e32 v157, s79, v155
	s_cselect_b64 s[56:57], -1, 0
	ds_read_b128 v[128:131], v157
	ds_read_b128 v[132:135], v157 offset:1024
	ds_read_b128 v[158:161], v157 offset:2048
	ds_read_b128 v[162:165], v157 offset:3072
	v_add_u32_e32 v157, s80, v155
	s_and_b64 s[96:97], s[56:57], exec
	ds_read_b128 v[166:169], v157
	ds_read_b128 v[170:173], v157 offset:1024
	ds_read_b128 v[174:177], v157 offset:2048
	ds_read_b128 v[178:181], v157 offset:3072
	s_cselect_b32 s8, 0, -8
	s_add_i32 s8, s8, s95
	s_add_i32 s8, s8, 1
	s_and_b64 s[56:57], s[56:57], exec
	s_cselect_b32 s96, s29, s85
	s_cselect_b32 s97, s28, s84
	s_lshl_b64 s[56:57], s[8:9], 7
	s_add_u32 s8, s97, s56
	s_addc_u32 s57, s96, s57
	s_add_u32 s56, s8, 0x160000
	s_addc_u32 s57, s57, 0
	s_add_i32 m0, s62, 0xc000
	ds_read_b128 v[182:185], v156
	ds_read_b128 v[186:189], v156 offset:1024
	ds_read_b128 v[190:193], v156 offset:2048
	ds_read_b128 v[194:197], v156 offset:3072
	ds_read_b128 v[198:201], v156 offset:4096
	ds_read_b128 v[202:205], v156 offset:5120
	ds_read_b128 v[206:209], v156 offset:6144
	ds_read_b128 v[210:213], v156 offset:7168
	global_load_lds_dwordx4 v136, s[56:57]
	s_add_i32 m0, s62, 0xe000
	s_nop 0
	global_load_lds_dwordx4 v140, s[56:57]
	s_waitcnt vmcnt(8)
	s_waitcnt lgkmcnt(0)
	s_setprio 1
	s_barrier
	v_mfma_f32_16x16x32_bf16 v[124:127], v[128:131], v[182:185], v[124:127]
	v_mfma_f32_16x16x32_bf16 v[120:123], v[158:161], v[182:185], v[120:123]
	v_mfma_f32_16x16x32_bf16 v[112:115], v[128:131], v[190:193], v[112:115]
	v_mfma_f32_16x16x32_bf16 v[104:107], v[158:161], v[190:193], v[104:107]
	v_mfma_f32_16x16x32_bf16 v[96:99], v[128:131], v[198:201], v[96:99]
	v_mfma_f32_16x16x32_bf16 v[88:91], v[158:161], v[198:201], v[88:91]
	v_mfma_f32_16x16x32_bf16 v[80:83], v[128:131], v[206:209], v[80:83]
	v_mfma_f32_16x16x32_bf16 v[72:75], v[158:161], v[206:209], v[72:75]
	v_mfma_f32_16x16x32_bf16 v[124:127], v[132:135], v[186:189], v[124:127]
	v_mfma_f32_16x16x32_bf16 v[120:123], v[162:165], v[186:189], v[120:123]
	v_mfma_f32_16x16x32_bf16 v[112:115], v[132:135], v[194:197], v[112:115]
	v_mfma_f32_16x16x32_bf16 v[104:107], v[162:165], v[194:197], v[104:107]
	v_mfma_f32_16x16x32_bf16 v[96:99], v[132:135], v[202:205], v[96:99]
	v_mfma_f32_16x16x32_bf16 v[88:91], v[162:165], v[202:205], v[88:91]
	v_mfma_f32_16x16x32_bf16 v[80:83], v[132:135], v[210:213], v[80:83]
	v_mfma_f32_16x16x32_bf16 v[72:75], v[162:165], v[210:213], v[72:75]
	s_setprio 0
	s_setprio 1
	v_mfma_f32_16x16x32_bf16 v[116:119], v[166:169], v[182:185], v[116:119]
	v_mfma_f32_16x16x32_bf16 v[108:111], v[174:177], v[182:185], v[108:111]
	v_mfma_f32_16x16x32_bf16 v[100:103], v[166:169], v[190:193], v[100:103]
	v_mfma_f32_16x16x32_bf16 v[92:95], v[174:177], v[190:193], v[92:95]
	v_mfma_f32_16x16x32_bf16 v[84:87], v[166:169], v[198:201], v[84:87]
	v_mfma_f32_16x16x32_bf16 v[76:79], v[174:177], v[198:201], v[76:79]
	v_mfma_f32_16x16x32_bf16 v[68:71], v[166:169], v[206:209], v[68:71]
	v_mfma_f32_16x16x32_bf16 v[64:67], v[174:177], v[206:209], v[64:67]
	v_mfma_f32_16x16x32_bf16 v[116:119], v[170:173], v[186:189], v[116:119]
	v_mfma_f32_16x16x32_bf16 v[108:111], v[178:181], v[186:189], v[108:111]
	v_mfma_f32_16x16x32_bf16 v[100:103], v[170:173], v[194:197], v[100:103]
	v_mfma_f32_16x16x32_bf16 v[92:95], v[178:181], v[194:197], v[92:95]
	v_mfma_f32_16x16x32_bf16 v[84:87], v[170:173], v[202:205], v[84:87]
	v_mfma_f32_16x16x32_bf16 v[76:79], v[178:181], v[202:205], v[76:79]
	v_mfma_f32_16x16x32_bf16 v[68:71], v[170:173], v[210:213], v[68:71]
	v_mfma_f32_16x16x32_bf16 v[64:67], v[178:181], v[210:213], v[64:67]
	s_setprio 0
	s_barrier
	s_add_i32 s8, s79, s61
	s_mov_b32 m0, s8
	ds_read_b128 v[182:185], v156 offset:16384
	ds_read_b128 v[186:189], v156 offset:17408
	ds_read_b128 v[190:193], v156 offset:18432
	ds_read_b128 v[194:197], v156 offset:19456
	ds_read_b128 v[198:201], v156 offset:20480
	ds_read_b128 v[202:205], v156 offset:21504
	ds_read_b128 v[206:209], v156 offset:22528
	ds_read_b128 v[210:213], v156 offset:23552
	global_load_lds_dwordx4 v138, s[54:55]
	s_add_i32 m0, s8, 0x2000
	s_nop 0
	global_load_lds_dwordx4 v142, s[54:55]
	s_add_u32 s54, s54, 0x20000
	s_addc_u32 s55, s55, 0
	s_add_i32 s8, s80, s61
	s_mov_b32 m0, s8
	s_nop 0
	global_load_lds_dwordx4 v138, s[54:55]
	s_add_i32 m0, s8, 0x2000
	s_nop 0
	global_load_lds_dwordx4 v142, s[54:55]
	s_mov_b32 m0, s62
	s_nop 0
	global_load_lds_dwordx4 v136, s[50:51]
	s_mov_b32 m0, s63
	s_nop 0
	global_load_lds_dwordx4 v140, s[50:51]
	s_waitcnt vmcnt(8)
	s_waitcnt lgkmcnt(0)
	s_setprio 1
	s_barrier
	v_mfma_f32_16x16x32_bf16 v[60:63], v[128:131], v[182:185], v[60:63]
	v_mfma_f32_16x16x32_bf16 v[56:59], v[158:161], v[182:185], v[56:59]
	v_mfma_f32_16x16x32_bf16 v[48:51], v[128:131], v[190:193], v[48:51]
	v_mfma_f32_16x16x32_bf16 v[40:43], v[158:161], v[190:193], v[40:43]
	v_mfma_f32_16x16x32_bf16 v[32:35], v[128:131], v[198:201], v[32:35]
	v_mfma_f32_16x16x32_bf16 v[24:27], v[158:161], v[198:201], v[24:27]
	v_mfma_f32_16x16x32_bf16 v[16:19], v[128:131], v[206:209], v[16:19]
	v_mfma_f32_16x16x32_bf16 v[8:11], v[158:161], v[206:209], v[8:11]
	v_mfma_f32_16x16x32_bf16 v[60:63], v[132:135], v[186:189], v[60:63]
	v_mfma_f32_16x16x32_bf16 v[56:59], v[162:165], v[186:189], v[56:59]
	v_mfma_f32_16x16x32_bf16 v[48:51], v[132:135], v[194:197], v[48:51]
	v_mfma_f32_16x16x32_bf16 v[40:43], v[162:165], v[194:197], v[40:43]
	v_mfma_f32_16x16x32_bf16 v[32:35], v[132:135], v[202:205], v[32:35]
	v_mfma_f32_16x16x32_bf16 v[24:27], v[162:165], v[202:205], v[24:27]
	v_mfma_f32_16x16x32_bf16 v[16:19], v[132:135], v[210:213], v[16:19]
	v_mfma_f32_16x16x32_bf16 v[8:11], v[162:165], v[210:213], v[8:11]
	s_setprio 0
	s_setprio 1
	v_mfma_f32_16x16x32_bf16 v[52:55], v[166:169], v[182:185], v[52:55]
	v_mfma_f32_16x16x32_bf16 v[44:47], v[174:177], v[182:185], v[44:47]
	v_mfma_f32_16x16x32_bf16 v[36:39], v[166:169], v[190:193], v[36:39]
	v_mfma_f32_16x16x32_bf16 v[28:31], v[174:177], v[190:193], v[28:31]
	v_mfma_f32_16x16x32_bf16 v[20:23], v[166:169], v[198:201], v[20:23]
	v_mfma_f32_16x16x32_bf16 v[12:15], v[174:177], v[198:201], v[12:15]
	v_mfma_f32_16x16x32_bf16 v[4:7], v[166:169], v[206:209], v[4:7]
	v_mfma_f32_16x16x32_bf16 v[0:3], v[174:177], v[206:209], v[0:3]
	v_mfma_f32_16x16x32_bf16 v[52:55], v[170:173], v[186:189], v[52:55]
	v_mfma_f32_16x16x32_bf16 v[44:47], v[178:181], v[186:189], v[44:47]
	v_mfma_f32_16x16x32_bf16 v[36:39], v[170:173], v[194:197], v[36:39]
	v_mfma_f32_16x16x32_bf16 v[28:31], v[178:181], v[194:197], v[28:31]
	v_mfma_f32_16x16x32_bf16 v[20:23], v[170:173], v[202:205], v[20:23]
	v_mfma_f32_16x16x32_bf16 v[12:15], v[178:181], v[202:205], v[12:15]
	v_mfma_f32_16x16x32_bf16 v[4:7], v[170:173], v[210:213], v[4:7]
	v_mfma_f32_16x16x32_bf16 v[0:3], v[178:181], v[210:213], v[0:3]
	s_setprio 0
	s_barrier
	s_add_i32 s8, 0, 0x18000
	v_add_u32_e32 v157, s8, v155
	s_add_i32 s54, 0, 0x1c000
	ds_read_b128 v[128:131], v157
	ds_read_b128 v[132:135], v157 offset:1024
	ds_read_b128 v[158:161], v157 offset:2048
	ds_read_b128 v[162:165], v157 offset:3072
	v_add_u32_e32 v157, s54, v155
	ds_read_b128 v[166:169], v157
	ds_read_b128 v[170:173], v157 offset:1024
	ds_read_b128 v[174:177], v157 offset:2048
	ds_read_b128 v[178:181], v157 offset:3072
	s_add_u32 s50, s50, 0x160000
	s_addc_u32 s51, s51, 0
	s_mov_b32 m0, s64
	ds_read_b128 v[182:185], v156 offset:32768
	ds_read_b128 v[186:189], v156 offset:33792
	ds_read_b128 v[190:193], v156 offset:34816
	ds_read_b128 v[194:197], v156 offset:35840
	ds_read_b128 v[198:201], v156 offset:36864
	ds_read_b128 v[202:205], v156 offset:37888
	ds_read_b128 v[206:209], v156 offset:38912
	ds_read_b128 v[210:213], v156 offset:39936
	global_load_lds_dwordx4 v136, s[50:51]
	s_mov_b32 m0, s65
	s_nop 0
	global_load_lds_dwordx4 v140, s[50:51]
	s_waitcnt vmcnt(8)
	s_waitcnt lgkmcnt(0)
	s_setprio 1
	s_barrier
	v_mfma_f32_16x16x32_bf16 v[124:127], v[128:131], v[182:185], v[124:127]
	v_mfma_f32_16x16x32_bf16 v[120:123], v[158:161], v[182:185], v[120:123]
	v_mfma_f32_16x16x32_bf16 v[112:115], v[128:131], v[190:193], v[112:115]
	v_mfma_f32_16x16x32_bf16 v[104:107], v[158:161], v[190:193], v[104:107]
	v_mfma_f32_16x16x32_bf16 v[96:99], v[128:131], v[198:201], v[96:99]
	v_mfma_f32_16x16x32_bf16 v[88:91], v[158:161], v[198:201], v[88:91]
	v_mfma_f32_16x16x32_bf16 v[80:83], v[128:131], v[206:209], v[80:83]
	v_mfma_f32_16x16x32_bf16 v[72:75], v[158:161], v[206:209], v[72:75]
	v_mfma_f32_16x16x32_bf16 v[124:127], v[132:135], v[186:189], v[124:127]
	v_mfma_f32_16x16x32_bf16 v[120:123], v[162:165], v[186:189], v[120:123]
	v_mfma_f32_16x16x32_bf16 v[112:115], v[132:135], v[194:197], v[112:115]
	v_mfma_f32_16x16x32_bf16 v[104:107], v[162:165], v[194:197], v[104:107]
	v_mfma_f32_16x16x32_bf16 v[96:99], v[132:135], v[202:205], v[96:99]
	v_mfma_f32_16x16x32_bf16 v[88:91], v[162:165], v[202:205], v[88:91]
	v_mfma_f32_16x16x32_bf16 v[80:83], v[132:135], v[210:213], v[80:83]
	v_mfma_f32_16x16x32_bf16 v[72:75], v[162:165], v[210:213], v[72:75]
	s_setprio 0
	s_setprio 1
	v_mfma_f32_16x16x32_bf16 v[116:119], v[166:169], v[182:185], v[116:119]
	v_mfma_f32_16x16x32_bf16 v[108:111], v[174:177], v[182:185], v[108:111]
	v_mfma_f32_16x16x32_bf16 v[100:103], v[166:169], v[190:193], v[100:103]
	v_mfma_f32_16x16x32_bf16 v[92:95], v[174:177], v[190:193], v[92:95]
	v_mfma_f32_16x16x32_bf16 v[84:87], v[166:169], v[198:201], v[84:87]
	v_mfma_f32_16x16x32_bf16 v[76:79], v[174:177], v[198:201], v[76:79]
	v_mfma_f32_16x16x32_bf16 v[68:71], v[166:169], v[206:209], v[68:71]
	v_mfma_f32_16x16x32_bf16 v[64:67], v[174:177], v[206:209], v[64:67]
	v_mfma_f32_16x16x32_bf16 v[116:119], v[170:173], v[186:189], v[116:119]
	v_mfma_f32_16x16x32_bf16 v[108:111], v[178:181], v[186:189], v[108:111]
	v_mfma_f32_16x16x32_bf16 v[100:103], v[170:173], v[194:197], v[100:103]
	v_mfma_f32_16x16x32_bf16 v[92:95], v[178:181], v[194:197], v[92:95]
	v_mfma_f32_16x16x32_bf16 v[84:87], v[170:173], v[202:205], v[84:87]
	v_mfma_f32_16x16x32_bf16 v[76:79], v[178:181], v[202:205], v[76:79]
	v_mfma_f32_16x16x32_bf16 v[68:71], v[170:173], v[210:213], v[68:71]
	v_mfma_f32_16x16x32_bf16 v[64:67], v[178:181], v[210:213], v[64:67]
	s_setprio 0
	s_barrier
	s_add_i32 s8, s8, s61
	s_mov_b32 m0, s8
	ds_read_b128 v[182:185], v156 offset:49152
	ds_read_b128 v[186:189], v156 offset:50176
	ds_read_b128 v[190:193], v156 offset:51200
	ds_read_b128 v[194:197], v156 offset:52224
	ds_read_b128 v[198:201], v156 offset:53248
	ds_read_b128 v[202:205], v156 offset:54272
	ds_read_b128 v[206:209], v156 offset:55296
	ds_read_b128 v[210:213], v156 offset:56320
	global_load_lds_dwordx4 v138, s[4:5]
	s_add_i32 m0, s8, 0x2000
	s_nop 0
	global_load_lds_dwordx4 v142, s[4:5]
	s_add_u32 s4, s4, 0x20000
	s_addc_u32 s5, s5, 0
	s_add_i32 s8, s54, s61
	s_mov_b32 m0, s8
	s_nop 0
	global_load_lds_dwordx4 v138, s[4:5]
	s_add_i32 m0, s8, 0x2000
	s_nop 0
	global_load_lds_dwordx4 v142, s[4:5]
	s_mov_b32 m0, s71
	s_nop 0
	global_load_lds_dwordx4 v136, s[52:53]
	s_mov_b32 m0, s72
	s_nop 0
	global_load_lds_dwordx4 v140, s[52:53]
	s_waitcnt vmcnt(8)
	s_waitcnt lgkmcnt(0)
	s_setprio 1
	s_barrier
	v_mfma_f32_16x16x32_bf16 v[60:63], v[128:131], v[182:185], v[60:63]
	v_mfma_f32_16x16x32_bf16 v[56:59], v[158:161], v[182:185], v[56:59]
	v_mfma_f32_16x16x32_bf16 v[48:51], v[128:131], v[190:193], v[48:51]
	v_mfma_f32_16x16x32_bf16 v[40:43], v[158:161], v[190:193], v[40:43]
	v_mfma_f32_16x16x32_bf16 v[32:35], v[128:131], v[198:201], v[32:35]
	v_mfma_f32_16x16x32_bf16 v[24:27], v[158:161], v[198:201], v[24:27]
	v_mfma_f32_16x16x32_bf16 v[16:19], v[128:131], v[206:209], v[16:19]
	v_mfma_f32_16x16x32_bf16 v[8:11], v[158:161], v[206:209], v[8:11]
	v_mfma_f32_16x16x32_bf16 v[60:63], v[132:135], v[186:189], v[60:63]
	v_mfma_f32_16x16x32_bf16 v[56:59], v[162:165], v[186:189], v[56:59]
	v_mfma_f32_16x16x32_bf16 v[48:51], v[132:135], v[194:197], v[48:51]
	v_mfma_f32_16x16x32_bf16 v[40:43], v[162:165], v[194:197], v[40:43]
	v_mfma_f32_16x16x32_bf16 v[32:35], v[132:135], v[202:205], v[32:35]
	v_mfma_f32_16x16x32_bf16 v[24:27], v[162:165], v[202:205], v[24:27]
	v_mfma_f32_16x16x32_bf16 v[16:19], v[132:135], v[210:213], v[16:19]
	v_mfma_f32_16x16x32_bf16 v[8:11], v[162:165], v[210:213], v[8:11]
	s_setprio 0
	s_setprio 1
	v_mfma_f32_16x16x32_bf16 v[52:55], v[166:169], v[182:185], v[52:55]
	v_mfma_f32_16x16x32_bf16 v[44:47], v[174:177], v[182:185], v[44:47]
	v_mfma_f32_16x16x32_bf16 v[36:39], v[166:169], v[190:193], v[36:39]
	v_mfma_f32_16x16x32_bf16 v[28:31], v[174:177], v[190:193], v[28:31]
	v_mfma_f32_16x16x32_bf16 v[20:23], v[166:169], v[198:201], v[20:23]
	v_mfma_f32_16x16x32_bf16 v[12:15], v[174:177], v[198:201], v[12:15]
	v_mfma_f32_16x16x32_bf16 v[4:7], v[166:169], v[206:209], v[4:7]
	v_mfma_f32_16x16x32_bf16 v[0:3], v[174:177], v[206:209], v[0:3]
	v_mfma_f32_16x16x32_bf16 v[52:55], v[170:173], v[186:189], v[52:55]
	v_mfma_f32_16x16x32_bf16 v[44:47], v[178:181], v[186:189], v[44:47]
	v_mfma_f32_16x16x32_bf16 v[36:39], v[170:173], v[194:197], v[36:39]
	v_mfma_f32_16x16x32_bf16 v[28:31], v[178:181], v[194:197], v[28:31]
	v_mfma_f32_16x16x32_bf16 v[20:23], v[170:173], v[202:205], v[20:23]
	v_mfma_f32_16x16x32_bf16 v[12:15], v[178:181], v[202:205], v[12:15]
	v_mfma_f32_16x16x32_bf16 v[4:7], v[170:173], v[210:213], v[4:7]
	v_mfma_f32_16x16x32_bf16 v[0:3], v[178:181], v[210:213], v[0:3]
	s_setprio 0
	s_barrier
	s_add_i32 s4, s95, 2
	s_add_u32 s48, s48, 0x100
	s_addc_u32 s49, s49, 0
	s_cmp_gt_u32 s95, 13
	s_mov_b32 s95, s4
	s_cbranch_scc1 .LBB0_635

.LBB0_713:
	s_add_u32 s19, s63, s6
	s_addc_u32 s29, s64, s7
	s_add_u32 s31, s65, s8
	s_addc_u32 s79, s66, s9
	s_ashr_i32 s23, s22, 31
	s_lshl_b64 s[6:7], s[22:23], 19
	s_add_u32 s24, s34, s6
	s_addc_u32 s25, s35, s7
	s_and_b64 s[8:9], s[4:5], exec
	s_cselect_b32 s23, s25, s45
	s_cselect_b32 s80, s24, s44
	s_ashr_i32 s21, s20, 31
	s_lshl_b64 s[8:9], s[20:21], 19
	s_add_u32 s26, s42, s8
	s_addc_u32 s27, s43, s9
	s_and_b64 s[36:37], s[4:5], exec
	s_cselect_b32 s21, s27, s39
	s_cselect_b32 s81, s26, s38
	s_add_u32 s36, s80, 0x80
	s_addc_u32 s37, s23, 0
	s_add_u32 s46, s81, 0x80
	s_addc_u32 s47, s21, 0
	v_lshl_add_u64 v[128:129], s[44:45], 0, v[156:157]
	v_lshl_add_u64 v[130:131], s[44:45], 0, v[158:159]
	s_mov_b32 s82, 0
	s_mov_b64 s[48:49], 0
	s_cmpk_eq_i32 s48, 0x700
	s_cselect_b64 s[54:55], -1, 0
	s_add_u32 s56, s44, s48
	s_addc_u32 s57, s45, s49
	s_add_u32 s84, s38, s48
	s_addc_u32 s83, s39, s49
	s_add_u32 s50, s56, 0x180
	s_addc_u32 s51, s57, 0
	s_add_u32 s52, s84, 0x180
	s_addc_u32 s53, s83, 0
	s_cmpk_eq_i32 s48, 0x700
	s_cselect_b32 s50, s36, s50
	s_cselect_b32 s51, s37, s51
	s_cselect_b32 s52, s46, s52
	s_cselect_b32 s53, s47, s53
	v_add_u32_e32 v164, s72, v171
	v_add_u32_e32 v168, s73, v171
	ds_read_b128 v[132:135], v164
	ds_read_b128 v[136:139], v164 offset:1024
	ds_read_b128 v[140:143], v164 offset:2048
	ds_read_b128 v[164:167], v164 offset:3072
	ds_read_b128 v[174:177], v168
	ds_read_b128 v[178:181], v168 offset:1024
	ds_read_b128 v[182:185], v168 offset:2048
	ds_read_b128 v[186:189], v168 offset:3072
	s_add_u32 s10, s56, 0x100
	s_addc_u32 s85, s57, 0
	s_and_b64 s[56:57], exec, s[54:55]
	s_cselect_b32 s57, s23, s85
	s_cselect_b32 s56, s80, s10
	s_add_u32 s10, s84, 0x100
	s_addc_u32 s83, s83, 0
	s_and_b64 s[54:55], exec, s[54:55]
	s_cselect_b32 s55, s21, s83
	s_cselect_b32 s54, s81, s10
	v_lshl_add_u64 v[168:169], v[128:129], 0, s[48:49]
	s_add_i32 m0, s59, 0xc000
	ds_read_b128 v[190:193], v172
	ds_read_b128 v[194:197], v172 offset:1024
	ds_read_b128 v[198:201], v172 offset:2048
	ds_read_b128 v[202:205], v172 offset:3072
	ds_read_b128 v[206:209], v172 offset:4096
	ds_read_b128 v[210:213], v172 offset:5120
	ds_read_b128 v[214:217], v172 offset:6144
	global_load_lds_dwordx4 v[168:169], off
	v_lshl_add_u64 v[168:169], v[130:131], 0, s[48:49]
	s_add_i32 m0, s59, 0xe000
	ds_read_b128 v[218:221], v172 offset:7168
	global_load_lds_dwordx4 v[168:169], off
	s_waitcnt vmcnt(8)
	s_waitcnt lgkmcnt(0)
	s_setprio 1
	s_barrier
	v_mfma_f32_16x16x32_bf16 v[124:127], v[132:135], v[190:193], 0
	v_mfma_f32_16x16x32_bf16 v[120:123], v[140:143], v[190:193], 0
	v_mfma_f32_16x16x32_bf16 v[108:111], v[132:135], v[198:201], 0
	v_mfma_f32_16x16x32_bf16 v[104:107], v[140:143], v[198:201], 0
	v_mfma_f32_16x16x32_bf16 v[92:95], v[132:135], v[206:209], 0
	v_mfma_f32_16x16x32_bf16 v[88:91], v[140:143], v[206:209], 0
	v_mfma_f32_16x16x32_bf16 v[76:79], v[132:135], v[214:217], 0
	v_mfma_f32_16x16x32_bf16 v[72:75], v[140:143], v[214:217], 0
	v_mfma_f32_16x16x32_bf16 v[124:127], v[136:139], v[194:197], v[124:127]
	v_mfma_f32_16x16x32_bf16 v[120:123], v[164:167], v[194:197], v[120:123]
	v_mfma_f32_16x16x32_bf16 v[108:111], v[136:139], v[202:205], v[108:111]
	v_mfma_f32_16x16x32_bf16 v[104:107], v[164:167], v[202:205], v[104:107]
	v_mfma_f32_16x16x32_bf16 v[92:95], v[136:139], v[210:213], v[92:95]
	v_mfma_f32_16x16x32_bf16 v[88:91], v[164:167], v[210:213], v[88:91]
	v_mfma_f32_16x16x32_bf16 v[76:79], v[136:139], v[218:221], v[76:79]
	v_mfma_f32_16x16x32_bf16 v[72:75], v[164:167], v[218:221], v[72:75]
	s_setprio 0
	s_setprio 1
	v_mfma_f32_16x16x32_bf16 v[116:119], v[174:177], v[190:193], 0
	v_mfma_f32_16x16x32_bf16 v[112:115], v[182:185], v[190:193], 0
	v_mfma_f32_16x16x32_bf16 v[100:103], v[174:177], v[198:201], 0
	v_mfma_f32_16x16x32_bf16 v[96:99], v[182:185], v[198:201], 0
	v_mfma_f32_16x16x32_bf16 v[84:87], v[174:177], v[206:209], 0
	v_mfma_f32_16x16x32_bf16 v[80:83], v[182:185], v[206:209], 0
	v_mfma_f32_16x16x32_bf16 v[68:71], v[174:177], v[214:217], 0
	v_mfma_f32_16x16x32_bf16 v[64:67], v[182:185], v[214:217], 0
	v_mfma_f32_16x16x32_bf16 v[116:119], v[178:181], v[194:197], v[116:119]
	v_mfma_f32_16x16x32_bf16 v[112:115], v[186:189], v[194:197], v[112:115]
	v_mfma_f32_16x16x32_bf16 v[100:103], v[178:181], v[202:205], v[100:103]
	v_mfma_f32_16x16x32_bf16 v[96:99], v[186:189], v[202:205], v[96:99]
	v_mfma_f32_16x16x32_bf16 v[84:87], v[178:181], v[210:213], v[84:87]
	v_mfma_f32_16x16x32_bf16 v[80:83], v[186:189], v[210:213], v[80:83]
	v_mfma_f32_16x16x32_bf16 v[68:71], v[178:181], v[218:221], v[68:71]
	v_mfma_f32_16x16x32_bf16 v[64:67], v[186:189], v[218:221], v[64:67]
	s_setprio 0
	s_barrier
	s_add_i32 s10, s72, s58
	s_mov_b32 m0, s10
	ds_read_b128 v[190:193], v172 offset:16384
	ds_read_b128 v[194:197], v172 offset:17408
	ds_read_b128 v[198:201], v172 offset:18432
	global_load_lds_dwordx4 v146, s[54:55]
	s_add_i32 m0, s10, 0x2000
	ds_read_b128 v[202:205], v172 offset:19456
	global_load_lds_dwordx4 v150, s[54:55]
	s_add_u32 s54, s54, 0x40000
	s_addc_u32 s55, s55, 0
	s_add_i32 s10, s73, s58
	s_mov_b32 m0, s10
	ds_read_b128 v[206:209], v172 offset:20480
	global_load_lds_dwordx4 v146, s[54:55]
	s_add_i32 m0, s10, 0x2000
	ds_read_b128 v[210:213], v172 offset:21504
	global_load_lds_dwordx4 v150, s[54:55]
	s_mov_b32 m0, s59
	ds_read_b128 v[214:217], v172 offset:22528
	global_load_lds_dwordx4 v144, s[56:57]
	s_mov_b32 m0, s60
	ds_read_b128 v[218:221], v172 offset:23552
	global_load_lds_dwordx4 v148, s[56:57]
	s_waitcnt vmcnt(8)
	s_waitcnt lgkmcnt(0)
	s_setprio 1
	s_barrier
	v_mfma_f32_16x16x32_bf16 v[60:63], v[132:135], v[190:193], 0
	v_mfma_f32_16x16x32_bf16 v[56:59], v[140:143], v[190:193], 0
	v_mfma_f32_16x16x32_bf16 v[44:47], v[132:135], v[198:201], 0
	v_mfma_f32_16x16x32_bf16 v[40:43], v[140:143], v[198:201], 0
	v_mfma_f32_16x16x32_bf16 v[28:31], v[132:135], v[206:209], 0
	v_mfma_f32_16x16x32_bf16 v[24:27], v[140:143], v[206:209], 0
	v_mfma_f32_16x16x32_bf16 v[12:15], v[132:135], v[214:217], 0
	v_mfma_f32_16x16x32_bf16 v[8:11], v[140:143], v[214:217], 0
	v_mfma_f32_16x16x32_bf16 v[60:63], v[136:139], v[194:197], v[60:63]
	v_mfma_f32_16x16x32_bf16 v[56:59], v[164:167], v[194:197], v[56:59]
	v_mfma_f32_16x16x32_bf16 v[44:47], v[136:139], v[202:205], v[44:47]
	v_mfma_f32_16x16x32_bf16 v[40:43], v[164:167], v[202:205], v[40:43]
	v_mfma_f32_16x16x32_bf16 v[28:31], v[136:139], v[210:213], v[28:31]
	v_mfma_f32_16x16x32_bf16 v[24:27], v[164:167], v[210:213], v[24:27]
	v_mfma_f32_16x16x32_bf16 v[12:15], v[136:139], v[218:221], v[12:15]
	v_mfma_f32_16x16x32_bf16 v[8:11], v[164:167], v[218:221], v[8:11]
	s_setprio 0
	s_setprio 1
	v_mfma_f32_16x16x32_bf16 v[52:55], v[174:177], v[190:193], 0
	v_mfma_f32_16x16x32_bf16 v[48:51], v[182:185], v[190:193], 0
	v_mfma_f32_16x16x32_bf16 v[36:39], v[174:177], v[198:201], 0
	v_mfma_f32_16x16x32_bf16 v[32:35], v[182:185], v[198:201], 0
	v_mfma_f32_16x16x32_bf16 v[20:23], v[174:177], v[206:209], 0
	v_mfma_f32_16x16x32_bf16 v[16:19], v[182:185], v[206:209], 0
	v_mfma_f32_16x16x32_bf16 v[4:7], v[174:177], v[214:217], 0
	v_mfma_f32_16x16x32_bf16 v[0:3], v[182:185], v[214:217], 0
	v_mfma_f32_16x16x32_bf16 v[52:55], v[178:181], v[194:197], v[52:55]
	v_mfma_f32_16x16x32_bf16 v[48:51], v[186:189], v[194:197], v[48:51]
	v_mfma_f32_16x16x32_bf16 v[36:39], v[178:181], v[202:205], v[36:39]
	v_mfma_f32_16x16x32_bf16 v[32:35], v[186:189], v[202:205], v[32:35]
	v_mfma_f32_16x16x32_bf16 v[20:23], v[178:181], v[210:213], v[20:23]
	v_mfma_f32_16x16x32_bf16 v[16:19], v[186:189], v[210:213], v[16:19]
	v_mfma_f32_16x16x32_bf16 v[4:7], v[178:181], v[218:221], v[4:7]
	v_mfma_f32_16x16x32_bf16 v[0:3], v[186:189], v[218:221], v[0:3]
	s_setprio 0
	s_barrier
	s_add_i32 s10, 0, 0x18000
	s_add_i32 s83, 0, 0x1c000
	v_add_u32_e32 v164, s10, v171
	v_add_u32_e32 v168, s83, v171
	ds_read_b128 v[132:135], v164
	ds_read_b128 v[136:139], v164 offset:1024
	ds_read_b128 v[140:143], v164 offset:2048
	ds_read_b128 v[164:167], v164 offset:3072
	ds_read_b128 v[174:177], v168
	ds_read_b128 v[178:181], v168 offset:1024
	ds_read_b128 v[182:185], v168 offset:2048
	ds_read_b128 v[186:189], v168 offset:3072
	s_add_u32 s54, s56, 0x40000
	s_addc_u32 s55, s57, 0
	s_mov_b32 m0, s61
	ds_read_b128 v[190:193], v172 offset:32768
	ds_read_b128 v[194:197], v172 offset:33792
	ds_read_b128 v[198:201], v172 offset:34816
	ds_read_b128 v[202:205], v172 offset:35840
	ds_read_b128 v[206:209], v172 offset:36864
	ds_read_b128 v[210:213], v172 offset:37888
	ds_read_b128 v[214:217], v172 offset:38912
	global_load_lds_dwordx4 v144, s[54:55]
	s_mov_b32 m0, s62
	ds_read_b128 v[218:221], v172 offset:39936
	global_load_lds_dwordx4 v148, s[54:55]
	s_waitcnt vmcnt(8)
	s_waitcnt lgkmcnt(0)
	s_setprio 1
	s_barrier
	v_mfma_f32_16x16x32_bf16 v[124:127], v[132:135], v[190:193], v[124:127]
	v_mfma_f32_16x16x32_bf16 v[120:123], v[140:143], v[190:193], v[120:123]
	v_mfma_f32_16x16x32_bf16 v[108:111], v[132:135], v[198:201], v[108:111]
	v_mfma_f32_16x16x32_bf16 v[104:107], v[140:143], v[198:201], v[104:107]
	v_mfma_f32_16x16x32_bf16 v[92:95], v[132:135], v[206:209], v[92:95]
	v_mfma_f32_16x16x32_bf16 v[88:91], v[140:143], v[206:209], v[88:91]
	v_mfma_f32_16x16x32_bf16 v[76:79], v[132:135], v[214:217], v[76:79]
	v_mfma_f32_16x16x32_bf16 v[72:75], v[140:143], v[214:217], v[72:75]
	v_mfma_f32_16x16x32_bf16 v[124:127], v[136:139], v[194:197], v[124:127]
	v_mfma_f32_16x16x32_bf16 v[120:123], v[164:167], v[194:197], v[120:123]
	v_mfma_f32_16x16x32_bf16 v[108:111], v[136:139], v[202:205], v[108:111]
	v_mfma_f32_16x16x32_bf16 v[104:107], v[164:167], v[202:205], v[104:107]
	v_mfma_f32_16x16x32_bf16 v[92:95], v[136:139], v[210:213], v[92:95]
	v_mfma_f32_16x16x32_bf16 v[88:91], v[164:167], v[210:213], v[88:91]
	v_mfma_f32_16x16x32_bf16 v[76:79], v[136:139], v[218:221], v[76:79]
	v_mfma_f32_16x16x32_bf16 v[72:75], v[164:167], v[218:221], v[72:75]
	s_setprio 0
	s_setprio 1
	v_mfma_f32_16x16x32_bf16 v[116:119], v[174:177], v[190:193], v[116:119]
	v_mfma_f32_16x16x32_bf16 v[112:115], v[182:185], v[190:193], v[112:115]
	v_mfma_f32_16x16x32_bf16 v[100:103], v[174:177], v[198:201], v[100:103]
	v_mfma_f32_16x16x32_bf16 v[96:99], v[182:185], v[198:201], v[96:99]
	v_mfma_f32_16x16x32_bf16 v[84:87], v[174:177], v[206:209], v[84:87]
	v_mfma_f32_16x16x32_bf16 v[80:83], v[182:185], v[206:209], v[80:83]
	v_mfma_f32_16x16x32_bf16 v[68:71], v[174:177], v[214:217], v[68:71]
	v_mfma_f32_16x16x32_bf16 v[64:67], v[182:185], v[214:217], v[64:67]
	v_mfma_f32_16x16x32_bf16 v[116:119], v[178:181], v[194:197], v[116:119]
	v_mfma_f32_16x16x32_bf16 v[112:115], v[186:189], v[194:197], v[112:115]
	v_mfma_f32_16x16x32_bf16 v[100:103], v[178:181], v[202:205], v[100:103]
	v_mfma_f32_16x16x32_bf16 v[96:99], v[186:189], v[202:205], v[96:99]
	v_mfma_f32_16x16x32_bf16 v[84:87], v[178:181], v[210:213], v[84:87]
	v_mfma_f32_16x16x32_bf16 v[80:83], v[186:189], v[210:213], v[80:83]
	v_mfma_f32_16x16x32_bf16 v[68:71], v[178:181], v[218:221], v[68:71]
	v_mfma_f32_16x16x32_bf16 v[64:67], v[186:189], v[218:221], v[64:67]
	s_setprio 0
	s_barrier
	s_add_i32 s10, s10, s58
	s_mov_b32 m0, s10
	ds_read_b128 v[190:193], v172 offset:49152
	ds_read_b128 v[194:197], v172 offset:50176
	ds_read_b128 v[198:201], v172 offset:51200
	global_load_lds_dwordx4 v146, s[52:53]
	s_add_i32 m0, s10, 0x2000
	ds_read_b128 v[202:205], v172 offset:52224
	global_load_lds_dwordx4 v150, s[52:53]
	s_add_u32 s52, s52, 0x40000
	s_addc_u32 s53, s53, 0
	s_add_i32 s10, s83, s58
	s_mov_b32 m0, s10
	ds_read_b128 v[206:209], v172 offset:53248
	global_load_lds_dwordx4 v146, s[52:53]
	s_add_i32 m0, s10, 0x2000
	ds_read_b128 v[210:213], v172 offset:54272
	global_load_lds_dwordx4 v150, s[52:53]
	s_mov_b32 m0, s68
	ds_read_b128 v[214:217], v172 offset:55296
	global_load_lds_dwordx4 v144, s[50:51]
	s_mov_b32 m0, s69
	ds_read_b128 v[218:221], v172 offset:56320
	global_load_lds_dwordx4 v148, s[50:51]
	s_waitcnt vmcnt(8)
	s_waitcnt lgkmcnt(0)
	s_setprio 1
	s_barrier
	v_mfma_f32_16x16x32_bf16 v[60:63], v[132:135], v[190:193], v[60:63]
	v_mfma_f32_16x16x32_bf16 v[56:59], v[140:143], v[190:193], v[56:59]
	v_mfma_f32_16x16x32_bf16 v[44:47], v[132:135], v[198:201], v[44:47]
	v_mfma_f32_16x16x32_bf16 v[40:43], v[140:143], v[198:201], v[40:43]
	v_mfma_f32_16x16x32_bf16 v[28:31], v[132:135], v[206:209], v[28:31]
	v_mfma_f32_16x16x32_bf16 v[24:27], v[140:143], v[206:209], v[24:27]
	v_mfma_f32_16x16x32_bf16 v[12:15], v[132:135], v[214:217], v[12:15]
	v_mfma_f32_16x16x32_bf16 v[8:11], v[140:143], v[214:217], v[8:11]
	v_mfma_f32_16x16x32_bf16 v[60:63], v[136:139], v[194:197], v[60:63]
	v_mfma_f32_16x16x32_bf16 v[56:59], v[164:167], v[194:197], v[56:59]
	v_mfma_f32_16x16x32_bf16 v[44:47], v[136:139], v[202:205], v[44:47]
	v_mfma_f32_16x16x32_bf16 v[40:43], v[164:167], v[202:205], v[40:43]
	v_mfma_f32_16x16x32_bf16 v[28:31], v[136:139], v[210:213], v[28:31]
	v_mfma_f32_16x16x32_bf16 v[24:27], v[164:167], v[210:213], v[24:27]
	v_mfma_f32_16x16x32_bf16 v[12:15], v[136:139], v[218:221], v[12:15]
	v_mfma_f32_16x16x32_bf16 v[8:11], v[164:167], v[218:221], v[8:11]
	s_setprio 0
	s_setprio 1
	v_mfma_f32_16x16x32_bf16 v[52:55], v[174:177], v[190:193], v[52:55]
	v_mfma_f32_16x16x32_bf16 v[48:51], v[182:185], v[190:193], v[48:51]
	v_mfma_f32_16x16x32_bf16 v[36:39], v[174:177], v[198:201], v[36:39]
	v_mfma_f32_16x16x32_bf16 v[32:35], v[182:185], v[198:201], v[32:35]
	v_mfma_f32_16x16x32_bf16 v[20:23], v[174:177], v[206:209], v[20:23]
	v_mfma_f32_16x16x32_bf16 v[16:19], v[182:185], v[206:209], v[16:19]
	v_mfma_f32_16x16x32_bf16 v[4:7], v[174:177], v[214:217], v[4:7]
	v_mfma_f32_16x16x32_bf16 v[0:3], v[182:185], v[214:217], v[0:3]
	v_mfma_f32_16x16x32_bf16 v[52:55], v[178:181], v[194:197], v[52:55]
	v_mfma_f32_16x16x32_bf16 v[48:51], v[186:189], v[194:197], v[48:51]
	v_mfma_f32_16x16x32_bf16 v[36:39], v[178:181], v[202:205], v[36:39]
	v_mfma_f32_16x16x32_bf16 v[32:35], v[186:189], v[202:205], v[32:35]
	v_mfma_f32_16x16x32_bf16 v[20:23], v[178:181], v[210:213], v[20:23]
	v_mfma_f32_16x16x32_bf16 v[16:19], v[186:189], v[210:213], v[16:19]
	v_mfma_f32_16x16x32_bf16 v[4:7], v[178:181], v[218:221], v[4:7]
	v_mfma_f32_16x16x32_bf16 v[0:3], v[186:189], v[218:221], v[0:3]
	s_setprio 0
	s_barrier
	s_add_i32 s10, s82, 2
	s_add_u32 s48, s48, 0x100
	s_addc_u32 s49, s49, 0
	s_cmp_gt_u32 s82, 13
	s_mov_b32 s82, s10
	s_cbranch_scc1 .LBB0_721
	s_branch .LBB0_715
.LBB0_714:
	v_add_u32_e32 v164, s72, v171
	v_add_u32_e32 v168, s73, v171
	ds_read_b128 v[132:135], v164
	ds_read_b128 v[136:139], v164 offset:1024
	ds_read_b128 v[140:143], v164 offset:2048
	ds_read_b128 v[164:167], v164 offset:3072
	ds_read_b128 v[174:177], v168
	ds_read_b128 v[178:181], v168 offset:1024
	ds_read_b128 v[182:185], v168 offset:2048
	ds_read_b128 v[186:189], v168 offset:3072
	s_add_u32 s10, s56, 0x100
	s_addc_u32 s85, s57, 0
	s_and_b64 s[56:57], exec, s[54:55]
	s_cselect_b32 s57, s23, s85
	s_cselect_b32 s56, s80, s10
	s_add_u32 s10, s84, 0x100
	s_addc_u32 s83, s83, 0
	s_and_b64 s[54:55], exec, s[54:55]
	s_cselect_b32 s55, s21, s83
	s_cselect_b32 s54, s81, s10
	v_lshl_add_u64 v[168:169], v[128:129], 0, s[48:49]
	s_add_i32 m0, s59, 0xc000
	ds_read_b128 v[190:193], v172
	ds_read_b128 v[194:197], v172 offset:1024
	ds_read_b128 v[198:201], v172 offset:2048
	ds_read_b128 v[202:205], v172 offset:3072
	ds_read_b128 v[206:209], v172 offset:4096
	ds_read_b128 v[210:213], v172 offset:5120
	ds_read_b128 v[214:217], v172 offset:6144
	global_load_lds_dwordx4 v[168:169], off
	v_lshl_add_u64 v[168:169], v[130:131], 0, s[48:49]
	s_add_i32 m0, s59, 0xe000
	ds_read_b128 v[218:221], v172 offset:7168
	global_load_lds_dwordx4 v[168:169], off
	s_waitcnt vmcnt(8)
	s_waitcnt lgkmcnt(0)
	s_setprio 1
	s_barrier
	v_mfma_f32_16x16x32_bf16 v[124:127], v[132:135], v[190:193], v[124:127]
	v_mfma_f32_16x16x32_bf16 v[120:123], v[140:143], v[190:193], v[120:123]
	v_mfma_f32_16x16x32_bf16 v[108:111], v[132:135], v[198:201], v[108:111]
	v_mfma_f32_16x16x32_bf16 v[104:107], v[140:143], v[198:201], v[104:107]
	v_mfma_f32_16x16x32_bf16 v[92:95], v[132:135], v[206:209], v[92:95]
	v_mfma_f32_16x16x32_bf16 v[88:91], v[140:143], v[206:209], v[88:91]
	v_mfma_f32_16x16x32_bf16 v[76:79], v[132:135], v[214:217], v[76:79]
	v_mfma_f32_16x16x32_bf16 v[72:75], v[140:143], v[214:217], v[72:75]
	v_mfma_f32_16x16x32_bf16 v[124:127], v[136:139], v[194:197], v[124:127]
	v_mfma_f32_16x16x32_bf16 v[120:123], v[164:167], v[194:197], v[120:123]
	v_mfma_f32_16x16x32_bf16 v[108:111], v[136:139], v[202:205], v[108:111]
	v_mfma_f32_16x16x32_bf16 v[104:107], v[164:167], v[202:205], v[104:107]
	v_mfma_f32_16x16x32_bf16 v[92:95], v[136:139], v[210:213], v[92:95]
	v_mfma_f32_16x16x32_bf16 v[88:91], v[164:167], v[210:213], v[88:91]
	v_mfma_f32_16x16x32_bf16 v[76:79], v[136:139], v[218:221], v[76:79]
	v_mfma_f32_16x16x32_bf16 v[72:75], v[164:167], v[218:221], v[72:75]
	s_setprio 0
	s_setprio 1
	v_mfma_f32_16x16x32_bf16 v[116:119], v[174:177], v[190:193], v[116:119]
	v_mfma_f32_16x16x32_bf16 v[112:115], v[182:185], v[190:193], v[112:115]
	v_mfma_f32_16x16x32_bf16 v[100:103], v[174:177], v[198:201], v[100:103]
	v_mfma_f32_16x16x32_bf16 v[96:99], v[182:185], v[198:201], v[96:99]
	v_mfma_f32_16x16x32_bf16 v[84:87], v[174:177], v[206:209], v[84:87]
	v_mfma_f32_16x16x32_bf16 v[80:83], v[182:185], v[206:209], v[80:83]
	v_mfma_f32_16x16x32_bf16 v[68:71], v[174:177], v[214:217], v[68:71]
	v_mfma_f32_16x16x32_bf16 v[64:67], v[182:185], v[214:217], v[64:67]
	v_mfma_f32_16x16x32_bf16 v[116:119], v[178:181], v[194:197], v[116:119]
	v_mfma_f32_16x16x32_bf16 v[112:115], v[186:189], v[194:197], v[112:115]
	v_mfma_f32_16x16x32_bf16 v[100:103], v[178:181], v[202:205], v[100:103]
	v_mfma_f32_16x16x32_bf16 v[96:99], v[186:189], v[202:205], v[96:99]
	v_mfma_f32_16x16x32_bf16 v[84:87], v[178:181], v[210:213], v[84:87]
	v_mfma_f32_16x16x32_bf16 v[80:83], v[186:189], v[210:213], v[80:83]
	v_mfma_f32_16x16x32_bf16 v[68:71], v[178:181], v[218:221], v[68:71]
	v_mfma_f32_16x16x32_bf16 v[64:67], v[186:189], v[218:221], v[64:67]
	s_setprio 0
	s_barrier
	s_add_i32 s10, s72, s58
	s_mov_b32 m0, s10
	ds_read_b128 v[190:193], v172 offset:16384
	ds_read_b128 v[194:197], v172 offset:17408
	ds_read_b128 v[198:201], v172 offset:18432
	global_load_lds_dwordx4 v146, s[54:55]
	s_add_i32 m0, s10, 0x2000
	ds_read_b128 v[202:205], v172 offset:19456
	global_load_lds_dwordx4 v150, s[54:55]
	s_add_u32 s54, s54, 0x40000
	s_addc_u32 s55, s55, 0
	s_add_i32 s10, s73, s58
	s_mov_b32 m0, s10
	ds_read_b128 v[206:209], v172 offset:20480
	global_load_lds_dwordx4 v146, s[54:55]
	s_add_i32 m0, s10, 0x2000
	ds_read_b128 v[210:213], v172 offset:21504
	global_load_lds_dwordx4 v150, s[54:55]
	s_mov_b32 m0, s59
	ds_read_b128 v[214:217], v172 offset:22528
	global_load_lds_dwordx4 v144, s[56:57]
	s_mov_b32 m0, s60
	ds_read_b128 v[218:221], v172 offset:23552
	global_load_lds_dwordx4 v148, s[56:57]
	s_waitcnt vmcnt(8)
	s_waitcnt lgkmcnt(0)
	s_setprio 1
	s_barrier
	v_mfma_f32_16x16x32_bf16 v[60:63], v[132:135], v[190:193], v[60:63]
	v_mfma_f32_16x16x32_bf16 v[56:59], v[140:143], v[190:193], v[56:59]
	v_mfma_f32_16x16x32_bf16 v[44:47], v[132:135], v[198:201], v[44:47]
	v_mfma_f32_16x16x32_bf16 v[40:43], v[140:143], v[198:201], v[40:43]
	v_mfma_f32_16x16x32_bf16 v[28:31], v[132:135], v[206:209], v[28:31]
	v_mfma_f32_16x16x32_bf16 v[24:27], v[140:143], v[206:209], v[24:27]
	v_mfma_f32_16x16x32_bf16 v[12:15], v[132:135], v[214:217], v[12:15]
	v_mfma_f32_16x16x32_bf16 v[8:11], v[140:143], v[214:217], v[8:11]
	v_mfma_f32_16x16x32_bf16 v[60:63], v[136:139], v[194:197], v[60:63]
	v_mfma_f32_16x16x32_bf16 v[56:59], v[164:167], v[194:197], v[56:59]
	v_mfma_f32_16x16x32_bf16 v[44:47], v[136:139], v[202:205], v[44:47]
	v_mfma_f32_16x16x32_bf16 v[40:43], v[164:167], v[202:205], v[40:43]
	v_mfma_f32_16x16x32_bf16 v[28:31], v[136:139], v[210:213], v[28:31]
	v_mfma_f32_16x16x32_bf16 v[24:27], v[164:167], v[210:213], v[24:27]
	v_mfma_f32_16x16x32_bf16 v[12:15], v[136:139], v[218:221], v[12:15]
	v_mfma_f32_16x16x32_bf16 v[8:11], v[164:167], v[218:221], v[8:11]
	s_setprio 0
	s_setprio 1
	v_mfma_f32_16x16x32_bf16 v[52:55], v[174:177], v[190:193], v[52:55]
	v_mfma_f32_16x16x32_bf16 v[48:51], v[182:185], v[190:193], v[48:51]
	v_mfma_f32_16x16x32_bf16 v[36:39], v[174:177], v[198:201], v[36:39]
	v_mfma_f32_16x16x32_bf16 v[32:35], v[182:185], v[198:201], v[32:35]
	v_mfma_f32_16x16x32_bf16 v[20:23], v[174:177], v[206:209], v[20:23]
	v_mfma_f32_16x16x32_bf16 v[16:19], v[182:185], v[206:209], v[16:19]
	v_mfma_f32_16x16x32_bf16 v[4:7], v[174:177], v[214:217], v[4:7]
	v_mfma_f32_16x16x32_bf16 v[0:3], v[182:185], v[214:217], v[0:3]
	v_mfma_f32_16x16x32_bf16 v[52:55], v[178:181], v[194:197], v[52:55]
	v_mfma_f32_16x16x32_bf16 v[48:51], v[186:189], v[194:197], v[48:51]
	v_mfma_f32_16x16x32_bf16 v[36:39], v[178:181], v[202:205], v[36:39]
	v_mfma_f32_16x16x32_bf16 v[32:35], v[186:189], v[202:205], v[32:35]
	v_mfma_f32_16x16x32_bf16 v[20:23], v[178:181], v[210:213], v[20:23]
	v_mfma_f32_16x16x32_bf16 v[16:19], v[186:189], v[210:213], v[16:19]
	v_mfma_f32_16x16x32_bf16 v[4:7], v[178:181], v[218:221], v[4:7]
	v_mfma_f32_16x16x32_bf16 v[0:3], v[186:189], v[218:221], v[0:3]
	s_setprio 0
	s_barrier
	s_add_i32 s10, 0, 0x18000
	s_add_i32 s83, 0, 0x1c000
	v_add_u32_e32 v164, s10, v171
	v_add_u32_e32 v168, s83, v171
	ds_read_b128 v[132:135], v164
	ds_read_b128 v[136:139], v164 offset:1024
	ds_read_b128 v[140:143], v164 offset:2048
	ds_read_b128 v[164:167], v164 offset:3072
	ds_read_b128 v[174:177], v168
	ds_read_b128 v[178:181], v168 offset:1024
	ds_read_b128 v[182:185], v168 offset:2048
	ds_read_b128 v[186:189], v168 offset:3072
	s_add_u32 s54, s56, 0x40000
	s_addc_u32 s55, s57, 0
	s_mov_b32 m0, s61
	ds_read_b128 v[190:193], v172 offset:32768
	ds_read_b128 v[194:197], v172 offset:33792
	ds_read_b128 v[198:201], v172 offset:34816
	ds_read_b128 v[202:205], v172 offset:35840
	ds_read_b128 v[206:209], v172 offset:36864
	ds_read_b128 v[210:213], v172 offset:37888
	ds_read_b128 v[214:217], v172 offset:38912
	global_load_lds_dwordx4 v144, s[54:55]
	s_mov_b32 m0, s62
	ds_read_b128 v[218:221], v172 offset:39936
	global_load_lds_dwordx4 v148, s[54:55]
	s_waitcnt vmcnt(8)
	s_waitcnt lgkmcnt(0)
	s_setprio 1
	s_barrier
	v_mfma_f32_16x16x32_bf16 v[124:127], v[132:135], v[190:193], v[124:127]
	v_mfma_f32_16x16x32_bf16 v[120:123], v[140:143], v[190:193], v[120:123]
	v_mfma_f32_16x16x32_bf16 v[108:111], v[132:135], v[198:201], v[108:111]
	v_mfma_f32_16x16x32_bf16 v[104:107], v[140:143], v[198:201], v[104:107]
	v_mfma_f32_16x16x32_bf16 v[92:95], v[132:135], v[206:209], v[92:95]
	v_mfma_f32_16x16x32_bf16 v[88:91], v[140:143], v[206:209], v[88:91]
	v_mfma_f32_16x16x32_bf16 v[76:79], v[132:135], v[214:217], v[76:79]
	v_mfma_f32_16x16x32_bf16 v[72:75], v[140:143], v[214:217], v[72:75]
	v_mfma_f32_16x16x32_bf16 v[124:127], v[136:139], v[194:197], v[124:127]
	v_mfma_f32_16x16x32_bf16 v[120:123], v[164:167], v[194:197], v[120:123]
	v_mfma_f32_16x16x32_bf16 v[108:111], v[136:139], v[202:205], v[108:111]
	v_mfma_f32_16x16x32_bf16 v[104:107], v[164:167], v[202:205], v[104:107]
	v_mfma_f32_16x16x32_bf16 v[92:95], v[136:139], v[210:213], v[92:95]
	v_mfma_f32_16x16x32_bf16 v[88:91], v[164:167], v[210:213], v[88:91]
	v_mfma_f32_16x16x32_bf16 v[76:79], v[136:139], v[218:221], v[76:79]
	v_mfma_f32_16x16x32_bf16 v[72:75], v[164:167], v[218:221], v[72:75]
	s_setprio 0
	s_setprio 1
	v_mfma_f32_16x16x32_bf16 v[116:119], v[174:177], v[190:193], v[116:119]
	v_mfma_f32_16x16x32_bf16 v[112:115], v[182:185], v[190:193], v[112:115]
	v_mfma_f32_16x16x32_bf16 v[100:103], v[174:177], v[198:201], v[100:103]
	v_mfma_f32_16x16x32_bf16 v[96:99], v[182:185], v[198:201], v[96:99]
	v_mfma_f32_16x16x32_bf16 v[84:87], v[174:177], v[206:209], v[84:87]
	v_mfma_f32_16x16x32_bf16 v[80:83], v[182:185], v[206:209], v[80:83]
	v_mfma_f32_16x16x32_bf16 v[68:71], v[174:177], v[214:217], v[68:71]
	v_mfma_f32_16x16x32_bf16 v[64:67], v[182:185], v[214:217], v[64:67]
	v_mfma_f32_16x16x32_bf16 v[116:119], v[178:181], v[194:197], v[116:119]
	v_mfma_f32_16x16x32_bf16 v[112:115], v[186:189], v[194:197], v[112:115]
	v_mfma_f32_16x16x32_bf16 v[100:103], v[178:181], v[202:205], v[100:103]
	v_mfma_f32_16x16x32_bf16 v[96:99], v[186:189], v[202:205], v[96:99]
	v_mfma_f32_16x16x32_bf16 v[84:87], v[178:181], v[210:213], v[84:87]
	v_mfma_f32_16x16x32_bf16 v[80:83], v[186:189], v[210:213], v[80:83]
	v_mfma_f32_16x16x32_bf16 v[68:71], v[178:181], v[218:221], v[68:71]
	v_mfma_f32_16x16x32_bf16 v[64:67], v[186:189], v[218:221], v[64:67]
	s_setprio 0
	s_barrier
	s_add_i32 s10, s10, s58
	s_mov_b32 m0, s10
	ds_read_b128 v[190:193], v172 offset:49152
	ds_read_b128 v[194:197], v172 offset:50176
	ds_read_b128 v[198:201], v172 offset:51200
	global_load_lds_dwordx4 v146, s[52:53]
	s_add_i32 m0, s10, 0x2000
	ds_read_b128 v[202:205], v172 offset:52224
	global_load_lds_dwordx4 v150, s[52:53]
	s_add_u32 s52, s52, 0x40000
	s_addc_u32 s53, s53, 0
	s_add_i32 s10, s83, s58
	s_mov_b32 m0, s10
	ds_read_b128 v[206:209], v172 offset:53248
	global_load_lds_dwordx4 v146, s[52:53]
	s_add_i32 m0, s10, 0x2000
	ds_read_b128 v[210:213], v172 offset:54272
	global_load_lds_dwordx4 v150, s[52:53]
	s_mov_b32 m0, s68
	ds_read_b128 v[214:217], v172 offset:55296
	global_load_lds_dwordx4 v144, s[50:51]
	s_mov_b32 m0, s69
	ds_read_b128 v[218:221], v172 offset:56320
	global_load_lds_dwordx4 v148, s[50:51]
	s_waitcnt vmcnt(8)
	s_waitcnt lgkmcnt(0)
	s_setprio 1
	s_barrier
	v_mfma_f32_16x16x32_bf16 v[60:63], v[132:135], v[190:193], v[60:63]
	v_mfma_f32_16x16x32_bf16 v[56:59], v[140:143], v[190:193], v[56:59]
	v_mfma_f32_16x16x32_bf16 v[44:47], v[132:135], v[198:201], v[44:47]
	v_mfma_f32_16x16x32_bf16 v[40:43], v[140:143], v[198:201], v[40:43]
	v_mfma_f32_16x16x32_bf16 v[28:31], v[132:135], v[206:209], v[28:31]
	v_mfma_f32_16x16x32_bf16 v[24:27], v[140:143], v[206:209], v[24:27]
	v_mfma_f32_16x16x32_bf16 v[12:15], v[132:135], v[214:217], v[12:15]
	v_mfma_f32_16x16x32_bf16 v[8:11], v[140:143], v[214:217], v[8:11]
	v_mfma_f32_16x16x32_bf16 v[60:63], v[136:139], v[194:197], v[60:63]
	v_mfma_f32_16x16x32_bf16 v[56:59], v[164:167], v[194:197], v[56:59]
	v_mfma_f32_16x16x32_bf16 v[44:47], v[136:139], v[202:205], v[44:47]
	v_mfma_f32_16x16x32_bf16 v[40:43], v[164:167], v[202:205], v[40:43]
	v_mfma_f32_16x16x32_bf16 v[28:31], v[136:139], v[210:213], v[28:31]
	v_mfma_f32_16x16x32_bf16 v[24:27], v[164:167], v[210:213], v[24:27]
	v_mfma_f32_16x16x32_bf16 v[12:15], v[136:139], v[218:221], v[12:15]
	v_mfma_f32_16x16x32_bf16 v[8:11], v[164:167], v[218:221], v[8:11]
	s_setprio 0
	s_setprio 1
	v_mfma_f32_16x16x32_bf16 v[52:55], v[174:177], v[190:193], v[52:55]
	v_mfma_f32_16x16x32_bf16 v[48:51], v[182:185], v[190:193], v[48:51]
	v_mfma_f32_16x16x32_bf16 v[36:39], v[174:177], v[198:201], v[36:39]
	v_mfma_f32_16x16x32_bf16 v[32:35], v[182:185], v[198:201], v[32:35]
	v_mfma_f32_16x16x32_bf16 v[20:23], v[174:177], v[206:209], v[20:23]
	v_mfma_f32_16x16x32_bf16 v[16:19], v[182:185], v[206:209], v[16:19]
	v_mfma_f32_16x16x32_bf16 v[4:7], v[174:177], v[214:217], v[4:7]
	v_mfma_f32_16x16x32_bf16 v[0:3], v[182:185], v[214:217], v[0:3]
	v_mfma_f32_16x16x32_bf16 v[52:55], v[178:181], v[194:197], v[52:55]
	v_mfma_f32_16x16x32_bf16 v[48:51], v[186:189], v[194:197], v[48:51]
	v_mfma_f32_16x16x32_bf16 v[36:39], v[178:181], v[202:205], v[36:39]
	v_mfma_f32_16x16x32_bf16 v[32:35], v[186:189], v[202:205], v[32:35]
	v_mfma_f32_16x16x32_bf16 v[20:23], v[178:181], v[210:213], v[20:23]
	v_mfma_f32_16x16x32_bf16 v[16:19], v[186:189], v[210:213], v[16:19]
	v_mfma_f32_16x16x32_bf16 v[4:7], v[178:181], v[218:221], v[4:7]
	v_mfma_f32_16x16x32_bf16 v[0:3], v[186:189], v[218:221], v[0:3]
	s_setprio 0
	s_barrier
	s_add_i32 s10, s82, 2
	s_add_u32 s48, s48, 0x100
	s_addc_u32 s49, s49, 0
	s_cmp_gt_u32 s82, 13
	s_mov_b32 s82, s10
	s_cbranch_scc1 .LBB0_721

.LBB0_805:
	s_add_u32 s27, s61, s4
	s_addc_u32 s72, s62, s5
	s_add_u32 s73, s63, s6
	s_addc_u32 s78, s64, s7
	s_ashr_i32 s21, s20, 31
	s_lshl_b64 s[4:5], s[20:21], 19
	s_add_u32 s22, s40, s4
	s_addc_u32 s23, s41, s5
	s_and_b64 s[6:7], s[0:1], exec
	s_cselect_b32 s21, s23, s31
	s_cselect_b32 s79, s22, s30
	s_ashr_i32 s19, s18, 31
	s_lshl_b64 s[6:7], s[18:19], 19
	s_add_u32 s24, s42, s6
	s_addc_u32 s25, s43, s7
	s_and_b64 s[36:37], s[0:1], exec
	s_cselect_b32 s19, s25, s29
	s_cselect_b32 s80, s24, s28
	s_add_u32 s36, s79, 0x80
	s_addc_u32 s37, s21, 0
	s_add_u32 s38, s80, 0x80
	s_addc_u32 s39, s19, 0
	v_lshl_add_u64 v[148:149], s[30:31], 0, v[140:141]
	v_lshl_add_u64 v[150:151], s[30:31], 0, v[142:143]
	s_mov_b32 s81, 0
	s_mov_b64 s[44:45], 0
	s_cmpk_eq_i32 s44, 0x700
	s_cselect_b64 s[50:51], -1, 0
	s_add_u32 s52, s30, s44
	s_addc_u32 s53, s31, s45
	s_add_u32 s83, s28, s44
	s_addc_u32 s82, s29, s45
	s_add_u32 s46, s52, 0x180
	s_addc_u32 s47, s53, 0
	s_add_u32 s48, s83, 0x180
	s_addc_u32 s49, s82, 0
	s_cmpk_eq_i32 s44, 0x700
	s_cselect_b32 s46, s36, s46
	s_cselect_b32 s47, s37, s47
	s_cselect_b32 s48, s38, s48
	s_cselect_b32 s49, s39, s49
	v_add_u32_e32 v152, s68, v157
	ds_read_b128 v[166:169], v152
	ds_read_b128 v[170:173], v152 offset:1024
	ds_read_b128 v[174:177], v152 offset:2048
	ds_read_b128 v[178:181], v152 offset:3072
	v_add_u32_e32 v152, s69, v157
	ds_read_b128 v[182:185], v152
	ds_read_b128 v[186:189], v152 offset:1024
	ds_read_b128 v[190:193], v152 offset:2048
	ds_read_b128 v[194:197], v152 offset:3072
	s_add_u32 s8, s52, 0x100
	s_addc_u32 s84, s53, 0
	s_and_b64 s[52:53], exec, s[50:51]
	s_cselect_b32 s53, s21, s84
	s_cselect_b32 s52, s79, s8
	s_add_u32 s8, s83, 0x100
	s_addc_u32 s82, s82, 0
	s_and_b64 s[50:51], exec, s[50:51]
	s_cselect_b32 s51, s19, s82
	s_cselect_b32 s50, s80, s8
	v_lshl_add_u64 v[154:155], v[148:149], 0, s[44:45]
	s_add_i32 m0, s57, 0xc000
	ds_read_b128 v[198:201], v161
	ds_read_b128 v[202:205], v161 offset:1024
	ds_read_b128 v[206:209], v161 offset:2048
	ds_read_b128 v[210:213], v161 offset:3072
	ds_read_b128 v[214:217], v161 offset:4096
	ds_read_b128 v[218:221], v161 offset:5120
	ds_read_b128 v[222:225], v161 offset:6144
	global_load_lds_dwordx4 v[154:155], off
	v_lshl_add_u64 v[154:155], v[150:151], 0, s[44:45]
	s_add_i32 m0, s57, 0xe000
	ds_read_b128 v[226:229], v161 offset:7168
	global_load_lds_dwordx4 v[154:155], off
	s_waitcnt vmcnt(8)
	s_waitcnt lgkmcnt(0)
	s_setprio 1
	s_barrier
	v_mfma_f32_16x16x32_bf16 v[124:127], v[166:169], v[198:201], 0
	v_mfma_f32_16x16x32_bf16 v[120:123], v[174:177], v[198:201], 0
	v_mfma_f32_16x16x32_bf16 v[108:111], v[166:169], v[206:209], 0
	v_mfma_f32_16x16x32_bf16 v[104:107], v[174:177], v[206:209], 0
	v_mfma_f32_16x16x32_bf16 v[92:95], v[166:169], v[214:217], 0
	v_mfma_f32_16x16x32_bf16 v[88:91], v[174:177], v[214:217], 0
	v_mfma_f32_16x16x32_bf16 v[76:79], v[166:169], v[222:225], 0
	v_mfma_f32_16x16x32_bf16 v[72:75], v[174:177], v[222:225], 0
	v_mfma_f32_16x16x32_bf16 v[124:127], v[170:173], v[202:205], v[124:127]
	v_mfma_f32_16x16x32_bf16 v[120:123], v[178:181], v[202:205], v[120:123]
	v_mfma_f32_16x16x32_bf16 v[108:111], v[170:173], v[210:213], v[108:111]
	v_mfma_f32_16x16x32_bf16 v[104:107], v[178:181], v[210:213], v[104:107]
	v_mfma_f32_16x16x32_bf16 v[92:95], v[170:173], v[218:221], v[92:95]
	v_mfma_f32_16x16x32_bf16 v[88:91], v[178:181], v[218:221], v[88:91]
	v_mfma_f32_16x16x32_bf16 v[76:79], v[170:173], v[226:229], v[76:79]
	v_mfma_f32_16x16x32_bf16 v[72:75], v[178:181], v[226:229], v[72:75]
	s_setprio 0
	s_setprio 1
	v_mfma_f32_16x16x32_bf16 v[116:119], v[182:185], v[198:201], 0
	v_mfma_f32_16x16x32_bf16 v[112:115], v[190:193], v[198:201], 0
	v_mfma_f32_16x16x32_bf16 v[100:103], v[182:185], v[206:209], 0
	v_mfma_f32_16x16x32_bf16 v[96:99], v[190:193], v[206:209], 0
	v_mfma_f32_16x16x32_bf16 v[84:87], v[182:185], v[214:217], 0
	v_mfma_f32_16x16x32_bf16 v[80:83], v[190:193], v[214:217], 0
	v_mfma_f32_16x16x32_bf16 v[68:71], v[182:185], v[222:225], 0
	v_mfma_f32_16x16x32_bf16 v[64:67], v[190:193], v[222:225], 0
	v_mfma_f32_16x16x32_bf16 v[116:119], v[186:189], v[202:205], v[116:119]
	v_mfma_f32_16x16x32_bf16 v[112:115], v[194:197], v[202:205], v[112:115]
	v_mfma_f32_16x16x32_bf16 v[100:103], v[186:189], v[210:213], v[100:103]
	v_mfma_f32_16x16x32_bf16 v[96:99], v[194:197], v[210:213], v[96:99]
	v_mfma_f32_16x16x32_bf16 v[84:87], v[186:189], v[218:221], v[84:87]
	v_mfma_f32_16x16x32_bf16 v[80:83], v[194:197], v[218:221], v[80:83]
	v_mfma_f32_16x16x32_bf16 v[68:71], v[186:189], v[226:229], v[68:71]
	v_mfma_f32_16x16x32_bf16 v[64:67], v[194:197], v[226:229], v[64:67]
	s_setprio 0
	s_barrier
	s_add_i32 s8, s68, s54
	s_mov_b32 m0, s8
	ds_read_b128 v[198:201], v161 offset:16384
	ds_read_b128 v[202:205], v161 offset:17408
	ds_read_b128 v[206:209], v161 offset:18432
	global_load_lds_dwordx4 v128, s[50:51]
	s_add_i32 m0, s8, 0x2000
	ds_read_b128 v[210:213], v161 offset:19456
	global_load_lds_dwordx4 v130, s[50:51]
	s_add_u32 s50, s50, 0x40000
	s_addc_u32 s51, s51, 0
	s_add_i32 s8, s69, s54
	s_mov_b32 m0, s8
	ds_read_b128 v[214:217], v161 offset:20480
	global_load_lds_dwordx4 v128, s[50:51]
	s_add_i32 m0, s8, 0x2000
	ds_read_b128 v[218:221], v161 offset:21504
	global_load_lds_dwordx4 v130, s[50:51]
	s_mov_b32 m0, s57
	ds_read_b128 v[222:225], v161 offset:22528
	global_load_lds_dwordx4 v134, s[52:53]
	s_mov_b32 m0, s58
	ds_read_b128 v[226:229], v161 offset:23552
	global_load_lds_dwordx4 v132, s[52:53]
	s_waitcnt vmcnt(8)
	s_waitcnt lgkmcnt(0)
	s_setprio 1
	s_barrier
	v_mfma_f32_16x16x32_bf16 v[60:63], v[166:169], v[198:201], 0
	v_mfma_f32_16x16x32_bf16 v[56:59], v[174:177], v[198:201], 0
	v_mfma_f32_16x16x32_bf16 v[44:47], v[166:169], v[206:209], 0
	v_mfma_f32_16x16x32_bf16 v[40:43], v[174:177], v[206:209], 0
	v_mfma_f32_16x16x32_bf16 v[28:31], v[166:169], v[214:217], 0
	v_mfma_f32_16x16x32_bf16 v[24:27], v[174:177], v[214:217], 0
	v_mfma_f32_16x16x32_bf16 v[12:15], v[166:169], v[222:225], 0
	v_mfma_f32_16x16x32_bf16 v[8:11], v[174:177], v[222:225], 0
	v_mfma_f32_16x16x32_bf16 v[60:63], v[170:173], v[202:205], v[60:63]
	v_mfma_f32_16x16x32_bf16 v[56:59], v[178:181], v[202:205], v[56:59]
	v_mfma_f32_16x16x32_bf16 v[44:47], v[170:173], v[210:213], v[44:47]
	v_mfma_f32_16x16x32_bf16 v[40:43], v[178:181], v[210:213], v[40:43]
	v_mfma_f32_16x16x32_bf16 v[28:31], v[170:173], v[218:221], v[28:31]
	v_mfma_f32_16x16x32_bf16 v[24:27], v[178:181], v[218:221], v[24:27]
	v_mfma_f32_16x16x32_bf16 v[12:15], v[170:173], v[226:229], v[12:15]
	v_mfma_f32_16x16x32_bf16 v[8:11], v[178:181], v[226:229], v[8:11]
	s_setprio 0
	s_setprio 1
	v_mfma_f32_16x16x32_bf16 v[52:55], v[182:185], v[198:201], 0
	v_mfma_f32_16x16x32_bf16 v[48:51], v[190:193], v[198:201], 0
	v_mfma_f32_16x16x32_bf16 v[36:39], v[182:185], v[206:209], 0
	v_mfma_f32_16x16x32_bf16 v[32:35], v[190:193], v[206:209], 0
	v_mfma_f32_16x16x32_bf16 v[20:23], v[182:185], v[214:217], 0
	v_mfma_f32_16x16x32_bf16 v[16:19], v[190:193], v[214:217], 0
	v_mfma_f32_16x16x32_bf16 v[4:7], v[182:185], v[222:225], 0
	v_mfma_f32_16x16x32_bf16 v[0:3], v[190:193], v[222:225], 0
	v_mfma_f32_16x16x32_bf16 v[52:55], v[186:189], v[202:205], v[52:55]
	v_mfma_f32_16x16x32_bf16 v[48:51], v[194:197], v[202:205], v[48:51]
	v_mfma_f32_16x16x32_bf16 v[36:39], v[186:189], v[210:213], v[36:39]
	v_mfma_f32_16x16x32_bf16 v[32:35], v[194:197], v[210:213], v[32:35]
	v_mfma_f32_16x16x32_bf16 v[20:23], v[186:189], v[218:221], v[20:23]
	v_mfma_f32_16x16x32_bf16 v[16:19], v[194:197], v[218:221], v[16:19]
	v_mfma_f32_16x16x32_bf16 v[4:7], v[186:189], v[226:229], v[4:7]
	v_mfma_f32_16x16x32_bf16 v[0:3], v[194:197], v[226:229], v[0:3]
	s_setprio 0
	s_barrier
	s_add_i32 s8, 0, 0x18000
	v_add_u32_e32 v152, s8, v157
	s_add_i32 s82, 0, 0x1c000
	ds_read_b128 v[166:169], v152
	ds_read_b128 v[170:173], v152 offset:1024
	ds_read_b128 v[174:177], v152 offset:2048
	ds_read_b128 v[178:181], v152 offset:3072
	v_add_u32_e32 v152, s82, v157
	ds_read_b128 v[182:185], v152
	ds_read_b128 v[186:189], v152 offset:1024
	ds_read_b128 v[190:193], v152 offset:2048
	ds_read_b128 v[194:197], v152 offset:3072
	s_add_u32 s50, s52, 0x40000
	s_addc_u32 s51, s53, 0
	s_mov_b32 m0, s59
	ds_read_b128 v[198:201], v161 offset:32768
	ds_read_b128 v[202:205], v161 offset:33792
	ds_read_b128 v[206:209], v161 offset:34816
	ds_read_b128 v[210:213], v161 offset:35840
	ds_read_b128 v[214:217], v161 offset:36864
	ds_read_b128 v[218:221], v161 offset:37888
	ds_read_b128 v[222:225], v161 offset:38912
	global_load_lds_dwordx4 v134, s[50:51]
	s_mov_b32 m0, s60
	ds_read_b128 v[226:229], v161 offset:39936
	global_load_lds_dwordx4 v132, s[50:51]
	s_waitcnt vmcnt(8)
	s_waitcnt lgkmcnt(0)
	s_setprio 1
	s_barrier
	v_mfma_f32_16x16x32_bf16 v[124:127], v[166:169], v[198:201], v[124:127]
	v_mfma_f32_16x16x32_bf16 v[120:123], v[174:177], v[198:201], v[120:123]
	v_mfma_f32_16x16x32_bf16 v[108:111], v[166:169], v[206:209], v[108:111]
	v_mfma_f32_16x16x32_bf16 v[104:107], v[174:177], v[206:209], v[104:107]
	v_mfma_f32_16x16x32_bf16 v[92:95], v[166:169], v[214:217], v[92:95]
	v_mfma_f32_16x16x32_bf16 v[88:91], v[174:177], v[214:217], v[88:91]
	v_mfma_f32_16x16x32_bf16 v[76:79], v[166:169], v[222:225], v[76:79]
	v_mfma_f32_16x16x32_bf16 v[72:75], v[174:177], v[222:225], v[72:75]
	v_mfma_f32_16x16x32_bf16 v[124:127], v[170:173], v[202:205], v[124:127]
	v_mfma_f32_16x16x32_bf16 v[120:123], v[178:181], v[202:205], v[120:123]
	v_mfma_f32_16x16x32_bf16 v[108:111], v[170:173], v[210:213], v[108:111]
	v_mfma_f32_16x16x32_bf16 v[104:107], v[178:181], v[210:213], v[104:107]
	v_mfma_f32_16x16x32_bf16 v[92:95], v[170:173], v[218:221], v[92:95]
	v_mfma_f32_16x16x32_bf16 v[88:91], v[178:181], v[218:221], v[88:91]
	v_mfma_f32_16x16x32_bf16 v[76:79], v[170:173], v[226:229], v[76:79]
	v_mfma_f32_16x16x32_bf16 v[72:75], v[178:181], v[226:229], v[72:75]
	s_setprio 0
	s_setprio 1
	v_mfma_f32_16x16x32_bf16 v[116:119], v[182:185], v[198:201], v[116:119]
	v_mfma_f32_16x16x32_bf16 v[112:115], v[190:193], v[198:201], v[112:115]
	v_mfma_f32_16x16x32_bf16 v[100:103], v[182:185], v[206:209], v[100:103]
	v_mfma_f32_16x16x32_bf16 v[96:99], v[190:193], v[206:209], v[96:99]
	v_mfma_f32_16x16x32_bf16 v[84:87], v[182:185], v[214:217], v[84:87]
	v_mfma_f32_16x16x32_bf16 v[80:83], v[190:193], v[214:217], v[80:83]
	v_mfma_f32_16x16x32_bf16 v[68:71], v[182:185], v[222:225], v[68:71]
	v_mfma_f32_16x16x32_bf16 v[64:67], v[190:193], v[222:225], v[64:67]
	v_mfma_f32_16x16x32_bf16 v[116:119], v[186:189], v[202:205], v[116:119]
	v_mfma_f32_16x16x32_bf16 v[112:115], v[194:197], v[202:205], v[112:115]
	v_mfma_f32_16x16x32_bf16 v[100:103], v[186:189], v[210:213], v[100:103]
	v_mfma_f32_16x16x32_bf16 v[96:99], v[194:197], v[210:213], v[96:99]
	v_mfma_f32_16x16x32_bf16 v[84:87], v[186:189], v[218:221], v[84:87]
	v_mfma_f32_16x16x32_bf16 v[80:83], v[194:197], v[218:221], v[80:83]
	v_mfma_f32_16x16x32_bf16 v[68:71], v[186:189], v[226:229], v[68:71]
	v_mfma_f32_16x16x32_bf16 v[64:67], v[194:197], v[226:229], v[64:67]
	s_setprio 0
	s_barrier
	s_add_i32 s8, s8, s54
	s_mov_b32 m0, s8
	ds_read_b128 v[198:201], v161 offset:49152
	ds_read_b128 v[202:205], v161 offset:50176
	ds_read_b128 v[206:209], v161 offset:51200
	global_load_lds_dwordx4 v128, s[48:49]
	s_add_i32 m0, s8, 0x2000
	ds_read_b128 v[210:213], v161 offset:52224
	global_load_lds_dwordx4 v130, s[48:49]
	s_add_u32 s48, s48, 0x40000
	s_addc_u32 s49, s49, 0
	s_add_i32 s8, s82, s54
	s_mov_b32 m0, s8
	ds_read_b128 v[214:217], v161 offset:53248
	global_load_lds_dwordx4 v128, s[48:49]
	s_add_i32 m0, s8, 0x2000
	ds_read_b128 v[218:221], v161 offset:54272
	global_load_lds_dwordx4 v130, s[48:49]
	s_mov_b32 m0, s65
	ds_read_b128 v[222:225], v161 offset:55296
	global_load_lds_dwordx4 v134, s[46:47]
	s_mov_b32 m0, s66
	ds_read_b128 v[226:229], v161 offset:56320
	global_load_lds_dwordx4 v132, s[46:47]
	s_waitcnt vmcnt(8)
	s_waitcnt lgkmcnt(0)
	s_setprio 1
	s_barrier
	v_mfma_f32_16x16x32_bf16 v[60:63], v[166:169], v[198:201], v[60:63]
	v_mfma_f32_16x16x32_bf16 v[56:59], v[174:177], v[198:201], v[56:59]
	v_mfma_f32_16x16x32_bf16 v[44:47], v[166:169], v[206:209], v[44:47]
	v_mfma_f32_16x16x32_bf16 v[40:43], v[174:177], v[206:209], v[40:43]
	v_mfma_f32_16x16x32_bf16 v[28:31], v[166:169], v[214:217], v[28:31]
	v_mfma_f32_16x16x32_bf16 v[24:27], v[174:177], v[214:217], v[24:27]
	v_mfma_f32_16x16x32_bf16 v[12:15], v[166:169], v[222:225], v[12:15]
	v_mfma_f32_16x16x32_bf16 v[8:11], v[174:177], v[222:225], v[8:11]
	v_mfma_f32_16x16x32_bf16 v[60:63], v[170:173], v[202:205], v[60:63]
	v_mfma_f32_16x16x32_bf16 v[56:59], v[178:181], v[202:205], v[56:59]
	v_mfma_f32_16x16x32_bf16 v[44:47], v[170:173], v[210:213], v[44:47]
	v_mfma_f32_16x16x32_bf16 v[40:43], v[178:181], v[210:213], v[40:43]
	v_mfma_f32_16x16x32_bf16 v[28:31], v[170:173], v[218:221], v[28:31]
	v_mfma_f32_16x16x32_bf16 v[24:27], v[178:181], v[218:221], v[24:27]
	v_mfma_f32_16x16x32_bf16 v[12:15], v[170:173], v[226:229], v[12:15]
	v_mfma_f32_16x16x32_bf16 v[8:11], v[178:181], v[226:229], v[8:11]
	s_setprio 0
	s_setprio 1
	v_mfma_f32_16x16x32_bf16 v[52:55], v[182:185], v[198:201], v[52:55]
	v_mfma_f32_16x16x32_bf16 v[48:51], v[190:193], v[198:201], v[48:51]
	v_mfma_f32_16x16x32_bf16 v[36:39], v[182:185], v[206:209], v[36:39]
	v_mfma_f32_16x16x32_bf16 v[32:35], v[190:193], v[206:209], v[32:35]
	v_mfma_f32_16x16x32_bf16 v[20:23], v[182:185], v[214:217], v[20:23]
	v_mfma_f32_16x16x32_bf16 v[16:19], v[190:193], v[214:217], v[16:19]
	v_mfma_f32_16x16x32_bf16 v[4:7], v[182:185], v[222:225], v[4:7]
	v_mfma_f32_16x16x32_bf16 v[0:3], v[190:193], v[222:225], v[0:3]
	v_mfma_f32_16x16x32_bf16 v[52:55], v[186:189], v[202:205], v[52:55]
	v_mfma_f32_16x16x32_bf16 v[48:51], v[194:197], v[202:205], v[48:51]
	v_mfma_f32_16x16x32_bf16 v[36:39], v[186:189], v[210:213], v[36:39]
	v_mfma_f32_16x16x32_bf16 v[32:35], v[194:197], v[210:213], v[32:35]
	v_mfma_f32_16x16x32_bf16 v[20:23], v[186:189], v[218:221], v[20:23]
	v_mfma_f32_16x16x32_bf16 v[16:19], v[194:197], v[218:221], v[16:19]
	v_mfma_f32_16x16x32_bf16 v[4:7], v[186:189], v[226:229], v[4:7]
	v_mfma_f32_16x16x32_bf16 v[0:3], v[194:197], v[226:229], v[0:3]
	s_setprio 0
	s_barrier
	s_add_i32 s8, s81, 2
	s_add_u32 s44, s44, 0x100
	s_addc_u32 s45, s45, 0
	s_cmp_gt_u32 s81, 13
	s_mov_b32 s81, s8
	s_cbranch_scc1 .LBB0_813
	s_branch .LBB0_807
.LBB0_806:
	v_add_u32_e32 v152, s68, v157
	ds_read_b128 v[166:169], v152
	ds_read_b128 v[170:173], v152 offset:1024
	ds_read_b128 v[174:177], v152 offset:2048
	ds_read_b128 v[178:181], v152 offset:3072
	v_add_u32_e32 v152, s69, v157
	ds_read_b128 v[182:185], v152
	ds_read_b128 v[186:189], v152 offset:1024
	ds_read_b128 v[190:193], v152 offset:2048
	ds_read_b128 v[194:197], v152 offset:3072
	s_add_u32 s8, s52, 0x100
	s_addc_u32 s84, s53, 0
	s_and_b64 s[52:53], exec, s[50:51]
	s_cselect_b32 s53, s21, s84
	s_cselect_b32 s52, s79, s8
	s_add_u32 s8, s83, 0x100
	s_addc_u32 s82, s82, 0
	s_and_b64 s[50:51], exec, s[50:51]
	s_cselect_b32 s51, s19, s82
	s_cselect_b32 s50, s80, s8
	v_lshl_add_u64 v[154:155], v[148:149], 0, s[44:45]
	s_add_i32 m0, s57, 0xc000
	ds_read_b128 v[198:201], v161
	ds_read_b128 v[202:205], v161 offset:1024
	ds_read_b128 v[206:209], v161 offset:2048
	ds_read_b128 v[210:213], v161 offset:3072
	ds_read_b128 v[214:217], v161 offset:4096
	ds_read_b128 v[218:221], v161 offset:5120
	ds_read_b128 v[222:225], v161 offset:6144
	global_load_lds_dwordx4 v[154:155], off
	v_lshl_add_u64 v[154:155], v[150:151], 0, s[44:45]
	s_add_i32 m0, s57, 0xe000
	ds_read_b128 v[226:229], v161 offset:7168
	global_load_lds_dwordx4 v[154:155], off
	s_waitcnt vmcnt(8)
	s_waitcnt lgkmcnt(0)
	s_setprio 1
	s_barrier
	v_mfma_f32_16x16x32_bf16 v[124:127], v[166:169], v[198:201], v[124:127]
	v_mfma_f32_16x16x32_bf16 v[120:123], v[174:177], v[198:201], v[120:123]
	v_mfma_f32_16x16x32_bf16 v[108:111], v[166:169], v[206:209], v[108:111]
	v_mfma_f32_16x16x32_bf16 v[104:107], v[174:177], v[206:209], v[104:107]
	v_mfma_f32_16x16x32_bf16 v[92:95], v[166:169], v[214:217], v[92:95]
	v_mfma_f32_16x16x32_bf16 v[88:91], v[174:177], v[214:217], v[88:91]
	v_mfma_f32_16x16x32_bf16 v[76:79], v[166:169], v[222:225], v[76:79]
	v_mfma_f32_16x16x32_bf16 v[72:75], v[174:177], v[222:225], v[72:75]
	v_mfma_f32_16x16x32_bf16 v[124:127], v[170:173], v[202:205], v[124:127]
	v_mfma_f32_16x16x32_bf16 v[120:123], v[178:181], v[202:205], v[120:123]
	v_mfma_f32_16x16x32_bf16 v[108:111], v[170:173], v[210:213], v[108:111]
	v_mfma_f32_16x16x32_bf16 v[104:107], v[178:181], v[210:213], v[104:107]
	v_mfma_f32_16x16x32_bf16 v[92:95], v[170:173], v[218:221], v[92:95]
	v_mfma_f32_16x16x32_bf16 v[88:91], v[178:181], v[218:221], v[88:91]
	v_mfma_f32_16x16x32_bf16 v[76:79], v[170:173], v[226:229], v[76:79]
	v_mfma_f32_16x16x32_bf16 v[72:75], v[178:181], v[226:229], v[72:75]
	s_setprio 0
	s_setprio 1
	v_mfma_f32_16x16x32_bf16 v[116:119], v[182:185], v[198:201], v[116:119]
	v_mfma_f32_16x16x32_bf16 v[112:115], v[190:193], v[198:201], v[112:115]
	v_mfma_f32_16x16x32_bf16 v[100:103], v[182:185], v[206:209], v[100:103]
	v_mfma_f32_16x16x32_bf16 v[96:99], v[190:193], v[206:209], v[96:99]
	v_mfma_f32_16x16x32_bf16 v[84:87], v[182:185], v[214:217], v[84:87]
	v_mfma_f32_16x16x32_bf16 v[80:83], v[190:193], v[214:217], v[80:83]
	v_mfma_f32_16x16x32_bf16 v[68:71], v[182:185], v[222:225], v[68:71]
	v_mfma_f32_16x16x32_bf16 v[64:67], v[190:193], v[222:225], v[64:67]
	v_mfma_f32_16x16x32_bf16 v[116:119], v[186:189], v[202:205], v[116:119]
	v_mfma_f32_16x16x32_bf16 v[112:115], v[194:197], v[202:205], v[112:115]
	v_mfma_f32_16x16x32_bf16 v[100:103], v[186:189], v[210:213], v[100:103]
	v_mfma_f32_16x16x32_bf16 v[96:99], v[194:197], v[210:213], v[96:99]
	v_mfma_f32_16x16x32_bf16 v[84:87], v[186:189], v[218:221], v[84:87]
	v_mfma_f32_16x16x32_bf16 v[80:83], v[194:197], v[218:221], v[80:83]
	v_mfma_f32_16x16x32_bf16 v[68:71], v[186:189], v[226:229], v[68:71]
	v_mfma_f32_16x16x32_bf16 v[64:67], v[194:197], v[226:229], v[64:67]
	s_setprio 0
	s_barrier
	s_add_i32 s8, s68, s54
	s_mov_b32 m0, s8
	ds_read_b128 v[198:201], v161 offset:16384
	ds_read_b128 v[202:205], v161 offset:17408
	ds_read_b128 v[206:209], v161 offset:18432
	global_load_lds_dwordx4 v128, s[50:51]
	s_add_i32 m0, s8, 0x2000
	ds_read_b128 v[210:213], v161 offset:19456
	global_load_lds_dwordx4 v130, s[50:51]
	s_add_u32 s50, s50, 0x40000
	s_addc_u32 s51, s51, 0
	s_add_i32 s8, s69, s54
	s_mov_b32 m0, s8
	ds_read_b128 v[214:217], v161 offset:20480
	global_load_lds_dwordx4 v128, s[50:51]
	s_add_i32 m0, s8, 0x2000
	ds_read_b128 v[218:221], v161 offset:21504
	global_load_lds_dwordx4 v130, s[50:51]
	s_mov_b32 m0, s57
	ds_read_b128 v[222:225], v161 offset:22528
	global_load_lds_dwordx4 v134, s[52:53]
	s_mov_b32 m0, s58
	ds_read_b128 v[226:229], v161 offset:23552
	global_load_lds_dwordx4 v132, s[52:53]
	s_waitcnt vmcnt(8)
	s_waitcnt lgkmcnt(0)
	s_setprio 1
	s_barrier
	v_mfma_f32_16x16x32_bf16 v[60:63], v[166:169], v[198:201], v[60:63]
	v_mfma_f32_16x16x32_bf16 v[56:59], v[174:177], v[198:201], v[56:59]
	v_mfma_f32_16x16x32_bf16 v[44:47], v[166:169], v[206:209], v[44:47]
	v_mfma_f32_16x16x32_bf16 v[40:43], v[174:177], v[206:209], v[40:43]
	v_mfma_f32_16x16x32_bf16 v[28:31], v[166:169], v[214:217], v[28:31]
	v_mfma_f32_16x16x32_bf16 v[24:27], v[174:177], v[214:217], v[24:27]
	v_mfma_f32_16x16x32_bf16 v[12:15], v[166:169], v[222:225], v[12:15]
	v_mfma_f32_16x16x32_bf16 v[8:11], v[174:177], v[222:225], v[8:11]
	v_mfma_f32_16x16x32_bf16 v[60:63], v[170:173], v[202:205], v[60:63]
	v_mfma_f32_16x16x32_bf16 v[56:59], v[178:181], v[202:205], v[56:59]
	v_mfma_f32_16x16x32_bf16 v[44:47], v[170:173], v[210:213], v[44:47]
	v_mfma_f32_16x16x32_bf16 v[40:43], v[178:181], v[210:213], v[40:43]
	v_mfma_f32_16x16x32_bf16 v[28:31], v[170:173], v[218:221], v[28:31]
	v_mfma_f32_16x16x32_bf16 v[24:27], v[178:181], v[218:221], v[24:27]
	v_mfma_f32_16x16x32_bf16 v[12:15], v[170:173], v[226:229], v[12:15]
	v_mfma_f32_16x16x32_bf16 v[8:11], v[178:181], v[226:229], v[8:11]
	s_setprio 0
	s_setprio 1
	v_mfma_f32_16x16x32_bf16 v[52:55], v[182:185], v[198:201], v[52:55]
	v_mfma_f32_16x16x32_bf16 v[48:51], v[190:193], v[198:201], v[48:51]
	v_mfma_f32_16x16x32_bf16 v[36:39], v[182:185], v[206:209], v[36:39]
	v_mfma_f32_16x16x32_bf16 v[32:35], v[190:193], v[206:209], v[32:35]
	v_mfma_f32_16x16x32_bf16 v[20:23], v[182:185], v[214:217], v[20:23]
	v_mfma_f32_16x16x32_bf16 v[16:19], v[190:193], v[214:217], v[16:19]
	v_mfma_f32_16x16x32_bf16 v[4:7], v[182:185], v[222:225], v[4:7]
	v_mfma_f32_16x16x32_bf16 v[0:3], v[190:193], v[222:225], v[0:3]
	v_mfma_f32_16x16x32_bf16 v[52:55], v[186:189], v[202:205], v[52:55]
	v_mfma_f32_16x16x32_bf16 v[48:51], v[194:197], v[202:205], v[48:51]
	v_mfma_f32_16x16x32_bf16 v[36:39], v[186:189], v[210:213], v[36:39]
	v_mfma_f32_16x16x32_bf16 v[32:35], v[194:197], v[210:213], v[32:35]
	v_mfma_f32_16x16x32_bf16 v[20:23], v[186:189], v[218:221], v[20:23]
	v_mfma_f32_16x16x32_bf16 v[16:19], v[194:197], v[218:221], v[16:19]
	v_mfma_f32_16x16x32_bf16 v[4:7], v[186:189], v[226:229], v[4:7]
	v_mfma_f32_16x16x32_bf16 v[0:3], v[194:197], v[226:229], v[0:3]
	s_setprio 0
	s_barrier
	s_add_i32 s8, 0, 0x18000
	v_add_u32_e32 v152, s8, v157
	s_add_i32 s82, 0, 0x1c000
	ds_read_b128 v[166:169], v152
	ds_read_b128 v[170:173], v152 offset:1024
	ds_read_b128 v[174:177], v152 offset:2048
	ds_read_b128 v[178:181], v152 offset:3072
	v_add_u32_e32 v152, s82, v157
	ds_read_b128 v[182:185], v152
	ds_read_b128 v[186:189], v152 offset:1024
	ds_read_b128 v[190:193], v152 offset:2048
	ds_read_b128 v[194:197], v152 offset:3072
	s_add_u32 s50, s52, 0x40000
	s_addc_u32 s51, s53, 0
	s_mov_b32 m0, s59
	ds_read_b128 v[198:201], v161 offset:32768
	ds_read_b128 v[202:205], v161 offset:33792
	ds_read_b128 v[206:209], v161 offset:34816
	ds_read_b128 v[210:213], v161 offset:35840
	ds_read_b128 v[214:217], v161 offset:36864
	ds_read_b128 v[218:221], v161 offset:37888
	ds_read_b128 v[222:225], v161 offset:38912
	global_load_lds_dwordx4 v134, s[50:51]
	s_mov_b32 m0, s60
	ds_read_b128 v[226:229], v161 offset:39936
	global_load_lds_dwordx4 v132, s[50:51]
	s_waitcnt vmcnt(8)
	s_waitcnt lgkmcnt(0)
	s_setprio 1
	s_barrier
	v_mfma_f32_16x16x32_bf16 v[124:127], v[166:169], v[198:201], v[124:127]
	v_mfma_f32_16x16x32_bf16 v[120:123], v[174:177], v[198:201], v[120:123]
	v_mfma_f32_16x16x32_bf16 v[108:111], v[166:169], v[206:209], v[108:111]
	v_mfma_f32_16x16x32_bf16 v[104:107], v[174:177], v[206:209], v[104:107]
	v_mfma_f32_16x16x32_bf16 v[92:95], v[166:169], v[214:217], v[92:95]
	v_mfma_f32_16x16x32_bf16 v[88:91], v[174:177], v[214:217], v[88:91]
	v_mfma_f32_16x16x32_bf16 v[76:79], v[166:169], v[222:225], v[76:79]
	v_mfma_f32_16x16x32_bf16 v[72:75], v[174:177], v[222:225], v[72:75]
	v_mfma_f32_16x16x32_bf16 v[124:127], v[170:173], v[202:205], v[124:127]
	v_mfma_f32_16x16x32_bf16 v[120:123], v[178:181], v[202:205], v[120:123]
	v_mfma_f32_16x16x32_bf16 v[108:111], v[170:173], v[210:213], v[108:111]
	v_mfma_f32_16x16x32_bf16 v[104:107], v[178:181], v[210:213], v[104:107]
	v_mfma_f32_16x16x32_bf16 v[92:95], v[170:173], v[218:221], v[92:95]
	v_mfma_f32_16x16x32_bf16 v[88:91], v[178:181], v[218:221], v[88:91]
	v_mfma_f32_16x16x32_bf16 v[76:79], v[170:173], v[226:229], v[76:79]
	v_mfma_f32_16x16x32_bf16 v[72:75], v[178:181], v[226:229], v[72:75]
	s_setprio 0
	s_setprio 1
	v_mfma_f32_16x16x32_bf16 v[116:119], v[182:185], v[198:201], v[116:119]
	v_mfma_f32_16x16x32_bf16 v[112:115], v[190:193], v[198:201], v[112:115]
	v_mfma_f32_16x16x32_bf16 v[100:103], v[182:185], v[206:209], v[100:103]
	v_mfma_f32_16x16x32_bf16 v[96:99], v[190:193], v[206:209], v[96:99]
	v_mfma_f32_16x16x32_bf16 v[84:87], v[182:185], v[214:217], v[84:87]
	v_mfma_f32_16x16x32_bf16 v[80:83], v[190:193], v[214:217], v[80:83]
	v_mfma_f32_16x16x32_bf16 v[68:71], v[182:185], v[222:225], v[68:71]
	v_mfma_f32_16x16x32_bf16 v[64:67], v[190:193], v[222:225], v[64:67]
	v_mfma_f32_16x16x32_bf16 v[116:119], v[186:189], v[202:205], v[116:119]
	v_mfma_f32_16x16x32_bf16 v[112:115], v[194:197], v[202:205], v[112:115]
	v_mfma_f32_16x16x32_bf16 v[100:103], v[186:189], v[210:213], v[100:103]
	v_mfma_f32_16x16x32_bf16 v[96:99], v[194:197], v[210:213], v[96:99]
	v_mfma_f32_16x16x32_bf16 v[84:87], v[186:189], v[218:221], v[84:87]
	v_mfma_f32_16x16x32_bf16 v[80:83], v[194:197], v[218:221], v[80:83]
	v_mfma_f32_16x16x32_bf16 v[68:71], v[186:189], v[226:229], v[68:71]
	v_mfma_f32_16x16x32_bf16 v[64:67], v[194:197], v[226:229], v[64:67]
	s_setprio 0
	s_barrier
	s_add_i32 s8, s8, s54
	s_mov_b32 m0, s8
	ds_read_b128 v[198:201], v161 offset:49152
	ds_read_b128 v[202:205], v161 offset:50176
	ds_read_b128 v[206:209], v161 offset:51200
	global_load_lds_dwordx4 v128, s[48:49]
	s_add_i32 m0, s8, 0x2000
	ds_read_b128 v[210:213], v161 offset:52224
	global_load_lds_dwordx4 v130, s[48:49]
	s_add_u32 s48, s48, 0x40000
	s_addc_u32 s49, s49, 0
	s_add_i32 s8, s82, s54
	s_mov_b32 m0, s8
	ds_read_b128 v[214:217], v161 offset:53248
	global_load_lds_dwordx4 v128, s[48:49]
	s_add_i32 m0, s8, 0x2000
	ds_read_b128 v[218:221], v161 offset:54272
	global_load_lds_dwordx4 v130, s[48:49]
	s_mov_b32 m0, s65
	ds_read_b128 v[222:225], v161 offset:55296
	global_load_lds_dwordx4 v134, s[46:47]
	s_mov_b32 m0, s66
	ds_read_b128 v[226:229], v161 offset:56320
	global_load_lds_dwordx4 v132, s[46:47]
	s_waitcnt vmcnt(8)
	s_waitcnt lgkmcnt(0)
	s_setprio 1
	s_barrier
	v_mfma_f32_16x16x32_bf16 v[60:63], v[166:169], v[198:201], v[60:63]
	v_mfma_f32_16x16x32_bf16 v[56:59], v[174:177], v[198:201], v[56:59]
	v_mfma_f32_16x16x32_bf16 v[44:47], v[166:169], v[206:209], v[44:47]
	v_mfma_f32_16x16x32_bf16 v[40:43], v[174:177], v[206:209], v[40:43]
	v_mfma_f32_16x16x32_bf16 v[28:31], v[166:169], v[214:217], v[28:31]
	v_mfma_f32_16x16x32_bf16 v[24:27], v[174:177], v[214:217], v[24:27]
	v_mfma_f32_16x16x32_bf16 v[12:15], v[166:169], v[222:225], v[12:15]
	v_mfma_f32_16x16x32_bf16 v[8:11], v[174:177], v[222:225], v[8:11]
	v_mfma_f32_16x16x32_bf16 v[60:63], v[170:173], v[202:205], v[60:63]
	v_mfma_f32_16x16x32_bf16 v[56:59], v[178:181], v[202:205], v[56:59]
	v_mfma_f32_16x16x32_bf16 v[44:47], v[170:173], v[210:213], v[44:47]
	v_mfma_f32_16x16x32_bf16 v[40:43], v[178:181], v[210:213], v[40:43]
	v_mfma_f32_16x16x32_bf16 v[28:31], v[170:173], v[218:221], v[28:31]
	v_mfma_f32_16x16x32_bf16 v[24:27], v[178:181], v[218:221], v[24:27]
	v_mfma_f32_16x16x32_bf16 v[12:15], v[170:173], v[226:229], v[12:15]
	v_mfma_f32_16x16x32_bf16 v[8:11], v[178:181], v[226:229], v[8:11]
	s_setprio 0
	s_setprio 1
	v_mfma_f32_16x16x32_bf16 v[52:55], v[182:185], v[198:201], v[52:55]
	v_mfma_f32_16x16x32_bf16 v[48:51], v[190:193], v[198:201], v[48:51]
	v_mfma_f32_16x16x32_bf16 v[36:39], v[182:185], v[206:209], v[36:39]
	v_mfma_f32_16x16x32_bf16 v[32:35], v[190:193], v[206:209], v[32:35]
	v_mfma_f32_16x16x32_bf16 v[20:23], v[182:185], v[214:217], v[20:23]
	v_mfma_f32_16x16x32_bf16 v[16:19], v[190:193], v[214:217], v[16:19]
	v_mfma_f32_16x16x32_bf16 v[4:7], v[182:185], v[222:225], v[4:7]
	v_mfma_f32_16x16x32_bf16 v[0:3], v[190:193], v[222:225], v[0:3]
	v_mfma_f32_16x16x32_bf16 v[52:55], v[186:189], v[202:205], v[52:55]
	v_mfma_f32_16x16x32_bf16 v[48:51], v[194:197], v[202:205], v[48:51]
	v_mfma_f32_16x16x32_bf16 v[36:39], v[186:189], v[210:213], v[36:39]
	v_mfma_f32_16x16x32_bf16 v[32:35], v[194:197], v[210:213], v[32:35]
	v_mfma_f32_16x16x32_bf16 v[20:23], v[186:189], v[218:221], v[20:23]
	v_mfma_f32_16x16x32_bf16 v[16:19], v[194:197], v[218:221], v[16:19]
	v_mfma_f32_16x16x32_bf16 v[4:7], v[186:189], v[226:229], v[4:7]
	v_mfma_f32_16x16x32_bf16 v[0:3], v[194:197], v[226:229], v[0:3]
	s_setprio 0
	s_barrier
	s_add_i32 s8, s81, 2
	s_add_u32 s44, s44, 0x100
	s_addc_u32 s45, s45, 0
	s_cmp_gt_u32 s81, 13
	s_mov_b32 s81, s8
	s_cbranch_scc1 .LBB0_813

.LBB0_895:
	s_add_u32 s70, s55, s28
	s_addc_u32 s71, s56, s29
	s_add_u32 s72, s57, s30
	s_addc_u32 s73, s58, s31
	s_add_u32 s28, s4, 0x80
	s_addc_u32 s29, s5, 0
	s_add_u32 s30, s20, 0x80
	s_addc_u32 s31, s21, 0
	v_lshl_add_u64 v[128:129], s[26:27], 0, v[148:149]
	v_lshl_add_u64 v[130:131], s[26:27], 0, v[150:151]
	s_mov_b32 s78, 0
	s_mov_b64 s[36:37], 0
	s_cmpk_eq_i32 s36, 0x1500
	s_cselect_b64 s[44:45], -1, 0
	s_add_u32 s46, s26, s36
	s_addc_u32 s47, s27, s37
	s_add_u32 s80, s24, s36
	s_addc_u32 s79, s25, s37
	s_add_u32 s38, s46, 0x180
	s_addc_u32 s39, s47, 0
	s_add_u32 s40, s80, 0x180
	s_addc_u32 s41, s79, 0
	s_cmpk_eq_i32 s36, 0x1500
	s_cselect_b32 s38, s28, s38
	s_cselect_b32 s39, s29, s39
	s_cselect_b32 s40, s30, s40
	s_cselect_b32 s41, s31, s41
	v_add_u32_e32 v167, s64, v165
	ds_read_b128 v[132:135], v167
	ds_read_b128 v[156:159], v167 offset:1024
	ds_read_b128 v[160:163], v167 offset:2048
	ds_read_b128 v[168:171], v167 offset:3072
	v_add_u32_e32 v167, s65, v165
	ds_read_b128 v[172:175], v167
	ds_read_b128 v[176:179], v167 offset:1024
	ds_read_b128 v[180:183], v167 offset:2048
	ds_read_b128 v[184:187], v167 offset:3072
	s_add_u32 s8, s46, 0x100
	s_addc_u32 s81, s47, 0
	s_and_b64 s[46:47], exec, s[44:45]
	s_cselect_b32 s47, s5, s81
	s_cselect_b32 s46, s4, s8
	s_add_u32 s8, s80, 0x100
	s_addc_u32 s79, s79, 0
	s_and_b64 s[44:45], exec, s[44:45]
	s_cselect_b32 s45, s21, s79
	s_cselect_b32 s44, s20, s8
	v_lshl_add_u64 v[220:221], v[128:129], 0, s[36:37]
	s_add_i32 m0, s51, 0xc000
	ds_read_b128 v[188:191], v166
	ds_read_b128 v[192:195], v166 offset:1024
	ds_read_b128 v[196:199], v166 offset:2048
	ds_read_b128 v[200:203], v166 offset:3072
	ds_read_b128 v[204:207], v166 offset:4096
	ds_read_b128 v[208:211], v166 offset:5120
	ds_read_b128 v[212:215], v166 offset:6144
	global_load_lds_dwordx4 v[220:221], off
	v_lshl_add_u64 v[220:221], v[130:131], 0, s[36:37]
	s_add_i32 m0, s51, 0xe000
	ds_read_b128 v[216:219], v166 offset:7168
	global_load_lds_dwordx4 v[220:221], off
	s_waitcnt vmcnt(8)
	s_waitcnt lgkmcnt(0)
	s_setprio 1
	s_barrier
	v_mfma_f32_16x16x32_bf16 v[124:127], v[132:135], v[188:191], 0
	v_mfma_f32_16x16x32_bf16 v[120:123], v[160:163], v[188:191], 0
	v_mfma_f32_16x16x32_bf16 v[108:111], v[132:135], v[196:199], 0
	v_mfma_f32_16x16x32_bf16 v[104:107], v[160:163], v[196:199], 0
	v_mfma_f32_16x16x32_bf16 v[92:95], v[132:135], v[204:207], 0
	v_mfma_f32_16x16x32_bf16 v[88:91], v[160:163], v[204:207], 0
	v_mfma_f32_16x16x32_bf16 v[76:79], v[132:135], v[212:215], 0
	v_mfma_f32_16x16x32_bf16 v[72:75], v[160:163], v[212:215], 0
	v_mfma_f32_16x16x32_bf16 v[124:127], v[156:159], v[192:195], v[124:127]
	v_mfma_f32_16x16x32_bf16 v[120:123], v[168:171], v[192:195], v[120:123]
	v_mfma_f32_16x16x32_bf16 v[108:111], v[156:159], v[200:203], v[108:111]
	v_mfma_f32_16x16x32_bf16 v[104:107], v[168:171], v[200:203], v[104:107]
	v_mfma_f32_16x16x32_bf16 v[92:95], v[156:159], v[208:211], v[92:95]
	v_mfma_f32_16x16x32_bf16 v[88:91], v[168:171], v[208:211], v[88:91]
	v_mfma_f32_16x16x32_bf16 v[76:79], v[156:159], v[216:219], v[76:79]
	v_mfma_f32_16x16x32_bf16 v[72:75], v[168:171], v[216:219], v[72:75]
	s_setprio 0
	s_setprio 1
	v_mfma_f32_16x16x32_bf16 v[116:119], v[172:175], v[188:191], 0
	v_mfma_f32_16x16x32_bf16 v[112:115], v[180:183], v[188:191], 0
	v_mfma_f32_16x16x32_bf16 v[100:103], v[172:175], v[196:199], 0
	v_mfma_f32_16x16x32_bf16 v[96:99], v[180:183], v[196:199], 0
	v_mfma_f32_16x16x32_bf16 v[84:87], v[172:175], v[204:207], 0
	v_mfma_f32_16x16x32_bf16 v[80:83], v[180:183], v[204:207], 0
	v_mfma_f32_16x16x32_bf16 v[68:71], v[172:175], v[212:215], 0
	v_mfma_f32_16x16x32_bf16 v[64:67], v[180:183], v[212:215], 0
	v_mfma_f32_16x16x32_bf16 v[116:119], v[176:179], v[192:195], v[116:119]
	v_mfma_f32_16x16x32_bf16 v[112:115], v[184:187], v[192:195], v[112:115]
	v_mfma_f32_16x16x32_bf16 v[100:103], v[176:179], v[200:203], v[100:103]
	v_mfma_f32_16x16x32_bf16 v[96:99], v[184:187], v[200:203], v[96:99]
	v_mfma_f32_16x16x32_bf16 v[84:87], v[176:179], v[208:211], v[84:87]
	v_mfma_f32_16x16x32_bf16 v[80:83], v[184:187], v[208:211], v[80:83]
	v_mfma_f32_16x16x32_bf16 v[68:71], v[176:179], v[216:219], v[68:71]
	v_mfma_f32_16x16x32_bf16 v[64:67], v[184:187], v[216:219], v[64:67]
	s_setprio 0
	s_barrier
	s_add_i32 s8, s64, s50
	s_mov_b32 m0, s8
	ds_read_b128 v[188:191], v166 offset:16384
	ds_read_b128 v[192:195], v166 offset:17408
	ds_read_b128 v[196:199], v166 offset:18432
	global_load_lds_dwordx4 v138, s[44:45]
	s_add_i32 m0, s8, 0x2000
	ds_read_b128 v[200:203], v166 offset:19456
	global_load_lds_dwordx4 v142, s[44:45]
	s_add_u32 s44, s44, 0xb0000
	s_addc_u32 s45, s45, 0
	s_add_i32 s8, s65, s50
	s_mov_b32 m0, s8
	ds_read_b128 v[204:207], v166 offset:20480
	global_load_lds_dwordx4 v138, s[44:45]
	s_add_i32 m0, s8, 0x2000
	ds_read_b128 v[208:211], v166 offset:21504
	global_load_lds_dwordx4 v142, s[44:45]
	s_mov_b32 m0, s51
	ds_read_b128 v[212:215], v166 offset:22528
	global_load_lds_dwordx4 v136, s[46:47]
	s_mov_b32 m0, s52
	ds_read_b128 v[216:219], v166 offset:23552
	global_load_lds_dwordx4 v140, s[46:47]
	s_waitcnt vmcnt(8)
	s_waitcnt lgkmcnt(0)
	s_setprio 1
	s_barrier
	v_mfma_f32_16x16x32_bf16 v[60:63], v[132:135], v[188:191], 0
	v_mfma_f32_16x16x32_bf16 v[56:59], v[160:163], v[188:191], 0
	v_mfma_f32_16x16x32_bf16 v[44:47], v[132:135], v[196:199], 0
	v_mfma_f32_16x16x32_bf16 v[40:43], v[160:163], v[196:199], 0
	v_mfma_f32_16x16x32_bf16 v[28:31], v[132:135], v[204:207], 0
	v_mfma_f32_16x16x32_bf16 v[24:27], v[160:163], v[204:207], 0
	v_mfma_f32_16x16x32_bf16 v[12:15], v[132:135], v[212:215], 0
	v_mfma_f32_16x16x32_bf16 v[8:11], v[160:163], v[212:215], 0
	v_mfma_f32_16x16x32_bf16 v[60:63], v[156:159], v[192:195], v[60:63]
	v_mfma_f32_16x16x32_bf16 v[56:59], v[168:171], v[192:195], v[56:59]
	v_mfma_f32_16x16x32_bf16 v[44:47], v[156:159], v[200:203], v[44:47]
	v_mfma_f32_16x16x32_bf16 v[40:43], v[168:171], v[200:203], v[40:43]
	v_mfma_f32_16x16x32_bf16 v[28:31], v[156:159], v[208:211], v[28:31]
	v_mfma_f32_16x16x32_bf16 v[24:27], v[168:171], v[208:211], v[24:27]
	v_mfma_f32_16x16x32_bf16 v[12:15], v[156:159], v[216:219], v[12:15]
	v_mfma_f32_16x16x32_bf16 v[8:11], v[168:171], v[216:219], v[8:11]
	s_setprio 0
	s_setprio 1
	v_mfma_f32_16x16x32_bf16 v[52:55], v[172:175], v[188:191], 0
	v_mfma_f32_16x16x32_bf16 v[48:51], v[180:183], v[188:191], 0
	v_mfma_f32_16x16x32_bf16 v[36:39], v[172:175], v[196:199], 0
	v_mfma_f32_16x16x32_bf16 v[32:35], v[180:183], v[196:199], 0
	v_mfma_f32_16x16x32_bf16 v[20:23], v[172:175], v[204:207], 0
	v_mfma_f32_16x16x32_bf16 v[16:19], v[180:183], v[204:207], 0
	v_mfma_f32_16x16x32_bf16 v[4:7], v[172:175], v[212:215], 0
	v_mfma_f32_16x16x32_bf16 v[0:3], v[180:183], v[212:215], 0
	v_mfma_f32_16x16x32_bf16 v[52:55], v[176:179], v[192:195], v[52:55]
	v_mfma_f32_16x16x32_bf16 v[48:51], v[184:187], v[192:195], v[48:51]
	v_mfma_f32_16x16x32_bf16 v[36:39], v[176:179], v[200:203], v[36:39]
	v_mfma_f32_16x16x32_bf16 v[32:35], v[184:187], v[200:203], v[32:35]
	v_mfma_f32_16x16x32_bf16 v[20:23], v[176:179], v[208:211], v[20:23]
	v_mfma_f32_16x16x32_bf16 v[16:19], v[184:187], v[208:211], v[16:19]
	v_mfma_f32_16x16x32_bf16 v[4:7], v[176:179], v[216:219], v[4:7]
	v_mfma_f32_16x16x32_bf16 v[0:3], v[184:187], v[216:219], v[0:3]
	s_setprio 0
	s_barrier
	s_add_i32 s8, 0, 0x18000
	v_add_u32_e32 v167, s8, v165
	s_add_i32 s79, 0, 0x1c000
	ds_read_b128 v[132:135], v167
	ds_read_b128 v[156:159], v167 offset:1024
	ds_read_b128 v[160:163], v167 offset:2048
	ds_read_b128 v[168:171], v167 offset:3072
	v_add_u32_e32 v167, s79, v165
	ds_read_b128 v[172:175], v167
	ds_read_b128 v[176:179], v167 offset:1024
	ds_read_b128 v[180:183], v167 offset:2048
	ds_read_b128 v[184:187], v167 offset:3072
	s_add_u32 s44, s46, 0xb0000
	s_addc_u32 s45, s47, 0
	s_mov_b32 m0, s53
	ds_read_b128 v[188:191], v166 offset:32768
	ds_read_b128 v[192:195], v166 offset:33792
	ds_read_b128 v[196:199], v166 offset:34816
	ds_read_b128 v[200:203], v166 offset:35840
	ds_read_b128 v[204:207], v166 offset:36864
	ds_read_b128 v[208:211], v166 offset:37888
	ds_read_b128 v[212:215], v166 offset:38912
	global_load_lds_dwordx4 v136, s[44:45]
	s_mov_b32 m0, s54
	ds_read_b128 v[216:219], v166 offset:39936
	global_load_lds_dwordx4 v140, s[44:45]
	s_waitcnt vmcnt(8)
	s_waitcnt lgkmcnt(0)
	s_setprio 1
	s_barrier
	v_mfma_f32_16x16x32_bf16 v[124:127], v[132:135], v[188:191], v[124:127]
	v_mfma_f32_16x16x32_bf16 v[120:123], v[160:163], v[188:191], v[120:123]
	v_mfma_f32_16x16x32_bf16 v[108:111], v[132:135], v[196:199], v[108:111]
	v_mfma_f32_16x16x32_bf16 v[104:107], v[160:163], v[196:199], v[104:107]
	v_mfma_f32_16x16x32_bf16 v[92:95], v[132:135], v[204:207], v[92:95]
	v_mfma_f32_16x16x32_bf16 v[88:91], v[160:163], v[204:207], v[88:91]
	v_mfma_f32_16x16x32_bf16 v[76:79], v[132:135], v[212:215], v[76:79]
	v_mfma_f32_16x16x32_bf16 v[72:75], v[160:163], v[212:215], v[72:75]
	v_mfma_f32_16x16x32_bf16 v[124:127], v[156:159], v[192:195], v[124:127]
	v_mfma_f32_16x16x32_bf16 v[120:123], v[168:171], v[192:195], v[120:123]
	v_mfma_f32_16x16x32_bf16 v[108:111], v[156:159], v[200:203], v[108:111]
	v_mfma_f32_16x16x32_bf16 v[104:107], v[168:171], v[200:203], v[104:107]
	v_mfma_f32_16x16x32_bf16 v[92:95], v[156:159], v[208:211], v[92:95]
	v_mfma_f32_16x16x32_bf16 v[88:91], v[168:171], v[208:211], v[88:91]
	v_mfma_f32_16x16x32_bf16 v[76:79], v[156:159], v[216:219], v[76:79]
	v_mfma_f32_16x16x32_bf16 v[72:75], v[168:171], v[216:219], v[72:75]
	s_setprio 0
	s_setprio 1
	v_mfma_f32_16x16x32_bf16 v[116:119], v[172:175], v[188:191], v[116:119]
	v_mfma_f32_16x16x32_bf16 v[112:115], v[180:183], v[188:191], v[112:115]
	v_mfma_f32_16x16x32_bf16 v[100:103], v[172:175], v[196:199], v[100:103]
	v_mfma_f32_16x16x32_bf16 v[96:99], v[180:183], v[196:199], v[96:99]
	v_mfma_f32_16x16x32_bf16 v[84:87], v[172:175], v[204:207], v[84:87]
	v_mfma_f32_16x16x32_bf16 v[80:83], v[180:183], v[204:207], v[80:83]
	v_mfma_f32_16x16x32_bf16 v[68:71], v[172:175], v[212:215], v[68:71]
	v_mfma_f32_16x16x32_bf16 v[64:67], v[180:183], v[212:215], v[64:67]
	v_mfma_f32_16x16x32_bf16 v[116:119], v[176:179], v[192:195], v[116:119]
	v_mfma_f32_16x16x32_bf16 v[112:115], v[184:187], v[192:195], v[112:115]
	v_mfma_f32_16x16x32_bf16 v[100:103], v[176:179], v[200:203], v[100:103]
	v_mfma_f32_16x16x32_bf16 v[96:99], v[184:187], v[200:203], v[96:99]
	v_mfma_f32_16x16x32_bf16 v[84:87], v[176:179], v[208:211], v[84:87]
	v_mfma_f32_16x16x32_bf16 v[80:83], v[184:187], v[208:211], v[80:83]
	v_mfma_f32_16x16x32_bf16 v[68:71], v[176:179], v[216:219], v[68:71]
	v_mfma_f32_16x16x32_bf16 v[64:67], v[184:187], v[216:219], v[64:67]
	s_setprio 0
	s_barrier
	s_add_i32 s8, s8, s50
	s_mov_b32 m0, s8
	ds_read_b128 v[188:191], v166 offset:49152
	ds_read_b128 v[192:195], v166 offset:50176
	ds_read_b128 v[196:199], v166 offset:51200
	global_load_lds_dwordx4 v138, s[40:41]
	s_add_i32 m0, s8, 0x2000
	ds_read_b128 v[200:203], v166 offset:52224
	global_load_lds_dwordx4 v142, s[40:41]
	s_add_u32 s40, s40, 0xb0000
	s_addc_u32 s41, s41, 0
	s_add_i32 s8, s79, s50
	s_mov_b32 m0, s8
	ds_read_b128 v[204:207], v166 offset:53248
	global_load_lds_dwordx4 v138, s[40:41]
	s_add_i32 m0, s8, 0x2000
	ds_read_b128 v[208:211], v166 offset:54272
	global_load_lds_dwordx4 v142, s[40:41]
	s_mov_b32 m0, s60
	ds_read_b128 v[212:215], v166 offset:55296
	global_load_lds_dwordx4 v136, s[38:39]
	s_mov_b32 m0, s61
	ds_read_b128 v[216:219], v166 offset:56320
	global_load_lds_dwordx4 v140, s[38:39]
	s_waitcnt vmcnt(8)
	s_waitcnt lgkmcnt(0)
	s_setprio 1
	s_barrier
	v_mfma_f32_16x16x32_bf16 v[60:63], v[132:135], v[188:191], v[60:63]
	v_mfma_f32_16x16x32_bf16 v[56:59], v[160:163], v[188:191], v[56:59]
	v_mfma_f32_16x16x32_bf16 v[44:47], v[132:135], v[196:199], v[44:47]
	v_mfma_f32_16x16x32_bf16 v[40:43], v[160:163], v[196:199], v[40:43]
	v_mfma_f32_16x16x32_bf16 v[28:31], v[132:135], v[204:207], v[28:31]
	v_mfma_f32_16x16x32_bf16 v[24:27], v[160:163], v[204:207], v[24:27]
	v_mfma_f32_16x16x32_bf16 v[12:15], v[132:135], v[212:215], v[12:15]
	v_mfma_f32_16x16x32_bf16 v[8:11], v[160:163], v[212:215], v[8:11]
	v_mfma_f32_16x16x32_bf16 v[60:63], v[156:159], v[192:195], v[60:63]
	v_mfma_f32_16x16x32_bf16 v[56:59], v[168:171], v[192:195], v[56:59]
	v_mfma_f32_16x16x32_bf16 v[44:47], v[156:159], v[200:203], v[44:47]
	v_mfma_f32_16x16x32_bf16 v[40:43], v[168:171], v[200:203], v[40:43]
	v_mfma_f32_16x16x32_bf16 v[28:31], v[156:159], v[208:211], v[28:31]
	v_mfma_f32_16x16x32_bf16 v[24:27], v[168:171], v[208:211], v[24:27]
	v_mfma_f32_16x16x32_bf16 v[12:15], v[156:159], v[216:219], v[12:15]
	v_mfma_f32_16x16x32_bf16 v[8:11], v[168:171], v[216:219], v[8:11]
	s_setprio 0
	s_setprio 1
	v_mfma_f32_16x16x32_bf16 v[52:55], v[172:175], v[188:191], v[52:55]
	v_mfma_f32_16x16x32_bf16 v[48:51], v[180:183], v[188:191], v[48:51]
	v_mfma_f32_16x16x32_bf16 v[36:39], v[172:175], v[196:199], v[36:39]
	v_mfma_f32_16x16x32_bf16 v[32:35], v[180:183], v[196:199], v[32:35]
	v_mfma_f32_16x16x32_bf16 v[20:23], v[172:175], v[204:207], v[20:23]
	v_mfma_f32_16x16x32_bf16 v[16:19], v[180:183], v[204:207], v[16:19]
	v_mfma_f32_16x16x32_bf16 v[4:7], v[172:175], v[212:215], v[4:7]
	v_mfma_f32_16x16x32_bf16 v[0:3], v[180:183], v[212:215], v[0:3]
	v_mfma_f32_16x16x32_bf16 v[52:55], v[176:179], v[192:195], v[52:55]
	v_mfma_f32_16x16x32_bf16 v[48:51], v[184:187], v[192:195], v[48:51]
	v_mfma_f32_16x16x32_bf16 v[36:39], v[176:179], v[200:203], v[36:39]
	v_mfma_f32_16x16x32_bf16 v[32:35], v[184:187], v[200:203], v[32:35]
	v_mfma_f32_16x16x32_bf16 v[20:23], v[176:179], v[208:211], v[20:23]
	v_mfma_f32_16x16x32_bf16 v[16:19], v[184:187], v[208:211], v[16:19]
	v_mfma_f32_16x16x32_bf16 v[4:7], v[176:179], v[216:219], v[4:7]
	v_mfma_f32_16x16x32_bf16 v[0:3], v[184:187], v[216:219], v[0:3]
	s_setprio 0
	s_barrier
	s_add_i32 s8, s78, 2
	s_add_u32 s36, s36, 0x100
	s_addc_u32 s37, s37, 0
	s_cmp_gt_u32 s78, 41
	s_mov_b32 s78, s8
	s_cbranch_scc1 .LBB0_903
	s_branch .LBB0_897
.LBB0_896:
	v_add_u32_e32 v167, s64, v165
	ds_read_b128 v[132:135], v167
	ds_read_b128 v[156:159], v167 offset:1024
	ds_read_b128 v[160:163], v167 offset:2048
	ds_read_b128 v[168:171], v167 offset:3072
	v_add_u32_e32 v167, s65, v165
	ds_read_b128 v[172:175], v167
	ds_read_b128 v[176:179], v167 offset:1024
	ds_read_b128 v[180:183], v167 offset:2048
	ds_read_b128 v[184:187], v167 offset:3072
	s_add_u32 s8, s46, 0x100
	s_addc_u32 s81, s47, 0
	s_and_b64 s[46:47], exec, s[44:45]
	s_cselect_b32 s47, s5, s81
	s_cselect_b32 s46, s4, s8
	s_add_u32 s8, s80, 0x100
	s_addc_u32 s79, s79, 0
	s_and_b64 s[44:45], exec, s[44:45]
	s_cselect_b32 s45, s21, s79
	s_cselect_b32 s44, s20, s8
	v_lshl_add_u64 v[220:221], v[128:129], 0, s[36:37]
	s_add_i32 m0, s51, 0xc000
	ds_read_b128 v[188:191], v166
	ds_read_b128 v[192:195], v166 offset:1024
	ds_read_b128 v[196:199], v166 offset:2048
	ds_read_b128 v[200:203], v166 offset:3072
	ds_read_b128 v[204:207], v166 offset:4096
	ds_read_b128 v[208:211], v166 offset:5120
	ds_read_b128 v[212:215], v166 offset:6144
	global_load_lds_dwordx4 v[220:221], off
	v_lshl_add_u64 v[220:221], v[130:131], 0, s[36:37]
	s_add_i32 m0, s51, 0xe000
	ds_read_b128 v[216:219], v166 offset:7168
	global_load_lds_dwordx4 v[220:221], off
	s_waitcnt vmcnt(8)
	s_waitcnt lgkmcnt(0)
	s_setprio 1
	s_barrier
	v_mfma_f32_16x16x32_bf16 v[124:127], v[132:135], v[188:191], v[124:127]
	v_mfma_f32_16x16x32_bf16 v[120:123], v[160:163], v[188:191], v[120:123]
	v_mfma_f32_16x16x32_bf16 v[108:111], v[132:135], v[196:199], v[108:111]
	v_mfma_f32_16x16x32_bf16 v[104:107], v[160:163], v[196:199], v[104:107]
	v_mfma_f32_16x16x32_bf16 v[92:95], v[132:135], v[204:207], v[92:95]
	v_mfma_f32_16x16x32_bf16 v[88:91], v[160:163], v[204:207], v[88:91]
	v_mfma_f32_16x16x32_bf16 v[76:79], v[132:135], v[212:215], v[76:79]
	v_mfma_f32_16x16x32_bf16 v[72:75], v[160:163], v[212:215], v[72:75]
	v_mfma_f32_16x16x32_bf16 v[124:127], v[156:159], v[192:195], v[124:127]
	v_mfma_f32_16x16x32_bf16 v[120:123], v[168:171], v[192:195], v[120:123]
	v_mfma_f32_16x16x32_bf16 v[108:111], v[156:159], v[200:203], v[108:111]
	v_mfma_f32_16x16x32_bf16 v[104:107], v[168:171], v[200:203], v[104:107]
	v_mfma_f32_16x16x32_bf16 v[92:95], v[156:159], v[208:211], v[92:95]
	v_mfma_f32_16x16x32_bf16 v[88:91], v[168:171], v[208:211], v[88:91]
	v_mfma_f32_16x16x32_bf16 v[76:79], v[156:159], v[216:219], v[76:79]
	v_mfma_f32_16x16x32_bf16 v[72:75], v[168:171], v[216:219], v[72:75]
	s_setprio 0
	s_setprio 1
	v_mfma_f32_16x16x32_bf16 v[116:119], v[172:175], v[188:191], v[116:119]
	v_mfma_f32_16x16x32_bf16 v[112:115], v[180:183], v[188:191], v[112:115]
	v_mfma_f32_16x16x32_bf16 v[100:103], v[172:175], v[196:199], v[100:103]
	v_mfma_f32_16x16x32_bf16 v[96:99], v[180:183], v[196:199], v[96:99]
	v_mfma_f32_16x16x32_bf16 v[84:87], v[172:175], v[204:207], v[84:87]
	v_mfma_f32_16x16x32_bf16 v[80:83], v[180:183], v[204:207], v[80:83]
	v_mfma_f32_16x16x32_bf16 v[68:71], v[172:175], v[212:215], v[68:71]
	v_mfma_f32_16x16x32_bf16 v[64:67], v[180:183], v[212:215], v[64:67]
	v_mfma_f32_16x16x32_bf16 v[116:119], v[176:179], v[192:195], v[116:119]
	v_mfma_f32_16x16x32_bf16 v[112:115], v[184:187], v[192:195], v[112:115]
	v_mfma_f32_16x16x32_bf16 v[100:103], v[176:179], v[200:203], v[100:103]
	v_mfma_f32_16x16x32_bf16 v[96:99], v[184:187], v[200:203], v[96:99]
	v_mfma_f32_16x16x32_bf16 v[84:87], v[176:179], v[208:211], v[84:87]
	v_mfma_f32_16x16x32_bf16 v[80:83], v[184:187], v[208:211], v[80:83]
	v_mfma_f32_16x16x32_bf16 v[68:71], v[176:179], v[216:219], v[68:71]
	v_mfma_f32_16x16x32_bf16 v[64:67], v[184:187], v[216:219], v[64:67]
	s_setprio 0
	s_barrier
	s_add_i32 s8, s64, s50
	s_mov_b32 m0, s8
	ds_read_b128 v[188:191], v166 offset:16384
	ds_read_b128 v[192:195], v166 offset:17408
	ds_read_b128 v[196:199], v166 offset:18432
	global_load_lds_dwordx4 v138, s[44:45]
	s_add_i32 m0, s8, 0x2000
	ds_read_b128 v[200:203], v166 offset:19456
	global_load_lds_dwordx4 v142, s[44:45]
	s_add_u32 s44, s44, 0xb0000
	s_addc_u32 s45, s45, 0
	s_add_i32 s8, s65, s50
	s_mov_b32 m0, s8
	ds_read_b128 v[204:207], v166 offset:20480
	global_load_lds_dwordx4 v138, s[44:45]
	s_add_i32 m0, s8, 0x2000
	ds_read_b128 v[208:211], v166 offset:21504
	global_load_lds_dwordx4 v142, s[44:45]
	s_mov_b32 m0, s51
	ds_read_b128 v[212:215], v166 offset:22528
	global_load_lds_dwordx4 v136, s[46:47]
	s_mov_b32 m0, s52
	ds_read_b128 v[216:219], v166 offset:23552
	global_load_lds_dwordx4 v140, s[46:47]
	s_waitcnt vmcnt(8)
	s_waitcnt lgkmcnt(0)
	s_setprio 1
	s_barrier
	v_mfma_f32_16x16x32_bf16 v[60:63], v[132:135], v[188:191], v[60:63]
	v_mfma_f32_16x16x32_bf16 v[56:59], v[160:163], v[188:191], v[56:59]
	v_mfma_f32_16x16x32_bf16 v[44:47], v[132:135], v[196:199], v[44:47]
	v_mfma_f32_16x16x32_bf16 v[40:43], v[160:163], v[196:199], v[40:43]
	v_mfma_f32_16x16x32_bf16 v[28:31], v[132:135], v[204:207], v[28:31]
	v_mfma_f32_16x16x32_bf16 v[24:27], v[160:163], v[204:207], v[24:27]
	v_mfma_f32_16x16x32_bf16 v[12:15], v[132:135], v[212:215], v[12:15]
	v_mfma_f32_16x16x32_bf16 v[8:11], v[160:163], v[212:215], v[8:11]
	v_mfma_f32_16x16x32_bf16 v[60:63], v[156:159], v[192:195], v[60:63]
	v_mfma_f32_16x16x32_bf16 v[56:59], v[168:171], v[192:195], v[56:59]
	v_mfma_f32_16x16x32_bf16 v[44:47], v[156:159], v[200:203], v[44:47]
	v_mfma_f32_16x16x32_bf16 v[40:43], v[168:171], v[200:203], v[40:43]
	v_mfma_f32_16x16x32_bf16 v[28:31], v[156:159], v[208:211], v[28:31]
	v_mfma_f32_16x16x32_bf16 v[24:27], v[168:171], v[208:211], v[24:27]
	v_mfma_f32_16x16x32_bf16 v[12:15], v[156:159], v[216:219], v[12:15]
	v_mfma_f32_16x16x32_bf16 v[8:11], v[168:171], v[216:219], v[8:11]
	s_setprio 0
	s_setprio 1
	v_mfma_f32_16x16x32_bf16 v[52:55], v[172:175], v[188:191], v[52:55]
	v_mfma_f32_16x16x32_bf16 v[48:51], v[180:183], v[188:191], v[48:51]
	v_mfma_f32_16x16x32_bf16 v[36:39], v[172:175], v[196:199], v[36:39]
	v_mfma_f32_16x16x32_bf16 v[32:35], v[180:183], v[196:199], v[32:35]
	v_mfma_f32_16x16x32_bf16 v[20:23], v[172:175], v[204:207], v[20:23]
	v_mfma_f32_16x16x32_bf16 v[16:19], v[180:183], v[204:207], v[16:19]
	v_mfma_f32_16x16x32_bf16 v[4:7], v[172:175], v[212:215], v[4:7]
	v_mfma_f32_16x16x32_bf16 v[0:3], v[180:183], v[212:215], v[0:3]
	v_mfma_f32_16x16x32_bf16 v[52:55], v[176:179], v[192:195], v[52:55]
	v_mfma_f32_16x16x32_bf16 v[48:51], v[184:187], v[192:195], v[48:51]
	v_mfma_f32_16x16x32_bf16 v[36:39], v[176:179], v[200:203], v[36:39]
	v_mfma_f32_16x16x32_bf16 v[32:35], v[184:187], v[200:203], v[32:35]
	v_mfma_f32_16x16x32_bf16 v[20:23], v[176:179], v[208:211], v[20:23]
	v_mfma_f32_16x16x32_bf16 v[16:19], v[184:187], v[208:211], v[16:19]
	v_mfma_f32_16x16x32_bf16 v[4:7], v[176:179], v[216:219], v[4:7]
	v_mfma_f32_16x16x32_bf16 v[0:3], v[184:187], v[216:219], v[0:3]
	s_setprio 0
	s_barrier
	s_add_i32 s8, 0, 0x18000
	v_add_u32_e32 v167, s8, v165
	s_add_i32 s79, 0, 0x1c000
	ds_read_b128 v[132:135], v167
	ds_read_b128 v[156:159], v167 offset:1024
	ds_read_b128 v[160:163], v167 offset:2048
	ds_read_b128 v[168:171], v167 offset:3072
	v_add_u32_e32 v167, s79, v165
	ds_read_b128 v[172:175], v167
	ds_read_b128 v[176:179], v167 offset:1024
	ds_read_b128 v[180:183], v167 offset:2048
	ds_read_b128 v[184:187], v167 offset:3072
	s_add_u32 s44, s46, 0xb0000
	s_addc_u32 s45, s47, 0
	s_mov_b32 m0, s53
	ds_read_b128 v[188:191], v166 offset:32768
	ds_read_b128 v[192:195], v166 offset:33792
	ds_read_b128 v[196:199], v166 offset:34816
	ds_read_b128 v[200:203], v166 offset:35840
	ds_read_b128 v[204:207], v166 offset:36864
	ds_read_b128 v[208:211], v166 offset:37888
	ds_read_b128 v[212:215], v166 offset:38912
	global_load_lds_dwordx4 v136, s[44:45]
	s_mov_b32 m0, s54
	ds_read_b128 v[216:219], v166 offset:39936
	global_load_lds_dwordx4 v140, s[44:45]
	s_waitcnt vmcnt(8)
	s_waitcnt lgkmcnt(0)
	s_setprio 1
	s_barrier
	v_mfma_f32_16x16x32_bf16 v[124:127], v[132:135], v[188:191], v[124:127]
	v_mfma_f32_16x16x32_bf16 v[120:123], v[160:163], v[188:191], v[120:123]
	v_mfma_f32_16x16x32_bf16 v[108:111], v[132:135], v[196:199], v[108:111]
	v_mfma_f32_16x16x32_bf16 v[104:107], v[160:163], v[196:199], v[104:107]
	v_mfma_f32_16x16x32_bf16 v[92:95], v[132:135], v[204:207], v[92:95]
	v_mfma_f32_16x16x32_bf16 v[88:91], v[160:163], v[204:207], v[88:91]
	v_mfma_f32_16x16x32_bf16 v[76:79], v[132:135], v[212:215], v[76:79]
	v_mfma_f32_16x16x32_bf16 v[72:75], v[160:163], v[212:215], v[72:75]
	v_mfma_f32_16x16x32_bf16 v[124:127], v[156:159], v[192:195], v[124:127]
	v_mfma_f32_16x16x32_bf16 v[120:123], v[168:171], v[192:195], v[120:123]
	v_mfma_f32_16x16x32_bf16 v[108:111], v[156:159], v[200:203], v[108:111]
	v_mfma_f32_16x16x32_bf16 v[104:107], v[168:171], v[200:203], v[104:107]
	v_mfma_f32_16x16x32_bf16 v[92:95], v[156:159], v[208:211], v[92:95]
	v_mfma_f32_16x16x32_bf16 v[88:91], v[168:171], v[208:211], v[88:91]
	v_mfma_f32_16x16x32_bf16 v[76:79], v[156:159], v[216:219], v[76:79]
	v_mfma_f32_16x16x32_bf16 v[72:75], v[168:171], v[216:219], v[72:75]
	s_setprio 0
	s_setprio 1
	v_mfma_f32_16x16x32_bf16 v[116:119], v[172:175], v[188:191], v[116:119]
	v_mfma_f32_16x16x32_bf16 v[112:115], v[180:183], v[188:191], v[112:115]
	v_mfma_f32_16x16x32_bf16 v[100:103], v[172:175], v[196:199], v[100:103]
	v_mfma_f32_16x16x32_bf16 v[96:99], v[180:183], v[196:199], v[96:99]
	v_mfma_f32_16x16x32_bf16 v[84:87], v[172:175], v[204:207], v[84:87]
	v_mfma_f32_16x16x32_bf16 v[80:83], v[180:183], v[204:207], v[80:83]
	v_mfma_f32_16x16x32_bf16 v[68:71], v[172:175], v[212:215], v[68:71]
	v_mfma_f32_16x16x32_bf16 v[64:67], v[180:183], v[212:215], v[64:67]
	v_mfma_f32_16x16x32_bf16 v[116:119], v[176:179], v[192:195], v[116:119]
	v_mfma_f32_16x16x32_bf16 v[112:115], v[184:187], v[192:195], v[112:115]
	v_mfma_f32_16x16x32_bf16 v[100:103], v[176:179], v[200:203], v[100:103]
	v_mfma_f32_16x16x32_bf16 v[96:99], v[184:187], v[200:203], v[96:99]
	v_mfma_f32_16x16x32_bf16 v[84:87], v[176:179], v[208:211], v[84:87]
	v_mfma_f32_16x16x32_bf16 v[80:83], v[184:187], v[208:211], v[80:83]
	v_mfma_f32_16x16x32_bf16 v[68:71], v[176:179], v[216:219], v[68:71]
	v_mfma_f32_16x16x32_bf16 v[64:67], v[184:187], v[216:219], v[64:67]
	s_setprio 0
	s_barrier
	s_add_i32 s8, s8, s50
	s_mov_b32 m0, s8
	ds_read_b128 v[188:191], v166 offset:49152
	ds_read_b128 v[192:195], v166 offset:50176
	ds_read_b128 v[196:199], v166 offset:51200
	global_load_lds_dwordx4 v138, s[40:41]
	s_add_i32 m0, s8, 0x2000
	ds_read_b128 v[200:203], v166 offset:52224
	global_load_lds_dwordx4 v142, s[40:41]
	s_add_u32 s40, s40, 0xb0000
	s_addc_u32 s41, s41, 0
	s_add_i32 s8, s79, s50
	s_mov_b32 m0, s8
	ds_read_b128 v[204:207], v166 offset:53248
	global_load_lds_dwordx4 v138, s[40:41]
	s_add_i32 m0, s8, 0x2000
	ds_read_b128 v[208:211], v166 offset:54272
	global_load_lds_dwordx4 v142, s[40:41]
	s_mov_b32 m0, s60
	ds_read_b128 v[212:215], v166 offset:55296
	global_load_lds_dwordx4 v136, s[38:39]
	s_mov_b32 m0, s61
	ds_read_b128 v[216:219], v166 offset:56320
	global_load_lds_dwordx4 v140, s[38:39]
	s_waitcnt vmcnt(8)
	s_waitcnt lgkmcnt(0)
	s_setprio 1
	s_barrier
	v_mfma_f32_16x16x32_bf16 v[60:63], v[132:135], v[188:191], v[60:63]
	v_mfma_f32_16x16x32_bf16 v[56:59], v[160:163], v[188:191], v[56:59]
	v_mfma_f32_16x16x32_bf16 v[44:47], v[132:135], v[196:199], v[44:47]
	v_mfma_f32_16x16x32_bf16 v[40:43], v[160:163], v[196:199], v[40:43]
	v_mfma_f32_16x16x32_bf16 v[28:31], v[132:135], v[204:207], v[28:31]
	v_mfma_f32_16x16x32_bf16 v[24:27], v[160:163], v[204:207], v[24:27]
	v_mfma_f32_16x16x32_bf16 v[12:15], v[132:135], v[212:215], v[12:15]
	v_mfma_f32_16x16x32_bf16 v[8:11], v[160:163], v[212:215], v[8:11]
	v_mfma_f32_16x16x32_bf16 v[60:63], v[156:159], v[192:195], v[60:63]
	v_mfma_f32_16x16x32_bf16 v[56:59], v[168:171], v[192:195], v[56:59]
	v_mfma_f32_16x16x32_bf16 v[44:47], v[156:159], v[200:203], v[44:47]
	v_mfma_f32_16x16x32_bf16 v[40:43], v[168:171], v[200:203], v[40:43]
	v_mfma_f32_16x16x32_bf16 v[28:31], v[156:159], v[208:211], v[28:31]
	v_mfma_f32_16x16x32_bf16 v[24:27], v[168:171], v[208:211], v[24:27]
	v_mfma_f32_16x16x32_bf16 v[12:15], v[156:159], v[216:219], v[12:15]
	v_mfma_f32_16x16x32_bf16 v[8:11], v[168:171], v[216:219], v[8:11]
	s_setprio 0
	s_setprio 1
	v_mfma_f32_16x16x32_bf16 v[52:55], v[172:175], v[188:191], v[52:55]
	v_mfma_f32_16x16x32_bf16 v[48:51], v[180:183], v[188:191], v[48:51]
	v_mfma_f32_16x16x32_bf16 v[36:39], v[172:175], v[196:199], v[36:39]
	v_mfma_f32_16x16x32_bf16 v[32:35], v[180:183], v[196:199], v[32:35]
	v_mfma_f32_16x16x32_bf16 v[20:23], v[172:175], v[204:207], v[20:23]
	v_mfma_f32_16x16x32_bf16 v[16:19], v[180:183], v[204:207], v[16:19]
	v_mfma_f32_16x16x32_bf16 v[4:7], v[172:175], v[212:215], v[4:7]
	v_mfma_f32_16x16x32_bf16 v[0:3], v[180:183], v[212:215], v[0:3]
	v_mfma_f32_16x16x32_bf16 v[52:55], v[176:179], v[192:195], v[52:55]
	v_mfma_f32_16x16x32_bf16 v[48:51], v[184:187], v[192:195], v[48:51]
	v_mfma_f32_16x16x32_bf16 v[36:39], v[176:179], v[200:203], v[36:39]
	v_mfma_f32_16x16x32_bf16 v[32:35], v[184:187], v[200:203], v[32:35]
	v_mfma_f32_16x16x32_bf16 v[20:23], v[176:179], v[208:211], v[20:23]
	v_mfma_f32_16x16x32_bf16 v[16:19], v[184:187], v[208:211], v[16:19]
	v_mfma_f32_16x16x32_bf16 v[4:7], v[176:179], v[216:219], v[4:7]
	v_mfma_f32_16x16x32_bf16 v[0:3], v[184:187], v[216:219], v[0:3]
	s_setprio 0
	s_barrier
	s_add_i32 s8, s78, 2
	s_add_u32 s36, s36, 0x100
	s_addc_u32 s37, s37, 0
	s_cmp_gt_u32 s78, 41
	s_mov_b32 s78, s8
	s_cbranch_scc1 .LBB0_903

.LBB0_995:
	ds_read_b128 v[0:3], v145
	ds_read_b128 v[4:7], v145 offset:1024
	ds_read_b128 v[8:11], v145 offset:2048
	ds_read_b128 v[12:15], v145 offset:3072
	ds_read_b128 v[16:19], v146
	ds_read_b128 v[20:23], v146 offset:1024
	ds_read_b128 v[24:27], v146 offset:2048
	ds_read_b128 v[28:31], v146 offset:3072
	s_ashr_i32 s25, s24, 31
	s_lshl_b64 s[28:29], s[24:25], 17
	s_add_u32 s28, s44, s28
	s_addc_u32 s29, s45, s29
	s_and_b64 s[30:31], s[0:1], exec
	s_cselect_b32 s43, s29, s37
	s_cselect_b32 s42, s28, s36
	s_ashr_i32 s23, s22, 31
	s_lshl_b64 s[30:31], s[22:23], 17
	s_add_u32 s30, s46, s30
	s_addc_u32 s31, s47, s31
	s_and_b64 s[40:41], s[0:1], exec
	s_cselect_b32 s41, s31, s39
	s_cselect_b32 s40, s30, s38
	s_add_u32 s64, s36, 0x10080
	s_addc_u32 s65, s37, 0
	s_mov_b32 m0, s56
	ds_read_b128 v[32:35], v147
	ds_read_b128 v[36:39], v147 offset:1024
	ds_read_b128 v[40:43], v147 offset:2048
	ds_read_b128 v[44:47], v147 offset:3072
	ds_read_b128 v[48:51], v147 offset:4096
	ds_read_b128 v[52:55], v147 offset:5120
	ds_read_b128 v[56:59], v147 offset:6144
	ds_read_b128 v[60:63], v147 offset:7168
	global_load_lds_dwordx4 v128, s[64:65]
	s_mov_b32 m0, s57
	s_nop 0
	global_load_lds_dwordx4 v132, s[64:65]
	s_waitcnt vmcnt(8)
	s_waitcnt lgkmcnt(0)
	s_setprio 1
	s_barrier
	v_mfma_f32_16x16x32_bf16 v[64:67], v[0:3], v[32:35], 0
	v_mfma_f32_16x16x32_bf16 v[68:71], v[8:11], v[32:35], 0
	v_mfma_f32_16x16x32_bf16 v[72:75], v[0:3], v[40:43], 0
	v_mfma_f32_16x16x32_bf16 v[76:79], v[8:11], v[40:43], 0
	v_mfma_f32_16x16x32_bf16 v[80:83], v[0:3], v[48:51], 0
	v_mfma_f32_16x16x32_bf16 v[84:87], v[8:11], v[48:51], 0
	v_mfma_f32_16x16x32_bf16 v[88:91], v[0:3], v[56:59], 0
	v_mfma_f32_16x16x32_bf16 v[92:95], v[8:11], v[56:59], 0
	v_mfma_f32_16x16x32_bf16 v[64:67], v[4:7], v[36:39], v[64:67]
	v_mfma_f32_16x16x32_bf16 v[68:71], v[12:15], v[36:39], v[68:71]
	v_mfma_f32_16x16x32_bf16 v[72:75], v[4:7], v[44:47], v[72:75]
	v_mfma_f32_16x16x32_bf16 v[76:79], v[12:15], v[44:47], v[76:79]
	v_mfma_f32_16x16x32_bf16 v[80:83], v[4:7], v[52:55], v[80:83]
	v_mfma_f32_16x16x32_bf16 v[84:87], v[12:15], v[52:55], v[84:87]
	v_mfma_f32_16x16x32_bf16 v[88:91], v[4:7], v[60:63], v[88:91]
	v_mfma_f32_16x16x32_bf16 v[92:95], v[12:15], v[60:63], v[92:95]
	s_setprio 0
	s_setprio 1
	v_mfma_f32_16x16x32_bf16 v[96:99], v[16:19], v[32:35], 0
	v_mfma_f32_16x16x32_bf16 v[32:35], v[24:27], v[32:35], 0
	v_mfma_f32_16x16x32_bf16 v[96:99], v[20:23], v[36:39], v[96:99]
	v_mfma_f32_16x16x32_bf16 v[32:35], v[28:31], v[36:39], v[32:35]
	v_mfma_f32_16x16x32_bf16 v[36:39], v[16:19], v[40:43], 0
	v_mfma_f32_16x16x32_bf16 v[40:43], v[24:27], v[40:43], 0
	v_mfma_f32_16x16x32_bf16 v[36:39], v[20:23], v[44:47], v[36:39]
	v_mfma_f32_16x16x32_bf16 v[40:43], v[28:31], v[44:47], v[40:43]
	v_mfma_f32_16x16x32_bf16 v[44:47], v[16:19], v[48:51], 0
	v_mfma_f32_16x16x32_bf16 v[48:51], v[24:27], v[48:51], 0
	v_mfma_f32_16x16x32_bf16 v[44:47], v[20:23], v[52:55], v[44:47]
	v_mfma_f32_16x16x32_bf16 v[48:51], v[28:31], v[52:55], v[48:51]
	v_mfma_f32_16x16x32_bf16 v[52:55], v[16:19], v[56:59], 0
	v_mfma_f32_16x16x32_bf16 v[56:59], v[24:27], v[56:59], 0
	v_mfma_f32_16x16x32_bf16 v[52:55], v[20:23], v[60:63], v[52:55]
	v_mfma_f32_16x16x32_bf16 v[56:59], v[28:31], v[60:63], v[56:59]
	s_setprio 0
	s_barrier
	v_lshl_add_u64 v[214:215], s[38:39], 0, v[130:131]
	s_mov_b32 m0, s58
	v_lshl_add_u64 v[150:151], v[214:215], 0, s[18:19]
	v_lshl_add_u64 v[216:217], s[38:39], 0, v[134:135]
	s_add_u32 s64, s38, 0x10100
	ds_read_b128 v[60:63], v147 offset:16384
	ds_read_b128 v[100:103], v147 offset:17408
	ds_read_b128 v[104:107], v147 offset:18432
	ds_read_b128 v[108:111], v147 offset:19456
	ds_read_b128 v[112:115], v147 offset:20480
	ds_read_b128 v[116:119], v147 offset:21504
	ds_read_b128 v[120:123], v147 offset:22528
	ds_read_b128 v[124:127], v147 offset:23552
	global_load_lds_dwordx4 v[150:151], off
	v_lshl_add_u64 v[150:151], v[216:217], 0, s[18:19]
	s_mov_b32 m0, s59
	s_addc_u32 s65, s39, 0
	global_load_lds_dwordx4 v[150:151], off
	s_mov_b32 m0, s60
	v_lshl_add_u64 v[218:219], s[36:37], 0, v[128:129]
	global_load_lds_dwordx4 v130, s[64:65]
	s_mov_b32 m0, s61
	v_lshl_add_u64 v[220:221], s[36:37], 0, v[132:133]
	global_load_lds_dwordx4 v134, s[64:65]
	v_lshl_add_u64 v[150:151], v[218:219], 0, s[18:19]
	s_mov_b32 m0, s49
	s_nop 0
	global_load_lds_dwordx4 v[150:151], off
	v_lshl_add_u64 v[150:151], v[220:221], 0, s[18:19]
	s_mov_b32 m0, s50
	s_nop 0
	global_load_lds_dwordx4 v[150:151], off
	s_waitcnt vmcnt(8)
	s_waitcnt lgkmcnt(0)
	s_setprio 1
	s_barrier
	v_mfma_f32_16x16x32_bf16 v[150:153], v[0:3], v[60:63], 0
	v_mfma_f32_16x16x32_bf16 v[158:161], v[0:3], v[104:107], 0
	v_mfma_f32_16x16x32_bf16 v[166:169], v[0:3], v[112:115], 0
	v_mfma_f32_16x16x32_bf16 v[0:3], v[0:3], v[120:123], 0
	v_mfma_f32_16x16x32_bf16 v[150:153], v[4:7], v[100:103], v[150:153]
	v_mfma_f32_16x16x32_bf16 v[158:161], v[4:7], v[108:111], v[158:161]
	v_mfma_f32_16x16x32_bf16 v[166:169], v[4:7], v[116:119], v[166:169]
	v_mfma_f32_16x16x32_bf16 v[0:3], v[4:7], v[124:127], v[0:3]
	v_mfma_f32_16x16x32_bf16 v[4:7], v[8:11], v[120:123], 0
	v_mfma_f32_16x16x32_bf16 v[154:157], v[8:11], v[60:63], 0
	v_mfma_f32_16x16x32_bf16 v[162:165], v[8:11], v[104:107], 0
	v_mfma_f32_16x16x32_bf16 v[170:173], v[8:11], v[112:115], 0
	v_mfma_f32_16x16x32_bf16 v[4:7], v[12:15], v[124:127], v[4:7]
	v_mfma_f32_16x16x32_bf16 v[154:157], v[12:15], v[100:103], v[154:157]
	v_mfma_f32_16x16x32_bf16 v[162:165], v[12:15], v[108:111], v[162:165]
	v_mfma_f32_16x16x32_bf16 v[170:173], v[12:15], v[116:119], v[170:173]
	s_setprio 0
	s_setprio 1
	v_mfma_f32_16x16x32_bf16 v[8:11], v[16:19], v[60:63], 0
	v_mfma_f32_16x16x32_bf16 v[12:15], v[24:27], v[60:63], 0
	v_mfma_f32_16x16x32_bf16 v[8:11], v[20:23], v[100:103], v[8:11]
	v_mfma_f32_16x16x32_bf16 v[12:15], v[28:31], v[100:103], v[12:15]
	v_mfma_f32_16x16x32_bf16 v[60:63], v[16:19], v[104:107], 0
	v_mfma_f32_16x16x32_bf16 v[100:103], v[24:27], v[104:107], 0
	v_mfma_f32_16x16x32_bf16 v[104:107], v[16:19], v[112:115], 0
	v_mfma_f32_16x16x32_bf16 v[16:19], v[16:19], v[120:123], 0
	v_mfma_f32_16x16x32_bf16 v[60:63], v[20:23], v[108:111], v[60:63]
	v_mfma_f32_16x16x32_bf16 v[100:103], v[28:31], v[108:111], v[100:103]
	v_mfma_f32_16x16x32_bf16 v[104:107], v[20:23], v[116:119], v[104:107]
	v_mfma_f32_16x16x32_bf16 v[108:111], v[24:27], v[112:115], 0
	v_mfma_f32_16x16x32_bf16 v[16:19], v[20:23], v[124:127], v[16:19]
	v_mfma_f32_16x16x32_bf16 v[20:23], v[24:27], v[120:123], 0
	v_mfma_f32_16x16x32_bf16 v[108:111], v[28:31], v[116:119], v[108:111]
	v_mfma_f32_16x16x32_bf16 v[20:23], v[28:31], v[124:127], v[20:23]
	s_setprio 0
	s_barrier
	s_add_i32 s25, 0, 0x1c000
	v_add_u32_e32 v149, s25, v144
	ds_read_b128 v[24:27], v148
	ds_read_b128 v[28:31], v148 offset:1024
	ds_read_b128 v[112:115], v148 offset:2048
	ds_read_b128 v[116:119], v148 offset:3072
	ds_read_b128 v[120:123], v149
	ds_read_b128 v[124:127], v149 offset:1024
	ds_read_b128 v[174:177], v149 offset:2048
	ds_read_b128 v[178:181], v149 offset:3072
	s_add_u32 s64, s36, 0x10100
	s_addc_u32 s65, s37, 0
	s_mov_b32 m0, s51
	ds_read_b128 v[182:185], v147 offset:32768
	ds_read_b128 v[186:189], v147 offset:33792
	ds_read_b128 v[190:193], v147 offset:34816
	ds_read_b128 v[194:197], v147 offset:35840
	ds_read_b128 v[198:201], v147 offset:36864
	ds_read_b128 v[202:205], v147 offset:37888
	ds_read_b128 v[206:209], v147 offset:38912
	ds_read_b128 v[210:213], v147 offset:39936
	global_load_lds_dwordx4 v128, s[64:65]
	s_mov_b32 m0, s52
	s_nop 0
	global_load_lds_dwordx4 v132, s[64:65]
	s_waitcnt vmcnt(8)
	s_waitcnt lgkmcnt(0)
	s_setprio 1
	s_barrier
	v_mfma_f32_16x16x32_bf16 v[64:67], v[24:27], v[182:185], v[64:67]
	v_mfma_f32_16x16x32_bf16 v[68:71], v[112:115], v[182:185], v[68:71]
	v_mfma_f32_16x16x32_bf16 v[72:75], v[24:27], v[190:193], v[72:75]
	v_mfma_f32_16x16x32_bf16 v[76:79], v[112:115], v[190:193], v[76:79]
	v_mfma_f32_16x16x32_bf16 v[80:83], v[24:27], v[198:201], v[80:83]
	v_mfma_f32_16x16x32_bf16 v[84:87], v[112:115], v[198:201], v[84:87]
	v_mfma_f32_16x16x32_bf16 v[88:91], v[24:27], v[206:209], v[88:91]
	v_mfma_f32_16x16x32_bf16 v[92:95], v[112:115], v[206:209], v[92:95]
	v_mfma_f32_16x16x32_bf16 v[64:67], v[28:31], v[186:189], v[64:67]
	v_mfma_f32_16x16x32_bf16 v[68:71], v[116:119], v[186:189], v[68:71]
	v_mfma_f32_16x16x32_bf16 v[72:75], v[28:31], v[194:197], v[72:75]
	v_mfma_f32_16x16x32_bf16 v[76:79], v[116:119], v[194:197], v[76:79]
	v_mfma_f32_16x16x32_bf16 v[80:83], v[28:31], v[202:205], v[80:83]
	v_mfma_f32_16x16x32_bf16 v[84:87], v[116:119], v[202:205], v[84:87]
	v_mfma_f32_16x16x32_bf16 v[88:91], v[28:31], v[210:213], v[88:91]
	v_mfma_f32_16x16x32_bf16 v[92:95], v[116:119], v[210:213], v[92:95]
	s_setprio 0
	s_setprio 1
	v_mfma_f32_16x16x32_bf16 v[96:99], v[120:123], v[182:185], v[96:99]
	v_mfma_f32_16x16x32_bf16 v[32:35], v[174:177], v[182:185], v[32:35]
	v_mfma_f32_16x16x32_bf16 v[36:39], v[120:123], v[190:193], v[36:39]
	v_mfma_f32_16x16x32_bf16 v[40:43], v[174:177], v[190:193], v[40:43]
	v_mfma_f32_16x16x32_bf16 v[44:47], v[120:123], v[198:201], v[44:47]
	v_mfma_f32_16x16x32_bf16 v[48:51], v[174:177], v[198:201], v[48:51]
	v_mfma_f32_16x16x32_bf16 v[52:55], v[120:123], v[206:209], v[52:55]
	v_mfma_f32_16x16x32_bf16 v[56:59], v[174:177], v[206:209], v[56:59]
	v_mfma_f32_16x16x32_bf16 v[96:99], v[124:127], v[186:189], v[96:99]
	v_mfma_f32_16x16x32_bf16 v[32:35], v[178:181], v[186:189], v[32:35]
	v_mfma_f32_16x16x32_bf16 v[36:39], v[124:127], v[194:197], v[36:39]
	v_mfma_f32_16x16x32_bf16 v[40:43], v[178:181], v[194:197], v[40:43]
	v_mfma_f32_16x16x32_bf16 v[44:47], v[124:127], v[202:205], v[44:47]
	v_mfma_f32_16x16x32_bf16 v[48:51], v[178:181], v[202:205], v[48:51]
	v_mfma_f32_16x16x32_bf16 v[52:55], v[124:127], v[210:213], v[52:55]
	v_mfma_f32_16x16x32_bf16 v[56:59], v[178:181], v[210:213], v[56:59]
	s_setprio 0
	s_barrier
	s_add_i32 s63, s62, s48
	s_add_i32 s23, s63, 0x2000
	v_lshl_add_u64 v[214:215], v[214:215], 0, s[20:21]
	s_mov_b32 m0, s63
	s_add_u32 s38, s38, 0x10180
	ds_read_b128 v[182:185], v147 offset:49152
	ds_read_b128 v[186:189], v147 offset:50176
	ds_read_b128 v[190:193], v147 offset:51200
	ds_read_b128 v[194:197], v147 offset:52224
	ds_read_b128 v[198:201], v147 offset:53248
	ds_read_b128 v[202:205], v147 offset:54272
	ds_read_b128 v[206:209], v147 offset:55296
	ds_read_b128 v[210:213], v147 offset:56320
	global_load_lds_dwordx4 v[214:215], off
	v_lshl_add_u64 v[214:215], v[216:217], 0, s[20:21]
	s_mov_b32 m0, s23
	s_addc_u32 s39, s39, 0
	s_add_i32 s25, s25, s48
	global_load_lds_dwordx4 v[214:215], off
	s_mov_b32 m0, s25
	s_nop 0
	global_load_lds_dwordx4 v130, s[38:39]
	v_lshl_add_u64 v[214:215], s[38:39], 0, v[134:135]
	s_add_i32 s38, s25, 0x2000
	s_mov_b32 m0, s38
	s_nop 0
	global_load_lds_dwordx4 v[214:215], off
	v_lshl_add_u64 v[214:215], v[218:219], 0, s[20:21]
	s_mov_b32 m0, s53
	s_nop 0
	global_load_lds_dwordx4 v[214:215], off
	v_lshl_add_u64 v[214:215], v[220:221], 0, s[20:21]
	s_mov_b32 m0, s54
	s_nop 0
	global_load_lds_dwordx4 v[214:215], off
	s_waitcnt vmcnt(8)
	s_waitcnt lgkmcnt(0)
	s_setprio 1
	s_barrier
	v_mfma_f32_16x16x32_bf16 v[0:3], v[24:27], v[206:209], v[0:3]
	v_mfma_f32_16x16x32_bf16 v[4:7], v[112:115], v[206:209], v[4:7]
	v_mfma_f32_16x16x32_bf16 v[150:153], v[24:27], v[182:185], v[150:153]
	v_mfma_f32_16x16x32_bf16 v[154:157], v[112:115], v[182:185], v[154:157]
	v_mfma_f32_16x16x32_bf16 v[158:161], v[24:27], v[190:193], v[158:161]
	v_mfma_f32_16x16x32_bf16 v[162:165], v[112:115], v[190:193], v[162:165]
	v_mfma_f32_16x16x32_bf16 v[166:169], v[24:27], v[198:201], v[166:169]
	v_mfma_f32_16x16x32_bf16 v[170:173], v[112:115], v[198:201], v[170:173]
	v_mfma_f32_16x16x32_bf16 v[0:3], v[28:31], v[210:213], v[0:3]
	v_mfma_f32_16x16x32_bf16 v[4:7], v[116:119], v[210:213], v[4:7]
	v_mfma_f32_16x16x32_bf16 v[150:153], v[28:31], v[186:189], v[150:153]
	v_mfma_f32_16x16x32_bf16 v[154:157], v[116:119], v[186:189], v[154:157]
	v_mfma_f32_16x16x32_bf16 v[158:161], v[28:31], v[194:197], v[158:161]
	v_mfma_f32_16x16x32_bf16 v[162:165], v[116:119], v[194:197], v[162:165]
	v_mfma_f32_16x16x32_bf16 v[166:169], v[28:31], v[202:205], v[166:169]
	v_mfma_f32_16x16x32_bf16 v[170:173], v[116:119], v[202:205], v[170:173]
	s_setprio 0
	s_setprio 1
	v_mfma_f32_16x16x32_bf16 v[8:11], v[120:123], v[182:185], v[8:11]
	v_mfma_f32_16x16x32_bf16 v[12:15], v[174:177], v[182:185], v[12:15]
	v_mfma_f32_16x16x32_bf16 v[24:27], v[120:123], v[190:193], v[60:63]
	v_mfma_f32_16x16x32_bf16 v[28:31], v[174:177], v[190:193], v[100:103]
	v_mfma_f32_16x16x32_bf16 v[60:63], v[120:123], v[198:201], v[104:107]
	v_mfma_f32_16x16x32_bf16 v[100:103], v[174:177], v[198:201], v[108:111]
	v_mfma_f32_16x16x32_bf16 v[16:19], v[120:123], v[206:209], v[16:19]
	v_mfma_f32_16x16x32_bf16 v[20:23], v[174:177], v[206:209], v[20:23]
	v_mfma_f32_16x16x32_bf16 v[8:11], v[124:127], v[186:189], v[8:11]
	v_mfma_f32_16x16x32_bf16 v[12:15], v[178:181], v[186:189], v[12:15]
	v_mfma_f32_16x16x32_bf16 v[24:27], v[124:127], v[194:197], v[24:27]
	v_mfma_f32_16x16x32_bf16 v[28:31], v[178:181], v[194:197], v[28:31]
	v_mfma_f32_16x16x32_bf16 v[60:63], v[124:127], v[202:205], v[60:63]
	v_mfma_f32_16x16x32_bf16 v[100:103], v[178:181], v[202:205], v[100:103]
	v_mfma_f32_16x16x32_bf16 v[16:19], v[124:127], v[210:213], v[16:19]
	v_mfma_f32_16x16x32_bf16 v[20:23], v[178:181], v[210:213], v[20:23]
	s_setprio 0
	s_barrier
	ds_read_b128 v[104:107], v145
	ds_read_b128 v[108:111], v145 offset:1024
	ds_read_b128 v[112:115], v145 offset:2048
	ds_read_b128 v[116:119], v145 offset:3072
	ds_read_b128 v[120:123], v146
	ds_read_b128 v[124:127], v146 offset:1024
	ds_read_b128 v[174:177], v146 offset:2048
	ds_read_b128 v[178:181], v146 offset:3072
	s_add_u32 s36, s36, 0x10180
	s_addc_u32 s37, s37, 0
	s_mov_b32 m0, s56
	ds_read_b128 v[182:185], v147
	ds_read_b128 v[186:189], v147 offset:1024
	ds_read_b128 v[190:193], v147 offset:2048
	ds_read_b128 v[194:197], v147 offset:3072
	ds_read_b128 v[198:201], v147 offset:4096
	ds_read_b128 v[202:205], v147 offset:5120
	ds_read_b128 v[206:209], v147 offset:6144
	ds_read_b128 v[210:213], v147 offset:7168
	global_load_lds_dwordx4 v128, s[36:37]
	s_mov_b32 m0, s57
	s_nop 0
	global_load_lds_dwordx4 v132, s[36:37]
	s_waitcnt vmcnt(8)
	s_waitcnt lgkmcnt(0)
	s_setprio 1
	s_barrier
	v_mfma_f32_16x16x32_bf16 v[64:67], v[104:107], v[182:185], v[64:67]
	v_mfma_f32_16x16x32_bf16 v[68:71], v[112:115], v[182:185], v[68:71]
	v_mfma_f32_16x16x32_bf16 v[72:75], v[104:107], v[190:193], v[72:75]
	v_mfma_f32_16x16x32_bf16 v[76:79], v[112:115], v[190:193], v[76:79]
	v_mfma_f32_16x16x32_bf16 v[80:83], v[104:107], v[198:201], v[80:83]
	v_mfma_f32_16x16x32_bf16 v[84:87], v[112:115], v[198:201], v[84:87]
	v_mfma_f32_16x16x32_bf16 v[88:91], v[104:107], v[206:209], v[88:91]
	v_mfma_f32_16x16x32_bf16 v[92:95], v[112:115], v[206:209], v[92:95]
	v_mfma_f32_16x16x32_bf16 v[64:67], v[108:111], v[186:189], v[64:67]
	v_mfma_f32_16x16x32_bf16 v[68:71], v[116:119], v[186:189], v[68:71]
	v_mfma_f32_16x16x32_bf16 v[72:75], v[108:111], v[194:197], v[72:75]
	v_mfma_f32_16x16x32_bf16 v[76:79], v[116:119], v[194:197], v[76:79]
	v_mfma_f32_16x16x32_bf16 v[80:83], v[108:111], v[202:205], v[80:83]
	v_mfma_f32_16x16x32_bf16 v[84:87], v[116:119], v[202:205], v[84:87]
	v_mfma_f32_16x16x32_bf16 v[88:91], v[108:111], v[210:213], v[88:91]
	v_mfma_f32_16x16x32_bf16 v[92:95], v[116:119], v[210:213], v[92:95]
	s_setprio 0
	s_setprio 1
	v_mfma_f32_16x16x32_bf16 v[32:35], v[174:177], v[182:185], v[32:35]
	v_mfma_f32_16x16x32_bf16 v[96:99], v[120:123], v[182:185], v[96:99]
	v_mfma_f32_16x16x32_bf16 v[182:185], v[178:181], v[186:189], v[32:35]
	v_mfma_f32_16x16x32_bf16 v[32:35], v[120:123], v[190:193], v[36:39]
	v_mfma_f32_16x16x32_bf16 v[214:217], v[124:127], v[186:189], v[96:99]
	v_mfma_f32_16x16x32_bf16 v[186:189], v[124:127], v[194:197], v[32:35]
	v_mfma_f32_16x16x32_bf16 v[32:35], v[174:177], v[190:193], v[40:43]
	v_mfma_f32_16x16x32_bf16 v[40:43], v[178:181], v[194:197], v[32:35]
	v_mfma_f32_16x16x32_bf16 v[32:35], v[120:123], v[198:201], v[44:47]
	v_mfma_f32_16x16x32_bf16 v[44:47], v[124:127], v[202:205], v[32:35]
	v_mfma_f32_16x16x32_bf16 v[32:35], v[174:177], v[198:201], v[48:51]
	v_mfma_f32_16x16x32_bf16 v[48:51], v[178:181], v[202:205], v[32:35]
	v_mfma_f32_16x16x32_bf16 v[32:35], v[120:123], v[206:209], v[52:55]
	v_mfma_f32_16x16x32_bf16 v[52:55], v[124:127], v[210:213], v[32:35]
	v_mfma_f32_16x16x32_bf16 v[32:35], v[174:177], v[206:209], v[56:59]
	v_mfma_f32_16x16x32_bf16 v[56:59], v[178:181], v[210:213], v[32:35]
	s_setprio 0
	s_barrier
	s_mov_b32 m0, s58
	v_lshl_add_u64 v[250:251], s[40:41], 0, v[130:131]
	s_add_u32 s36, s40, 0x10000
	s_nop 1
	ds_read_b128 v[32:35], v147 offset:16384
	ds_read_b128 v[36:39], v147 offset:17408
	ds_read_b128 v[96:99], v147 offset:18432
	ds_read_b128 v[190:193], v147 offset:19456
	ds_read_b128 v[194:197], v147 offset:20480
	ds_read_b128 v[198:201], v147 offset:21504
	ds_read_b128 v[202:205], v147 offset:22528
	ds_read_b128 v[206:209], v147 offset:23552
	global_load_lds_dwordx4 v[250:251], off
	v_lshl_add_u64 v[252:253], s[40:41], 0, v[134:135]
	s_mov_b32 m0, s59
	s_addc_u32 s37, s41, 0
	global_load_lds_dwordx4 v[252:253], off
	s_mov_b32 m0, s60
	v_lshl_add_u64 v[138:139], s[42:43], 0, v[128:129]
	global_load_lds_dwordx4 v130, s[36:37]
	s_mov_b32 m0, s61
	v_lshl_add_u64 v[140:141], s[42:43], 0, v[132:133]
	global_load_lds_dwordx4 v134, s[36:37]
	s_mov_b32 m0, s49
	s_nop 0
	global_load_lds_dwordx4 v[138:139], off
	s_mov_b32 m0, s50
	s_nop 0
	global_load_lds_dwordx4 v[140:141], off
	s_waitcnt vmcnt(8)
	s_waitcnt lgkmcnt(0)
	s_setprio 1
	s_barrier
	v_mfma_f32_16x16x32_bf16 v[0:3], v[104:107], v[202:205], v[0:3]
	v_mfma_f32_16x16x32_bf16 v[4:7], v[112:115], v[202:205], v[4:7]
	v_mfma_f32_16x16x32_bf16 v[150:153], v[104:107], v[32:35], v[150:153]
	v_mfma_f32_16x16x32_bf16 v[154:157], v[112:115], v[32:35], v[154:157]
	v_mfma_f32_16x16x32_bf16 v[158:161], v[104:107], v[96:99], v[158:161]
	v_mfma_f32_16x16x32_bf16 v[162:165], v[112:115], v[96:99], v[162:165]
	v_mfma_f32_16x16x32_bf16 v[166:169], v[104:107], v[194:197], v[166:169]
	v_mfma_f32_16x16x32_bf16 v[170:173], v[112:115], v[194:197], v[170:173]
	v_mfma_f32_16x16x32_bf16 v[0:3], v[108:111], v[206:209], v[0:3]
	v_mfma_f32_16x16x32_bf16 v[4:7], v[116:119], v[206:209], v[4:7]
	v_mfma_f32_16x16x32_bf16 v[150:153], v[108:111], v[36:39], v[150:153]
	v_mfma_f32_16x16x32_bf16 v[154:157], v[116:119], v[36:39], v[154:157]
	v_mfma_f32_16x16x32_bf16 v[158:161], v[108:111], v[190:193], v[158:161]
	v_mfma_f32_16x16x32_bf16 v[162:165], v[116:119], v[190:193], v[162:165]
	v_mfma_f32_16x16x32_bf16 v[166:169], v[108:111], v[198:201], v[166:169]
	v_mfma_f32_16x16x32_bf16 v[170:173], v[116:119], v[198:201], v[170:173]
	s_setprio 0
	s_setprio 1
	v_mfma_f32_16x16x32_bf16 v[8:11], v[120:123], v[32:35], v[8:11]
	v_mfma_f32_16x16x32_bf16 v[12:15], v[174:177], v[32:35], v[12:15]
	v_mfma_f32_16x16x32_bf16 v[24:27], v[120:123], v[96:99], v[24:27]
	v_mfma_f32_16x16x32_bf16 v[28:31], v[174:177], v[96:99], v[28:31]
	v_mfma_f32_16x16x32_bf16 v[32:35], v[120:123], v[194:197], v[60:63]
	v_mfma_f32_16x16x32_bf16 v[24:27], v[124:127], v[190:193], v[24:27]
	v_mfma_f32_16x16x32_bf16 v[28:31], v[178:181], v[190:193], v[28:31]
	v_mfma_f32_16x16x32_bf16 v[190:193], v[124:127], v[198:201], v[32:35]
	v_mfma_f32_16x16x32_bf16 v[32:35], v[174:177], v[194:197], v[100:103]
	v_mfma_f32_16x16x32_bf16 v[16:19], v[120:123], v[202:205], v[16:19]
	v_mfma_f32_16x16x32_bf16 v[8:11], v[124:127], v[36:39], v[8:11]
	v_mfma_f32_16x16x32_bf16 v[12:15], v[178:181], v[36:39], v[12:15]
	v_mfma_f32_16x16x32_bf16 v[194:197], v[178:181], v[198:201], v[32:35]
	v_mfma_f32_16x16x32_bf16 v[198:201], v[124:127], v[206:209], v[16:19]
	v_mfma_f32_16x16x32_bf16 v[16:19], v[174:177], v[202:205], v[20:23]
	v_mfma_f32_16x16x32_bf16 v[174:177], v[178:181], v[206:209], v[16:19]
	s_setprio 0
	s_barrier
	ds_read_b128 v[60:63], v148
	ds_read_b128 v[178:181], v148 offset:1024
	ds_read_b128 v[202:205], v148 offset:2048
	ds_read_b128 v[206:209], v148 offset:3072
	ds_read_b128 v[210:213], v149
	ds_read_b128 v[218:221], v149 offset:1024
	ds_read_b128 v[222:225], v149 offset:2048
	ds_read_b128 v[226:229], v149 offset:3072
	s_add_u32 s36, s42, 0x10000
	s_addc_u32 s37, s43, 0
	s_mov_b32 m0, s51
	ds_read_b128 v[16:19], v147 offset:32768
	ds_read_b128 v[20:23], v147 offset:33792
	ds_read_b128 v[108:111], v147 offset:34816
	ds_read_b128 v[230:233], v147 offset:35840
	ds_read_b128 v[234:237], v147 offset:36864
	ds_read_b128 v[238:241], v147 offset:37888
	ds_read_b128 v[242:245], v147 offset:38912
	ds_read_b128 v[246:249], v147 offset:39936
	global_load_lds_dwordx4 v128, s[36:37]
	s_mov_b32 m0, s52
	s_nop 0
	global_load_lds_dwordx4 v132, s[36:37]
	s_waitcnt vmcnt(8)
	s_waitcnt lgkmcnt(0)
	s_setprio 1
	s_barrier
	v_mfma_f32_16x16x32_bf16 v[32:35], v[60:63], v[16:19], v[64:67]
	v_mfma_f32_16x16x32_bf16 v[120:123], v[178:181], v[20:23], v[32:35]
	v_mfma_f32_16x16x32_bf16 v[32:35], v[202:205], v[16:19], v[68:71]
	v_mfma_f32_16x16x32_bf16 v[124:127], v[206:209], v[20:23], v[32:35]
	v_mfma_f32_16x16x32_bf16 v[32:35], v[60:63], v[108:111], v[72:75]
	v_mfma_f32_16x16x32_bf16 v[96:99], v[178:181], v[230:233], v[32:35]
	v_mfma_f32_16x16x32_bf16 v[32:35], v[202:205], v[108:111], v[76:79]
	v_mfma_f32_16x16x32_bf16 v[100:103], v[206:209], v[230:233], v[32:35]
	v_mfma_f32_16x16x32_bf16 v[32:35], v[60:63], v[234:237], v[80:83]
	v_mfma_f32_16x16x32_bf16 v[64:67], v[178:181], v[238:241], v[32:35]
	v_mfma_f32_16x16x32_bf16 v[32:35], v[202:205], v[234:237], v[84:87]
	v_mfma_f32_16x16x32_bf16 v[68:71], v[206:209], v[238:241], v[32:35]
	v_mfma_f32_16x16x32_bf16 v[32:35], v[60:63], v[242:245], v[88:91]
	v_mfma_f32_16x16x32_bf16 v[36:39], v[202:205], v[242:245], v[92:95]
	v_mfma_f32_16x16x32_bf16 v[32:35], v[178:181], v[246:249], v[32:35]
	v_mfma_f32_16x16x32_bf16 v[36:39], v[206:209], v[246:249], v[36:39]
	s_setprio 0
	s_setprio 1
	v_mfma_f32_16x16x32_bf16 v[72:75], v[210:213], v[16:19], v[214:217]
	v_mfma_f32_16x16x32_bf16 v[16:19], v[222:225], v[16:19], v[182:185]
	v_mfma_f32_16x16x32_bf16 v[116:119], v[226:229], v[20:23], v[16:19]
	v_mfma_f32_16x16x32_bf16 v[16:19], v[210:213], v[108:111], v[186:189]
	v_mfma_f32_16x16x32_bf16 v[104:107], v[218:221], v[230:233], v[16:19]
	v_mfma_f32_16x16x32_bf16 v[16:19], v[222:225], v[108:111], v[40:43]
	v_mfma_f32_16x16x32_bf16 v[108:111], v[226:229], v[230:233], v[16:19]
	v_mfma_f32_16x16x32_bf16 v[16:19], v[210:213], v[234:237], v[44:47]
	v_mfma_f32_16x16x32_bf16 v[112:115], v[218:221], v[20:23], v[72:75]
	v_mfma_f32_16x16x32_bf16 v[72:75], v[218:221], v[238:241], v[16:19]
	v_mfma_f32_16x16x32_bf16 v[16:19], v[222:225], v[234:237], v[48:51]
	v_mfma_f32_16x16x32_bf16 v[76:79], v[226:229], v[238:241], v[16:19]
	v_mfma_f32_16x16x32_bf16 v[16:19], v[210:213], v[242:245], v[52:55]
	v_mfma_f32_16x16x32_bf16 v[40:43], v[218:221], v[246:249], v[16:19]
	v_mfma_f32_16x16x32_bf16 v[16:19], v[222:225], v[242:245], v[56:59]
	v_mfma_f32_16x16x32_bf16 v[44:47], v[226:229], v[246:249], v[16:19]
	s_setprio 0
	s_barrier
	s_mov_b32 m0, s63
	s_nop 3
	v_lshl_add_u64 v[16:17], v[250:251], 0, s[12:13]
	s_add_u32 s36, s40, 0x10080
	ds_read_b128 v[56:59], v147 offset:49152
	ds_read_b128 v[92:95], v147 offset:50176
	ds_read_b128 v[182:185], v147 offset:51200
	ds_read_b128 v[186:189], v147 offset:52224
	ds_read_b128 v[214:217], v147 offset:53248
	ds_read_b128 v[230:233], v147 offset:54272
	ds_read_b128 v[234:237], v147 offset:55296
	ds_read_b128 v[238:241], v147 offset:56320
	global_load_lds_dwordx4 v[16:17], off
	v_lshl_add_u64 v[16:17], v[252:253], 0, s[12:13]
	s_mov_b32 m0, s23
	s_addc_u32 s37, s41, 0
	global_load_lds_dwordx4 v[16:17], off
	s_mov_b32 m0, s25
	s_nop 0
	global_load_lds_dwordx4 v130, s[36:37]
	s_mov_b32 m0, s38
	s_nop 0
	global_load_lds_dwordx4 v134, s[36:37]
	v_lshl_add_u64 v[16:17], v[138:139], 0, s[12:13]
	s_mov_b32 m0, s53
	s_nop 0
	global_load_lds_dwordx4 v[16:17], off
	v_lshl_add_u64 v[16:17], v[140:141], 0, s[12:13]
	s_mov_b32 m0, s54
	s_nop 0
	global_load_lds_dwordx4 v[16:17], off
	s_waitcnt vmcnt(8)
	s_waitcnt lgkmcnt(0)
	s_setprio 1
	s_barrier
	v_mfma_f32_16x16x32_bf16 v[16:19], v[60:63], v[56:59], v[150:153]
	v_mfma_f32_16x16x32_bf16 v[80:83], v[178:181], v[92:95], v[16:19]
	v_mfma_f32_16x16x32_bf16 v[16:19], v[202:205], v[56:59], v[154:157]
	v_mfma_f32_16x16x32_bf16 v[84:87], v[206:209], v[92:95], v[16:19]
	v_mfma_f32_16x16x32_bf16 v[16:19], v[60:63], v[182:185], v[158:161]
	v_mfma_f32_16x16x32_bf16 v[48:51], v[178:181], v[186:189], v[16:19]
	v_mfma_f32_16x16x32_bf16 v[16:19], v[202:205], v[182:185], v[162:165]
	v_mfma_f32_16x16x32_bf16 v[52:55], v[206:209], v[186:189], v[16:19]
	v_mfma_f32_16x16x32_bf16 v[16:19], v[60:63], v[214:217], v[166:169]
	v_mfma_f32_16x16x32_bf16 v[20:23], v[202:205], v[214:217], v[170:173]
	v_mfma_f32_16x16x32_bf16 v[0:3], v[60:63], v[234:237], v[0:3]
	v_mfma_f32_16x16x32_bf16 v[4:7], v[202:205], v[234:237], v[4:7]
	v_mfma_f32_16x16x32_bf16 v[16:19], v[178:181], v[230:233], v[16:19]
	v_mfma_f32_16x16x32_bf16 v[20:23], v[206:209], v[230:233], v[20:23]
	v_mfma_f32_16x16x32_bf16 v[0:3], v[178:181], v[238:241], v[0:3]
	v_mfma_f32_16x16x32_bf16 v[4:7], v[206:209], v[238:241], v[4:7]
	s_setprio 0
	s_setprio 1
	v_mfma_f32_16x16x32_bf16 v[8:11], v[210:213], v[56:59], v[8:11]
	v_mfma_f32_16x16x32_bf16 v[88:91], v[218:221], v[92:95], v[8:11]
	v_mfma_f32_16x16x32_bf16 v[8:11], v[222:225], v[56:59], v[12:15]
	v_mfma_f32_16x16x32_bf16 v[92:95], v[226:229], v[92:95], v[8:11]
	v_mfma_f32_16x16x32_bf16 v[8:11], v[210:213], v[182:185], v[24:27]
	v_mfma_f32_16x16x32_bf16 v[56:59], v[218:221], v[186:189], v[8:11]
	v_mfma_f32_16x16x32_bf16 v[8:11], v[222:225], v[182:185], v[28:31]
	v_mfma_f32_16x16x32_bf16 v[60:63], v[226:229], v[186:189], v[8:11]
	v_mfma_f32_16x16x32_bf16 v[8:11], v[210:213], v[214:217], v[190:193]
	v_mfma_f32_16x16x32_bf16 v[24:27], v[218:221], v[230:233], v[8:11]
	v_mfma_f32_16x16x32_bf16 v[8:11], v[222:225], v[214:217], v[194:197]
	v_mfma_f32_16x16x32_bf16 v[28:31], v[226:229], v[230:233], v[8:11]
	v_mfma_f32_16x16x32_bf16 v[8:11], v[210:213], v[234:237], v[198:201]
	v_mfma_f32_16x16x32_bf16 v[12:15], v[222:225], v[234:237], v[174:177]
	v_mfma_f32_16x16x32_bf16 v[8:11], v[218:221], v[238:241], v[8:11]
	v_mfma_f32_16x16x32_bf16 v[12:15], v[226:229], v[238:241], v[12:15]
	s_setprio 0
	s_barrier
	s_andn2_b64 vcc, exec, s[14:15]
	s_cbranch_vccnz .LBB0_997
	s_barrier

.LBB0_1017:
	s_add_u32 s65, s54, s6
	s_addc_u32 s66, s55, s7
	s_add_u32 s67, s56, s8
	s_addc_u32 s68, s57, s9
	s_ashr_i32 s19, s18, 31
	s_lshl_b64 s[6:7], s[18:19], 19
	s_add_u32 s20, s34, s6
	s_addc_u32 s21, s35, s7
	s_and_b64 s[8:9], s[0:1], exec
	s_cselect_b32 s19, s21, s29
	s_cselect_b32 s69, s20, s28
	s_ashr_i32 s17, s16, 31
	s_lshl_b64 s[8:9], s[16:17], 19
	s_add_u32 s22, s48, s8
	s_addc_u32 s23, s49, s9
	s_and_b64 s[30:31], s[0:1], exec
	s_cselect_b32 s17, s23, s27
	s_cselect_b32 s70, s22, s26
	s_add_u32 s30, s69, 0x80
	s_addc_u32 s31, s19, 0
	s_add_u32 s36, s70, 0x80
	s_addc_u32 s37, s17, 0
	v_lshl_add_u64 v[128:129], s[28:29], 0, v[196:197]
	v_lshl_add_u64 v[130:131], s[28:29], 0, v[198:199]
	s_mov_b32 s71, 0
	s_mov_b64 s[38:39], 0
	s_cmpk_eq_i32 s38, 0x700
	s_cselect_b64 s[44:45], -1, 0
	s_add_u32 s46, s28, s38
	s_addc_u32 s47, s29, s39
	s_add_u32 s73, s26, s38
	s_addc_u32 s72, s27, s39
	s_add_u32 s40, s46, 0x180
	s_addc_u32 s41, s47, 0
	s_add_u32 s42, s73, 0x180
	s_addc_u32 s43, s72, 0
	s_cmpk_eq_i32 s38, 0x700
	s_cselect_b32 s40, s30, s40
	s_cselect_b32 s41, s31, s41
	s_cselect_b32 s42, s36, s42
	s_cselect_b32 s43, s37, s43
	v_add_u32_e32 v144, s61, v220
	v_add_u32_e32 v160, s62, v220
	ds_read_b128 v[132:135], v144
	ds_read_b128 v[136:139], v144 offset:1024
	ds_read_b128 v[140:143], v144 offset:2048
	ds_read_b128 v[144:147], v144 offset:3072
	ds_read_b128 v[148:151], v160
	ds_read_b128 v[152:155], v160 offset:1024
	ds_read_b128 v[156:159], v160 offset:2048
	ds_read_b128 v[160:163], v160 offset:3072
	s_add_u32 s10, s46, 0x100
	s_addc_u32 s76, s47, 0
	s_and_b64 s[46:47], exec, s[44:45]
	s_cselect_b32 s47, s19, s76
	s_cselect_b32 s46, s69, s10
	s_add_u32 s10, s73, 0x100
	s_addc_u32 s72, s72, 0
	s_and_b64 s[44:45], exec, s[44:45]
	s_cselect_b32 s45, s17, s72
	s_cselect_b32 s44, s70, s10
	v_lshl_add_u64 v[216:217], v[128:129], 0, s[38:39]
	s_add_i32 m0, s25, 0xc000
	ds_read_b128 v[164:167], v221
	ds_read_b128 v[168:171], v221 offset:1024
	ds_read_b128 v[172:175], v221 offset:2048
	ds_read_b128 v[176:179], v221 offset:3072
	ds_read_b128 v[180:183], v221 offset:4096
	ds_read_b128 v[204:207], v221 offset:5120
	ds_read_b128 v[208:211], v221 offset:6144
	global_load_lds_dwordx4 v[216:217], off
	v_lshl_add_u64 v[216:217], v[130:131], 0, s[38:39]
	s_add_i32 m0, s25, 0xe000
	ds_read_b128 v[212:215], v221 offset:7168
	global_load_lds_dwordx4 v[216:217], off
	s_waitcnt vmcnt(8)
	s_waitcnt lgkmcnt(0)
	s_setprio 1
	s_barrier
	v_mfma_f32_16x16x32_bf16 v[124:127], v[132:135], v[164:167], 0
	v_mfma_f32_16x16x32_bf16 v[120:123], v[140:143], v[164:167], 0
	v_mfma_f32_16x16x32_bf16 v[108:111], v[132:135], v[172:175], 0
	v_mfma_f32_16x16x32_bf16 v[104:107], v[140:143], v[172:175], 0
	v_mfma_f32_16x16x32_bf16 v[92:95], v[132:135], v[180:183], 0
	v_mfma_f32_16x16x32_bf16 v[88:91], v[140:143], v[180:183], 0
	v_mfma_f32_16x16x32_bf16 v[76:79], v[132:135], v[208:211], 0
	v_mfma_f32_16x16x32_bf16 v[72:75], v[140:143], v[208:211], 0
	v_mfma_f32_16x16x32_bf16 v[124:127], v[136:139], v[168:171], v[124:127]
	v_mfma_f32_16x16x32_bf16 v[120:123], v[144:147], v[168:171], v[120:123]
	v_mfma_f32_16x16x32_bf16 v[108:111], v[136:139], v[176:179], v[108:111]
	v_mfma_f32_16x16x32_bf16 v[104:107], v[144:147], v[176:179], v[104:107]
	v_mfma_f32_16x16x32_bf16 v[92:95], v[136:139], v[204:207], v[92:95]
	v_mfma_f32_16x16x32_bf16 v[88:91], v[144:147], v[204:207], v[88:91]
	v_mfma_f32_16x16x32_bf16 v[76:79], v[136:139], v[212:215], v[76:79]
	v_mfma_f32_16x16x32_bf16 v[72:75], v[144:147], v[212:215], v[72:75]
	s_setprio 0
	s_setprio 1
	v_mfma_f32_16x16x32_bf16 v[116:119], v[148:151], v[164:167], 0
	v_mfma_f32_16x16x32_bf16 v[112:115], v[156:159], v[164:167], 0
	v_mfma_f32_16x16x32_bf16 v[100:103], v[148:151], v[172:175], 0
	v_mfma_f32_16x16x32_bf16 v[96:99], v[156:159], v[172:175], 0
	v_mfma_f32_16x16x32_bf16 v[84:87], v[148:151], v[180:183], 0
	v_mfma_f32_16x16x32_bf16 v[80:83], v[156:159], v[180:183], 0
	v_mfma_f32_16x16x32_bf16 v[68:71], v[148:151], v[208:211], 0
	v_mfma_f32_16x16x32_bf16 v[64:67], v[156:159], v[208:211], 0
	v_mfma_f32_16x16x32_bf16 v[116:119], v[152:155], v[168:171], v[116:119]
	v_mfma_f32_16x16x32_bf16 v[112:115], v[160:163], v[168:171], v[112:115]
	v_mfma_f32_16x16x32_bf16 v[100:103], v[152:155], v[176:179], v[100:103]
	v_mfma_f32_16x16x32_bf16 v[96:99], v[160:163], v[176:179], v[96:99]
	v_mfma_f32_16x16x32_bf16 v[84:87], v[152:155], v[204:207], v[84:87]
	v_mfma_f32_16x16x32_bf16 v[80:83], v[160:163], v[204:207], v[80:83]
	v_mfma_f32_16x16x32_bf16 v[68:71], v[152:155], v[212:215], v[68:71]
	v_mfma_f32_16x16x32_bf16 v[64:67], v[160:163], v[212:215], v[64:67]
	s_setprio 0
	s_barrier
	s_add_i32 s10, s61, s50
	s_mov_b32 m0, s10
	ds_read_b128 v[164:167], v221 offset:16384
	ds_read_b128 v[168:171], v221 offset:17408
	ds_read_b128 v[172:175], v221 offset:18432
	global_load_lds_dwordx4 v186, s[44:45]
	s_add_i32 m0, s10, 0x2000
	ds_read_b128 v[176:179], v221 offset:19456
	global_load_lds_dwordx4 v190, s[44:45]
	s_add_u32 s44, s44, 0x40000
	s_addc_u32 s45, s45, 0
	s_add_i32 s10, s62, s50
	s_mov_b32 m0, s10
	ds_read_b128 v[180:183], v221 offset:20480
	global_load_lds_dwordx4 v186, s[44:45]
	s_add_i32 m0, s10, 0x2000
	ds_read_b128 v[204:207], v221 offset:21504
	global_load_lds_dwordx4 v190, s[44:45]
	s_mov_b32 m0, s25
	ds_read_b128 v[208:211], v221 offset:22528
	global_load_lds_dwordx4 v184, s[46:47]
	s_mov_b32 m0, s51
	ds_read_b128 v[212:215], v221 offset:23552
	global_load_lds_dwordx4 v188, s[46:47]
	s_waitcnt vmcnt(8)
	s_waitcnt lgkmcnt(0)
	s_setprio 1
	s_barrier
	v_mfma_f32_16x16x32_bf16 v[60:63], v[132:135], v[164:167], 0
	v_mfma_f32_16x16x32_bf16 v[56:59], v[140:143], v[164:167], 0
	v_mfma_f32_16x16x32_bf16 v[44:47], v[132:135], v[172:175], 0
	v_mfma_f32_16x16x32_bf16 v[40:43], v[140:143], v[172:175], 0
	v_mfma_f32_16x16x32_bf16 v[28:31], v[132:135], v[180:183], 0
	v_mfma_f32_16x16x32_bf16 v[24:27], v[140:143], v[180:183], 0
	v_mfma_f32_16x16x32_bf16 v[12:15], v[132:135], v[208:211], 0
	v_mfma_f32_16x16x32_bf16 v[8:11], v[140:143], v[208:211], 0
	v_mfma_f32_16x16x32_bf16 v[60:63], v[136:139], v[168:171], v[60:63]
	v_mfma_f32_16x16x32_bf16 v[56:59], v[144:147], v[168:171], v[56:59]
	v_mfma_f32_16x16x32_bf16 v[44:47], v[136:139], v[176:179], v[44:47]
	v_mfma_f32_16x16x32_bf16 v[40:43], v[144:147], v[176:179], v[40:43]
	v_mfma_f32_16x16x32_bf16 v[28:31], v[136:139], v[204:207], v[28:31]
	v_mfma_f32_16x16x32_bf16 v[24:27], v[144:147], v[204:207], v[24:27]
	v_mfma_f32_16x16x32_bf16 v[12:15], v[136:139], v[212:215], v[12:15]
	v_mfma_f32_16x16x32_bf16 v[8:11], v[144:147], v[212:215], v[8:11]
	s_setprio 0
	s_setprio 1
	v_mfma_f32_16x16x32_bf16 v[52:55], v[148:151], v[164:167], 0
	v_mfma_f32_16x16x32_bf16 v[48:51], v[156:159], v[164:167], 0
	v_mfma_f32_16x16x32_bf16 v[36:39], v[148:151], v[172:175], 0
	v_mfma_f32_16x16x32_bf16 v[32:35], v[156:159], v[172:175], 0
	v_mfma_f32_16x16x32_bf16 v[20:23], v[148:151], v[180:183], 0
	v_mfma_f32_16x16x32_bf16 v[16:19], v[156:159], v[180:183], 0
	v_mfma_f32_16x16x32_bf16 v[4:7], v[148:151], v[208:211], 0
	v_mfma_f32_16x16x32_bf16 v[0:3], v[156:159], v[208:211], 0
	v_mfma_f32_16x16x32_bf16 v[52:55], v[152:155], v[168:171], v[52:55]
	v_mfma_f32_16x16x32_bf16 v[48:51], v[160:163], v[168:171], v[48:51]
	v_mfma_f32_16x16x32_bf16 v[36:39], v[152:155], v[176:179], v[36:39]
	v_mfma_f32_16x16x32_bf16 v[32:35], v[160:163], v[176:179], v[32:35]
	v_mfma_f32_16x16x32_bf16 v[20:23], v[152:155], v[204:207], v[20:23]
	v_mfma_f32_16x16x32_bf16 v[16:19], v[160:163], v[204:207], v[16:19]
	v_mfma_f32_16x16x32_bf16 v[4:7], v[152:155], v[212:215], v[4:7]
	v_mfma_f32_16x16x32_bf16 v[0:3], v[160:163], v[212:215], v[0:3]
	s_setprio 0
	s_barrier
	s_add_i32 s10, 0, 0x18000
	s_add_i32 s72, 0, 0x1c000
	v_add_u32_e32 v144, s10, v220
	v_add_u32_e32 v160, s72, v220
	ds_read_b128 v[132:135], v144
	ds_read_b128 v[136:139], v144 offset:1024
	ds_read_b128 v[140:143], v144 offset:2048
	ds_read_b128 v[144:147], v144 offset:3072
	ds_read_b128 v[148:151], v160
	ds_read_b128 v[152:155], v160 offset:1024
	ds_read_b128 v[156:159], v160 offset:2048
	ds_read_b128 v[160:163], v160 offset:3072
	s_add_u32 s44, s46, 0x40000
	s_addc_u32 s45, s47, 0
	s_mov_b32 m0, s52
	ds_read_b128 v[164:167], v221 offset:32768
	ds_read_b128 v[168:171], v221 offset:33792
	ds_read_b128 v[172:175], v221 offset:34816
	ds_read_b128 v[176:179], v221 offset:35840
	ds_read_b128 v[180:183], v221 offset:36864
	ds_read_b128 v[204:207], v221 offset:37888
	ds_read_b128 v[208:211], v221 offset:38912
	global_load_lds_dwordx4 v184, s[44:45]
	s_mov_b32 m0, s53
	ds_read_b128 v[212:215], v221 offset:39936
	global_load_lds_dwordx4 v188, s[44:45]
	s_waitcnt vmcnt(8)
	s_waitcnt lgkmcnt(0)
	s_setprio 1
	s_barrier
	v_mfma_f32_16x16x32_bf16 v[124:127], v[132:135], v[164:167], v[124:127]
	v_mfma_f32_16x16x32_bf16 v[120:123], v[140:143], v[164:167], v[120:123]
	v_mfma_f32_16x16x32_bf16 v[108:111], v[132:135], v[172:175], v[108:111]
	v_mfma_f32_16x16x32_bf16 v[104:107], v[140:143], v[172:175], v[104:107]
	v_mfma_f32_16x16x32_bf16 v[92:95], v[132:135], v[180:183], v[92:95]
	v_mfma_f32_16x16x32_bf16 v[88:91], v[140:143], v[180:183], v[88:91]
	v_mfma_f32_16x16x32_bf16 v[76:79], v[132:135], v[208:211], v[76:79]
	v_mfma_f32_16x16x32_bf16 v[72:75], v[140:143], v[208:211], v[72:75]
	v_mfma_f32_16x16x32_bf16 v[124:127], v[136:139], v[168:171], v[124:127]
	v_mfma_f32_16x16x32_bf16 v[120:123], v[144:147], v[168:171], v[120:123]
	v_mfma_f32_16x16x32_bf16 v[108:111], v[136:139], v[176:179], v[108:111]
	v_mfma_f32_16x16x32_bf16 v[104:107], v[144:147], v[176:179], v[104:107]
	v_mfma_f32_16x16x32_bf16 v[92:95], v[136:139], v[204:207], v[92:95]
	v_mfma_f32_16x16x32_bf16 v[88:91], v[144:147], v[204:207], v[88:91]
	v_mfma_f32_16x16x32_bf16 v[76:79], v[136:139], v[212:215], v[76:79]
	v_mfma_f32_16x16x32_bf16 v[72:75], v[144:147], v[212:215], v[72:75]
	s_setprio 0
	s_setprio 1
	v_mfma_f32_16x16x32_bf16 v[116:119], v[148:151], v[164:167], v[116:119]
	v_mfma_f32_16x16x32_bf16 v[112:115], v[156:159], v[164:167], v[112:115]
	v_mfma_f32_16x16x32_bf16 v[100:103], v[148:151], v[172:175], v[100:103]
	v_mfma_f32_16x16x32_bf16 v[96:99], v[156:159], v[172:175], v[96:99]
	v_mfma_f32_16x16x32_bf16 v[84:87], v[148:151], v[180:183], v[84:87]
	v_mfma_f32_16x16x32_bf16 v[80:83], v[156:159], v[180:183], v[80:83]
	v_mfma_f32_16x16x32_bf16 v[68:71], v[148:151], v[208:211], v[68:71]
	v_mfma_f32_16x16x32_bf16 v[64:67], v[156:159], v[208:211], v[64:67]
	v_mfma_f32_16x16x32_bf16 v[116:119], v[152:155], v[168:171], v[116:119]
	v_mfma_f32_16x16x32_bf16 v[112:115], v[160:163], v[168:171], v[112:115]
	v_mfma_f32_16x16x32_bf16 v[100:103], v[152:155], v[176:179], v[100:103]
	v_mfma_f32_16x16x32_bf16 v[96:99], v[160:163], v[176:179], v[96:99]
	v_mfma_f32_16x16x32_bf16 v[84:87], v[152:155], v[204:207], v[84:87]
	v_mfma_f32_16x16x32_bf16 v[80:83], v[160:163], v[204:207], v[80:83]
	v_mfma_f32_16x16x32_bf16 v[68:71], v[152:155], v[212:215], v[68:71]
	v_mfma_f32_16x16x32_bf16 v[64:67], v[160:163], v[212:215], v[64:67]
	s_setprio 0
	s_barrier
	s_add_i32 s10, s10, s50
	s_mov_b32 m0, s10
	ds_read_b128 v[164:167], v221 offset:49152
	ds_read_b128 v[168:171], v221 offset:50176
	ds_read_b128 v[172:175], v221 offset:51200
	global_load_lds_dwordx4 v186, s[42:43]
	s_add_i32 m0, s10, 0x2000
	ds_read_b128 v[176:179], v221 offset:52224
	global_load_lds_dwordx4 v190, s[42:43]
	s_add_u32 s42, s42, 0x40000
	s_addc_u32 s43, s43, 0
	s_add_i32 s10, s72, s50
	s_mov_b32 m0, s10
	ds_read_b128 v[180:183], v221 offset:53248
	global_load_lds_dwordx4 v186, s[42:43]
	s_add_i32 m0, s10, 0x2000
	ds_read_b128 v[204:207], v221 offset:54272
	global_load_lds_dwordx4 v190, s[42:43]
	s_mov_b32 m0, s58
	ds_read_b128 v[208:211], v221 offset:55296
	global_load_lds_dwordx4 v184, s[40:41]
	s_mov_b32 m0, s59
	ds_read_b128 v[212:215], v221 offset:56320
	global_load_lds_dwordx4 v188, s[40:41]
	s_waitcnt vmcnt(8)
	s_waitcnt lgkmcnt(0)
	s_setprio 1
	s_barrier
	v_mfma_f32_16x16x32_bf16 v[60:63], v[132:135], v[164:167], v[60:63]
	v_mfma_f32_16x16x32_bf16 v[56:59], v[140:143], v[164:167], v[56:59]
	v_mfma_f32_16x16x32_bf16 v[44:47], v[132:135], v[172:175], v[44:47]
	v_mfma_f32_16x16x32_bf16 v[40:43], v[140:143], v[172:175], v[40:43]
	v_mfma_f32_16x16x32_bf16 v[28:31], v[132:135], v[180:183], v[28:31]
	v_mfma_f32_16x16x32_bf16 v[24:27], v[140:143], v[180:183], v[24:27]
	v_mfma_f32_16x16x32_bf16 v[12:15], v[132:135], v[208:211], v[12:15]
	v_mfma_f32_16x16x32_bf16 v[8:11], v[140:143], v[208:211], v[8:11]
	v_mfma_f32_16x16x32_bf16 v[60:63], v[136:139], v[168:171], v[60:63]
	v_mfma_f32_16x16x32_bf16 v[56:59], v[144:147], v[168:171], v[56:59]
	v_mfma_f32_16x16x32_bf16 v[44:47], v[136:139], v[176:179], v[44:47]
	v_mfma_f32_16x16x32_bf16 v[40:43], v[144:147], v[176:179], v[40:43]
	v_mfma_f32_16x16x32_bf16 v[28:31], v[136:139], v[204:207], v[28:31]
	v_mfma_f32_16x16x32_bf16 v[24:27], v[144:147], v[204:207], v[24:27]
	v_mfma_f32_16x16x32_bf16 v[12:15], v[136:139], v[212:215], v[12:15]
	v_mfma_f32_16x16x32_bf16 v[8:11], v[144:147], v[212:215], v[8:11]
	s_setprio 0
	s_setprio 1
	v_mfma_f32_16x16x32_bf16 v[52:55], v[148:151], v[164:167], v[52:55]
	v_mfma_f32_16x16x32_bf16 v[48:51], v[156:159], v[164:167], v[48:51]
	v_mfma_f32_16x16x32_bf16 v[36:39], v[148:151], v[172:175], v[36:39]
	v_mfma_f32_16x16x32_bf16 v[32:35], v[156:159], v[172:175], v[32:35]
	v_mfma_f32_16x16x32_bf16 v[20:23], v[148:151], v[180:183], v[20:23]
	v_mfma_f32_16x16x32_bf16 v[16:19], v[156:159], v[180:183], v[16:19]
	v_mfma_f32_16x16x32_bf16 v[4:7], v[148:151], v[208:211], v[4:7]
	v_mfma_f32_16x16x32_bf16 v[0:3], v[156:159], v[208:211], v[0:3]
	v_mfma_f32_16x16x32_bf16 v[52:55], v[152:155], v[168:171], v[52:55]
	v_mfma_f32_16x16x32_bf16 v[48:51], v[160:163], v[168:171], v[48:51]
	v_mfma_f32_16x16x32_bf16 v[36:39], v[152:155], v[176:179], v[36:39]
	v_mfma_f32_16x16x32_bf16 v[32:35], v[160:163], v[176:179], v[32:35]
	v_mfma_f32_16x16x32_bf16 v[20:23], v[152:155], v[204:207], v[20:23]
	v_mfma_f32_16x16x32_bf16 v[16:19], v[160:163], v[204:207], v[16:19]
	v_mfma_f32_16x16x32_bf16 v[4:7], v[152:155], v[212:215], v[4:7]
	v_mfma_f32_16x16x32_bf16 v[0:3], v[160:163], v[212:215], v[0:3]
	s_setprio 0
	s_barrier
	s_add_i32 s10, s71, 2
	s_add_u32 s38, s38, 0x100
	s_addc_u32 s39, s39, 0
	s_cmp_gt_u32 s71, 13
	s_mov_b32 s71, s10
	s_cbranch_scc1 .LBB0_1025
	s_branch .LBB0_1019
.LBB0_1018:
	v_add_u32_e32 v144, s61, v220
	v_add_u32_e32 v160, s62, v220
	ds_read_b128 v[132:135], v144
	ds_read_b128 v[136:139], v144 offset:1024
	ds_read_b128 v[140:143], v144 offset:2048
	ds_read_b128 v[144:147], v144 offset:3072
	ds_read_b128 v[148:151], v160
	ds_read_b128 v[152:155], v160 offset:1024
	ds_read_b128 v[156:159], v160 offset:2048
	ds_read_b128 v[160:163], v160 offset:3072
	s_add_u32 s10, s46, 0x100
	s_addc_u32 s76, s47, 0
	s_and_b64 s[46:47], exec, s[44:45]
	s_cselect_b32 s47, s19, s76
	s_cselect_b32 s46, s69, s10
	s_add_u32 s10, s73, 0x100
	s_addc_u32 s72, s72, 0
	s_and_b64 s[44:45], exec, s[44:45]
	s_cselect_b32 s45, s17, s72
	s_cselect_b32 s44, s70, s10
	v_lshl_add_u64 v[216:217], v[128:129], 0, s[38:39]
	s_add_i32 m0, s25, 0xc000
	ds_read_b128 v[164:167], v221
	ds_read_b128 v[168:171], v221 offset:1024
	ds_read_b128 v[172:175], v221 offset:2048
	ds_read_b128 v[176:179], v221 offset:3072
	ds_read_b128 v[180:183], v221 offset:4096
	ds_read_b128 v[204:207], v221 offset:5120
	ds_read_b128 v[208:211], v221 offset:6144
	global_load_lds_dwordx4 v[216:217], off
	v_lshl_add_u64 v[216:217], v[130:131], 0, s[38:39]
	s_add_i32 m0, s25, 0xe000
	ds_read_b128 v[212:215], v221 offset:7168
	global_load_lds_dwordx4 v[216:217], off
	s_waitcnt vmcnt(8)
	s_waitcnt lgkmcnt(0)
	s_setprio 1
	s_barrier
	v_mfma_f32_16x16x32_bf16 v[124:127], v[132:135], v[164:167], v[124:127]
	v_mfma_f32_16x16x32_bf16 v[120:123], v[140:143], v[164:167], v[120:123]
	v_mfma_f32_16x16x32_bf16 v[108:111], v[132:135], v[172:175], v[108:111]
	v_mfma_f32_16x16x32_bf16 v[104:107], v[140:143], v[172:175], v[104:107]
	v_mfma_f32_16x16x32_bf16 v[92:95], v[132:135], v[180:183], v[92:95]
	v_mfma_f32_16x16x32_bf16 v[88:91], v[140:143], v[180:183], v[88:91]
	v_mfma_f32_16x16x32_bf16 v[76:79], v[132:135], v[208:211], v[76:79]
	v_mfma_f32_16x16x32_bf16 v[72:75], v[140:143], v[208:211], v[72:75]
	v_mfma_f32_16x16x32_bf16 v[124:127], v[136:139], v[168:171], v[124:127]
	v_mfma_f32_16x16x32_bf16 v[120:123], v[144:147], v[168:171], v[120:123]
	v_mfma_f32_16x16x32_bf16 v[108:111], v[136:139], v[176:179], v[108:111]
	v_mfma_f32_16x16x32_bf16 v[104:107], v[144:147], v[176:179], v[104:107]
	v_mfma_f32_16x16x32_bf16 v[92:95], v[136:139], v[204:207], v[92:95]
	v_mfma_f32_16x16x32_bf16 v[88:91], v[144:147], v[204:207], v[88:91]
	v_mfma_f32_16x16x32_bf16 v[76:79], v[136:139], v[212:215], v[76:79]
	v_mfma_f32_16x16x32_bf16 v[72:75], v[144:147], v[212:215], v[72:75]
	s_setprio 0
	s_setprio 1
	v_mfma_f32_16x16x32_bf16 v[116:119], v[148:151], v[164:167], v[116:119]
	v_mfma_f32_16x16x32_bf16 v[112:115], v[156:159], v[164:167], v[112:115]
	v_mfma_f32_16x16x32_bf16 v[100:103], v[148:151], v[172:175], v[100:103]
	v_mfma_f32_16x16x32_bf16 v[96:99], v[156:159], v[172:175], v[96:99]
	v_mfma_f32_16x16x32_bf16 v[84:87], v[148:151], v[180:183], v[84:87]
	v_mfma_f32_16x16x32_bf16 v[80:83], v[156:159], v[180:183], v[80:83]
	v_mfma_f32_16x16x32_bf16 v[68:71], v[148:151], v[208:211], v[68:71]
	v_mfma_f32_16x16x32_bf16 v[64:67], v[156:159], v[208:211], v[64:67]
	v_mfma_f32_16x16x32_bf16 v[116:119], v[152:155], v[168:171], v[116:119]
	v_mfma_f32_16x16x32_bf16 v[112:115], v[160:163], v[168:171], v[112:115]
	v_mfma_f32_16x16x32_bf16 v[100:103], v[152:155], v[176:179], v[100:103]
	v_mfma_f32_16x16x32_bf16 v[96:99], v[160:163], v[176:179], v[96:99]
	v_mfma_f32_16x16x32_bf16 v[84:87], v[152:155], v[204:207], v[84:87]
	v_mfma_f32_16x16x32_bf16 v[80:83], v[160:163], v[204:207], v[80:83]
	v_mfma_f32_16x16x32_bf16 v[68:71], v[152:155], v[212:215], v[68:71]
	v_mfma_f32_16x16x32_bf16 v[64:67], v[160:163], v[212:215], v[64:67]
	s_setprio 0
	s_barrier
	s_add_i32 s10, s61, s50
	s_mov_b32 m0, s10
	ds_read_b128 v[164:167], v221 offset:16384
	ds_read_b128 v[168:171], v221 offset:17408
	ds_read_b128 v[172:175], v221 offset:18432
	global_load_lds_dwordx4 v186, s[44:45]
	s_add_i32 m0, s10, 0x2000
	ds_read_b128 v[176:179], v221 offset:19456
	global_load_lds_dwordx4 v190, s[44:45]
	s_add_u32 s44, s44, 0x40000
	s_addc_u32 s45, s45, 0
	s_add_i32 s10, s62, s50
	s_mov_b32 m0, s10
	ds_read_b128 v[180:183], v221 offset:20480
	global_load_lds_dwordx4 v186, s[44:45]
	s_add_i32 m0, s10, 0x2000
	ds_read_b128 v[204:207], v221 offset:21504
	global_load_lds_dwordx4 v190, s[44:45]
	s_mov_b32 m0, s25
	ds_read_b128 v[208:211], v221 offset:22528
	global_load_lds_dwordx4 v184, s[46:47]
	s_mov_b32 m0, s51
	ds_read_b128 v[212:215], v221 offset:23552
	global_load_lds_dwordx4 v188, s[46:47]
	s_waitcnt vmcnt(8)
	s_waitcnt lgkmcnt(0)
	s_setprio 1
	s_barrier
	v_mfma_f32_16x16x32_bf16 v[60:63], v[132:135], v[164:167], v[60:63]
	v_mfma_f32_16x16x32_bf16 v[56:59], v[140:143], v[164:167], v[56:59]
	v_mfma_f32_16x16x32_bf16 v[44:47], v[132:135], v[172:175], v[44:47]
	v_mfma_f32_16x16x32_bf16 v[40:43], v[140:143], v[172:175], v[40:43]
	v_mfma_f32_16x16x32_bf16 v[28:31], v[132:135], v[180:183], v[28:31]
	v_mfma_f32_16x16x32_bf16 v[24:27], v[140:143], v[180:183], v[24:27]
	v_mfma_f32_16x16x32_bf16 v[12:15], v[132:135], v[208:211], v[12:15]
	v_mfma_f32_16x16x32_bf16 v[8:11], v[140:143], v[208:211], v[8:11]
	v_mfma_f32_16x16x32_bf16 v[60:63], v[136:139], v[168:171], v[60:63]
	v_mfma_f32_16x16x32_bf16 v[56:59], v[144:147], v[168:171], v[56:59]
	v_mfma_f32_16x16x32_bf16 v[44:47], v[136:139], v[176:179], v[44:47]
	v_mfma_f32_16x16x32_bf16 v[40:43], v[144:147], v[176:179], v[40:43]
	v_mfma_f32_16x16x32_bf16 v[28:31], v[136:139], v[204:207], v[28:31]
	v_mfma_f32_16x16x32_bf16 v[24:27], v[144:147], v[204:207], v[24:27]
	v_mfma_f32_16x16x32_bf16 v[12:15], v[136:139], v[212:215], v[12:15]
	v_mfma_f32_16x16x32_bf16 v[8:11], v[144:147], v[212:215], v[8:11]
	s_setprio 0
	s_setprio 1
	v_mfma_f32_16x16x32_bf16 v[52:55], v[148:151], v[164:167], v[52:55]
	v_mfma_f32_16x16x32_bf16 v[48:51], v[156:159], v[164:167], v[48:51]
	v_mfma_f32_16x16x32_bf16 v[36:39], v[148:151], v[172:175], v[36:39]
	v_mfma_f32_16x16x32_bf16 v[32:35], v[156:159], v[172:175], v[32:35]
	v_mfma_f32_16x16x32_bf16 v[20:23], v[148:151], v[180:183], v[20:23]
	v_mfma_f32_16x16x32_bf16 v[16:19], v[156:159], v[180:183], v[16:19]
	v_mfma_f32_16x16x32_bf16 v[4:7], v[148:151], v[208:211], v[4:7]
	v_mfma_f32_16x16x32_bf16 v[0:3], v[156:159], v[208:211], v[0:3]
	v_mfma_f32_16x16x32_bf16 v[52:55], v[152:155], v[168:171], v[52:55]
	v_mfma_f32_16x16x32_bf16 v[48:51], v[160:163], v[168:171], v[48:51]
	v_mfma_f32_16x16x32_bf16 v[36:39], v[152:155], v[176:179], v[36:39]
	v_mfma_f32_16x16x32_bf16 v[32:35], v[160:163], v[176:179], v[32:35]
	v_mfma_f32_16x16x32_bf16 v[20:23], v[152:155], v[204:207], v[20:23]
	v_mfma_f32_16x16x32_bf16 v[16:19], v[160:163], v[204:207], v[16:19]
	v_mfma_f32_16x16x32_bf16 v[4:7], v[152:155], v[212:215], v[4:7]
	v_mfma_f32_16x16x32_bf16 v[0:3], v[160:163], v[212:215], v[0:3]
	s_setprio 0
	s_barrier
	s_add_i32 s10, 0, 0x18000
	s_add_i32 s72, 0, 0x1c000
	v_add_u32_e32 v144, s10, v220
	v_add_u32_e32 v160, s72, v220
	ds_read_b128 v[132:135], v144
	ds_read_b128 v[136:139], v144 offset:1024
	ds_read_b128 v[140:143], v144 offset:2048
	ds_read_b128 v[144:147], v144 offset:3072
	ds_read_b128 v[148:151], v160
	ds_read_b128 v[152:155], v160 offset:1024
	ds_read_b128 v[156:159], v160 offset:2048
	ds_read_b128 v[160:163], v160 offset:3072
	s_add_u32 s44, s46, 0x40000
	s_addc_u32 s45, s47, 0
	s_mov_b32 m0, s52
	ds_read_b128 v[164:167], v221 offset:32768
	ds_read_b128 v[168:171], v221 offset:33792
	ds_read_b128 v[172:175], v221 offset:34816
	ds_read_b128 v[176:179], v221 offset:35840
	ds_read_b128 v[180:183], v221 offset:36864
	ds_read_b128 v[204:207], v221 offset:37888
	ds_read_b128 v[208:211], v221 offset:38912
	global_load_lds_dwordx4 v184, s[44:45]
	s_mov_b32 m0, s53
	ds_read_b128 v[212:215], v221 offset:39936
	global_load_lds_dwordx4 v188, s[44:45]
	s_waitcnt vmcnt(8)
	s_waitcnt lgkmcnt(0)
	s_setprio 1
	s_barrier
	v_mfma_f32_16x16x32_bf16 v[124:127], v[132:135], v[164:167], v[124:127]
	v_mfma_f32_16x16x32_bf16 v[120:123], v[140:143], v[164:167], v[120:123]
	v_mfma_f32_16x16x32_bf16 v[108:111], v[132:135], v[172:175], v[108:111]
	v_mfma_f32_16x16x32_bf16 v[104:107], v[140:143], v[172:175], v[104:107]
	v_mfma_f32_16x16x32_bf16 v[92:95], v[132:135], v[180:183], v[92:95]
	v_mfma_f32_16x16x32_bf16 v[88:91], v[140:143], v[180:183], v[88:91]
	v_mfma_f32_16x16x32_bf16 v[76:79], v[132:135], v[208:211], v[76:79]
	v_mfma_f32_16x16x32_bf16 v[72:75], v[140:143], v[208:211], v[72:75]
	v_mfma_f32_16x16x32_bf16 v[124:127], v[136:139], v[168:171], v[124:127]
	v_mfma_f32_16x16x32_bf16 v[120:123], v[144:147], v[168:171], v[120:123]
	v_mfma_f32_16x16x32_bf16 v[108:111], v[136:139], v[176:179], v[108:111]
	v_mfma_f32_16x16x32_bf16 v[104:107], v[144:147], v[176:179], v[104:107]
	v_mfma_f32_16x16x32_bf16 v[92:95], v[136:139], v[204:207], v[92:95]
	v_mfma_f32_16x16x32_bf16 v[88:91], v[144:147], v[204:207], v[88:91]
	v_mfma_f32_16x16x32_bf16 v[76:79], v[136:139], v[212:215], v[76:79]
	v_mfma_f32_16x16x32_bf16 v[72:75], v[144:147], v[212:215], v[72:75]
	s_setprio 0
	s_setprio 1
	v_mfma_f32_16x16x32_bf16 v[116:119], v[148:151], v[164:167], v[116:119]
	v_mfma_f32_16x16x32_bf16 v[112:115], v[156:159], v[164:167], v[112:115]
	v_mfma_f32_16x16x32_bf16 v[100:103], v[148:151], v[172:175], v[100:103]
	v_mfma_f32_16x16x32_bf16 v[96:99], v[156:159], v[172:175], v[96:99]
	v_mfma_f32_16x16x32_bf16 v[84:87], v[148:151], v[180:183], v[84:87]
	v_mfma_f32_16x16x32_bf16 v[80:83], v[156:159], v[180:183], v[80:83]
	v_mfma_f32_16x16x32_bf16 v[68:71], v[148:151], v[208:211], v[68:71]
	v_mfma_f32_16x16x32_bf16 v[64:67], v[156:159], v[208:211], v[64:67]
	v_mfma_f32_16x16x32_bf16 v[116:119], v[152:155], v[168:171], v[116:119]
	v_mfma_f32_16x16x32_bf16 v[112:115], v[160:163], v[168:171], v[112:115]
	v_mfma_f32_16x16x32_bf16 v[100:103], v[152:155], v[176:179], v[100:103]
	v_mfma_f32_16x16x32_bf16 v[96:99], v[160:163], v[176:179], v[96:99]
	v_mfma_f32_16x16x32_bf16 v[84:87], v[152:155], v[204:207], v[84:87]
	v_mfma_f32_16x16x32_bf16 v[80:83], v[160:163], v[204:207], v[80:83]
	v_mfma_f32_16x16x32_bf16 v[68:71], v[152:155], v[212:215], v[68:71]
	v_mfma_f32_16x16x32_bf16 v[64:67], v[160:163], v[212:215], v[64:67]
	s_setprio 0
	s_barrier
	s_add_i32 s10, s10, s50
	s_mov_b32 m0, s10
	ds_read_b128 v[164:167], v221 offset:49152
	ds_read_b128 v[168:171], v221 offset:50176
	ds_read_b128 v[172:175], v221 offset:51200
	global_load_lds_dwordx4 v186, s[42:43]
	s_add_i32 m0, s10, 0x2000
	ds_read_b128 v[176:179], v221 offset:52224
	global_load_lds_dwordx4 v190, s[42:43]
	s_add_u32 s42, s42, 0x40000
	s_addc_u32 s43, s43, 0
	s_add_i32 s10, s72, s50
	s_mov_b32 m0, s10
	ds_read_b128 v[180:183], v221 offset:53248
	global_load_lds_dwordx4 v186, s[42:43]
	s_add_i32 m0, s10, 0x2000
	ds_read_b128 v[204:207], v221 offset:54272
	global_load_lds_dwordx4 v190, s[42:43]
	s_mov_b32 m0, s58
	ds_read_b128 v[208:211], v221 offset:55296
	global_load_lds_dwordx4 v184, s[40:41]
	s_mov_b32 m0, s59
	ds_read_b128 v[212:215], v221 offset:56320
	global_load_lds_dwordx4 v188, s[40:41]
	s_waitcnt vmcnt(8)
	s_waitcnt lgkmcnt(0)
	s_setprio 1
	s_barrier
	v_mfma_f32_16x16x32_bf16 v[60:63], v[132:135], v[164:167], v[60:63]
	v_mfma_f32_16x16x32_bf16 v[56:59], v[140:143], v[164:167], v[56:59]
	v_mfma_f32_16x16x32_bf16 v[44:47], v[132:135], v[172:175], v[44:47]
	v_mfma_f32_16x16x32_bf16 v[40:43], v[140:143], v[172:175], v[40:43]
	v_mfma_f32_16x16x32_bf16 v[28:31], v[132:135], v[180:183], v[28:31]
	v_mfma_f32_16x16x32_bf16 v[24:27], v[140:143], v[180:183], v[24:27]
	v_mfma_f32_16x16x32_bf16 v[12:15], v[132:135], v[208:211], v[12:15]
	v_mfma_f32_16x16x32_bf16 v[8:11], v[140:143], v[208:211], v[8:11]
	v_mfma_f32_16x16x32_bf16 v[60:63], v[136:139], v[168:171], v[60:63]
	v_mfma_f32_16x16x32_bf16 v[56:59], v[144:147], v[168:171], v[56:59]
	v_mfma_f32_16x16x32_bf16 v[44:47], v[136:139], v[176:179], v[44:47]
	v_mfma_f32_16x16x32_bf16 v[40:43], v[144:147], v[176:179], v[40:43]
	v_mfma_f32_16x16x32_bf16 v[28:31], v[136:139], v[204:207], v[28:31]
	v_mfma_f32_16x16x32_bf16 v[24:27], v[144:147], v[204:207], v[24:27]
	v_mfma_f32_16x16x32_bf16 v[12:15], v[136:139], v[212:215], v[12:15]
	v_mfma_f32_16x16x32_bf16 v[8:11], v[144:147], v[212:215], v[8:11]
	s_setprio 0
	s_setprio 1
	v_mfma_f32_16x16x32_bf16 v[52:55], v[148:151], v[164:167], v[52:55]
	v_mfma_f32_16x16x32_bf16 v[48:51], v[156:159], v[164:167], v[48:51]
	v_mfma_f32_16x16x32_bf16 v[36:39], v[148:151], v[172:175], v[36:39]
	v_mfma_f32_16x16x32_bf16 v[32:35], v[156:159], v[172:175], v[32:35]
	v_mfma_f32_16x16x32_bf16 v[20:23], v[148:151], v[180:183], v[20:23]
	v_mfma_f32_16x16x32_bf16 v[16:19], v[156:159], v[180:183], v[16:19]
	v_mfma_f32_16x16x32_bf16 v[4:7], v[148:151], v[208:211], v[4:7]
	v_mfma_f32_16x16x32_bf16 v[0:3], v[156:159], v[208:211], v[0:3]
	v_mfma_f32_16x16x32_bf16 v[52:55], v[152:155], v[168:171], v[52:55]
	v_mfma_f32_16x16x32_bf16 v[48:51], v[160:163], v[168:171], v[48:51]
	v_mfma_f32_16x16x32_bf16 v[36:39], v[152:155], v[176:179], v[36:39]
	v_mfma_f32_16x16x32_bf16 v[32:35], v[160:163], v[176:179], v[32:35]
	v_mfma_f32_16x16x32_bf16 v[20:23], v[152:155], v[204:207], v[20:23]
	v_mfma_f32_16x16x32_bf16 v[16:19], v[160:163], v[204:207], v[16:19]
	v_mfma_f32_16x16x32_bf16 v[4:7], v[152:155], v[212:215], v[4:7]
	v_mfma_f32_16x16x32_bf16 v[0:3], v[160:163], v[212:215], v[0:3]
	s_setprio 0
	s_barrier
	s_add_i32 s10, s71, 2
	s_add_u32 s38, s38, 0x100
	s_addc_u32 s39, s39, 0
	s_cmp_gt_u32 s71, 13
	s_mov_b32 s71, s10
	s_cbranch_scc1 .LBB0_1025
